# attention: one static s_setprio 1 for waves 4-7 before each tile loop (on the half-split softmax schedule)
# baseline (speedup 1.0000x reference)
.LBB0_843:
	s_lshl_b32 s4, s63, 1
	s_and_b32 s14, s4, 0xe00
	s_and_b32 s78, s57, 7
	v_readfirstlane_b32 s4, v176
	s_xor_b32 s9, s78, 15
	s_ashr_i32 s4, s4, 6
	s_ashr_i32 s8, s57, 6
	s_lshl_b32 s87, s9, 8
	s_lshl_b32 s15, s4, 5
	s_lshl_b32 s82, s9, 2
	s_add_i32 s83, s15, s87
	s_ashr_i32 s9, s8, 31
	s_add_i32 s82, s82, 4
	s_or_b32 s84, s83, 31
	s_lshl_b64 s[40:41], s[8:9], 12
	s_lshl_b64 s[12:13], s[8:9], 26
	s_add_u32 s8, s2, s12
	s_addc_u32 s9, s3, s13
	s_lshl_b32 s10, s57, 5
	s_and_b32 s79, s10, 0x700
	s_lshl_b32 s10, s79, 1
	s_add_u32 s18, s8, s10
	s_addc_u32 s19, s9, 0
	s_add_u32 s38, s18, 0x1000
	s_addc_u32 s39, s19, 0
	s_add_u32 s16, s18, 0x2000
	s_addc_u32 s17, s19, 0
	s_add_u32 s8, s2, s10
	s_addc_u32 s9, s3, 0
	s_lshl_b32 s55, s4, 3
	s_lshl_b32 s54, s4, 11
	s_lshl_b32 s33, s4, 12
	s_add_u32 s10, s18, 0x102000
	s_addc_u32 s11, s19, 0
	s_or_b32 s22, s40, s87
	s_ashr_i32 s23, s15, 31
	s_add_u32 s80, s22, s15
	s_addc_u32 s81, s41, s23
	s_cmp_lg_u32 0, -1
	s_cselect_b32 s15, 0, 0
	s_add_i32 s22, s15, 0xc000
	s_add_i32 s85, s54, s15
	s_add_i32 s86, s33, s22
	v_mov_b32_e32 v4, v176
	v_mov_b32_e32 v181, v179
	v_bfe_u32 v0, v4, 4, 2
	v_or_b32_e32 v1, s55, v0
	v_bitop3_b32 v0, v0, v4, s55 bitop3:0x36
	v_lshlrev_b32_e32 v2, 14, v1
	v_lshlrev_b32_e32 v0, 4, v0
	v_and_or_b32 v178, v0, s67, v2
	v_or_b32_e32 v0, 4, v1
	v_bitop3_b32 v1, v1, v4, 4 bitop3:0x36
	v_lshlrev_b32_e32 v0, 14, v0
	v_lshlrev_b32_e32 v1, 4, v1
	v_and_or_b32 v180, v1, s67, v0
	v_bfe_u32 v0, v4, 5, 1
	v_or_b32_e32 v1, s55, v0
	v_and_b32_e32 v2, 31, v4
	v_lshlrev_b32_e32 v3, 14, v1
	v_lshlrev_b32_e32 v0, 6, v0
	v_lshlrev_b32_e32 v5, 4, v2
	v_bitop3_b32 v182, v0, v3, v5 bitop3:0xde
	v_or_b32_e32 v0, 2, v1
	v_lshlrev_b32_e32 v3, 2, v0
	v_bitop3_b32 v3, v3, v2, 12 bitop3:0x6c
	v_lshlrev_b32_e32 v0, 14, v0
	v_lshl_or_b32 v184, v3, 4, v0
	v_or_b32_e32 v0, 6, v1
	v_lshlrev_b32_e32 v1, 2, v0
	v_bitop3_b32 v1, v1, v2, 12 bitop3:0x6c
	v_lshlrev_b32_e32 v0, 14, v0
	v_lshl_or_b32 v188, v1, 4, v0
	v_lshl_add_u64 v[0:1], s[38:39], 0, v[178:179]
	s_mov_b32 s22, m0
	s_mov_b32 m0, s85
	s_nop 0
	global_load_lds_dwordx4 v[0:1], off
	s_mov_b32 m0, s22
	v_lshl_add_u64 v[0:1], s[38:39], 0, v[180:181]
	s_add_i32 s22, s85, 0x400
	s_mov_b32 s23, m0
	s_mov_b32 m0, s22
	s_nop 0
	global_load_lds_dwordx4 v[0:1], off
	s_mov_b32 m0, s23
	v_mov_b32_e32 v183, v179
	v_lshl_add_u64 v[0:1], s[16:17], 0, v[182:183]
	s_mov_b32 s22, m0
	s_mov_b32 m0, s86
	s_nop 0
	global_load_lds_dwordx4 v[0:1], off
	s_mov_b32 m0, s22
	s_add_i32 s15, s15, s33
	v_mov_b32_e32 v185, v179
	s_add_i32 s22, s15, 0xc400
	v_or_b32_e32 v186, 0x10000, v182
	v_lshl_add_u64 v[0:1], s[16:17], 0, v[184:185]
	s_mov_b32 s23, m0
	s_mov_b32 m0, s22
	s_nop 0
	global_load_lds_dwordx4 v[0:1], off
	s_mov_b32 m0, s23
	v_mov_b32_e32 v187, v179
	s_add_i32 s22, s15, 0xc800
	v_lshl_add_u64 v[0:1], s[16:17], 0, v[186:187]
	s_mov_b32 s23, m0
	s_mov_b32 m0, s22
	s_nop 0
	global_load_lds_dwordx4 v[0:1], off
	s_mov_b32 m0, s23
	s_add_i32 s22, s15, 0xcc00
	v_mov_b32_e32 v189, v179
	s_add_u32 s52, s18, 0x101000
	v_lshl_add_u64 v[0:1], s[16:17], 0, v[188:189]
	s_addc_u32 s53, s19, 0
	s_mov_b32 s23, m0
	s_mov_b32 m0, s22
	s_nop 0
	global_load_lds_dwordx4 v[0:1], off
	s_mov_b32 m0, s23
	v_lshl_add_u64 v[0:1], s[52:53], 0, v[178:179]
	s_add_i32 s18, s85, 0x4000
	s_mov_b32 s19, m0
	s_mov_b32 m0, s18
	s_nop 0
	global_load_lds_dwordx4 v[0:1], off
	s_mov_b32 m0, s19
	v_lshl_add_u64 v[0:1], s[52:53], 0, v[180:181]
	s_add_i32 s18, s85, 0x4400
	s_mov_b32 s19, m0
	s_mov_b32 m0, s18
	s_nop 0
	global_load_lds_dwordx4 v[0:1], off
	s_mov_b32 m0, s19
	v_lshl_add_u64 v[0:1], s[10:11], 0, v[182:183]
	s_add_i32 s18, s15, 0x14000
	s_mov_b32 s19, m0
	s_mov_b32 m0, s18
	s_nop 0
	global_load_lds_dwordx4 v[0:1], off
	s_mov_b32 m0, s19
	v_lshl_add_u64 v[0:1], s[10:11], 0, v[184:185]
	s_add_i32 s18, s15, 0x14400
	s_mov_b32 s19, m0
	s_mov_b32 m0, s18
	s_nop 0
	global_load_lds_dwordx4 v[0:1], off
	s_mov_b32 m0, s19
	v_lshl_add_u64 v[0:1], s[10:11], 0, v[186:187]
	s_add_i32 s18, s15, 0x14800
	s_mov_b32 s19, m0
	s_mov_b32 m0, s18
	s_nop 0
	global_load_lds_dwordx4 v[0:1], off
	s_mov_b32 m0, s19
	v_lshl_add_u64 v[0:1], s[10:11], 0, v[188:189]
	s_add_i32 s15, s15, 0x14c00
	s_mov_b32 s18, m0
	s_mov_b32 m0, s15
	s_nop 0
	global_load_lds_dwordx4 v[0:1], off
	s_mov_b32 m0, s18
	v_or_b32_e32 v0, s80, v2
	v_mov_b32_e32 v1, s81
	v_lshlrev_b64 v[0:1], 14, v[0:1]
	v_lshrrev_b32_e32 v2, 1, v4
	v_lshl_add_u64 v[0:1], s[8:9], 0, v[0:1]
	v_and_b32_e32 v2, 16, v2
	v_mov_b32_e32 v3, v179
	v_lshl_add_u64 v[0:1], v[0:1], 0, v[2:3]
	global_load_dwordx4 v[144:147], v[0:1], off
	global_load_dwordx4 v[148:151], v[0:1], off offset:32
	global_load_dwordx4 v[152:155], v[0:1], off offset:64
	global_load_dwordx4 v[156:159], v[0:1], off offset:96
	global_load_dwordx4 v[160:163], v[0:1], off offset:128
	global_load_dwordx4 v[164:167], v[0:1], off offset:160
	global_load_dwordx4 v[168:171], v[0:1], off offset:192
	global_load_dwordx4 v[172:175], v[0:1], off offset:224
	v_lshrrev_b32_e32 v0, 5, v4
	v_and_b32_e32 v1, 15, v4
	v_bitop3_b32 v0, v0, v1, 1 bitop3:0x6c
	v_lshlrev_b32_e32 v1, 8, v4
	s_addk_i32 s87, 0x100
	s_or_b32 s12, s12, s14
	v_lshlrev_b32_e32 v0, 4, v0
	v_and_b32_e32 v1, 0x1f00, v1
	s_add_u32 s22, s61, s12
	v_mov_b32_e32 v14, v179
	v_mov_b32_e32 v15, v179
	v_or_b32_e32 v194, v0, v1
	v_bitop3_b32 v195, v0, 32, v1 bitop3:0x36
	v_bitop3_b32 v196, v0, 64, v1 bitop3:0x36
	v_bitop3_b32 v197, v0, s68, v1 bitop3:0x36
	v_bitop3_b32 v198, v0, s69, v1 bitop3:0x36
	v_bitop3_b32 v199, v0, s70, v1 bitop3:0x36
	v_bitop3_b32 v200, v0, s71, v1 bitop3:0x36
	v_bitop3_b32 v201, v0, s72, v1 bitop3:0x36
	s_addc_u32 s23, s62, s13
	v_mov_b32_e32 v0, v179
	v_mov_b32_e32 v1, v179
	v_mov_b32_e32 v2, v179
	v_mov_b32_e32 v4, v179
	s_waitcnt vmcnt(7)
	s_waitcnt vmcnt(6)
	s_waitcnt vmcnt(5)
	s_waitcnt vmcnt(4)
	s_waitcnt vmcnt(3)
	s_waitcnt vmcnt(2)
	s_waitcnt vmcnt(1)
	s_waitcnt vmcnt(0)
	s_waitcnt vmcnt(0)
	v_mov_b32_e32 v5, v179
	v_mov_b32_e32 v6, v179
	v_mov_b32_e32 v7, v179
	v_mov_b32_e32 v8, v179
	v_mov_b32_e32 v9, v179
	v_mov_b32_e32 v10, v179
	v_mov_b32_e32 v11, v179
	v_mov_b32_e32 v12, v179
	v_mov_b32_e32 v13, v179
	v_mov_b64_e32 v[30:31], v[14:15]
	v_mov_b64_e32 v[46:47], v[14:15]
	v_mov_b64_e32 v[62:63], v[14:15]
	v_mov_b64_e32 v[78:79], v[14:15]
	v_mov_b64_e32 v[94:95], v[14:15]
	v_mov_b64_e32 v[110:111], v[14:15]
	v_mov_b64_e32 v[126:127], v[14:15]
	v_mov_b32_e32 v190, 0xf149f2ca
	s_mov_b32 s42, 2
	s_mov_b64 s[14:15], s[22:23]
	s_mov_b32 s43, 0
	v_mov_b64_e32 v[28:29], v[12:13]
	v_mov_b64_e32 v[26:27], v[10:11]
	v_mov_b64_e32 v[24:25], v[8:9]
	v_mov_b64_e32 v[22:23], v[6:7]
	v_mov_b64_e32 v[20:21], v[4:5]
	v_mov_b64_e32 v[18:19], v[2:3]
	v_mov_b64_e32 v[16:17], v[0:1]
	v_mov_b64_e32 v[44:45], v[12:13]
	v_mov_b64_e32 v[42:43], v[10:11]
	v_mov_b64_e32 v[40:41], v[8:9]
	v_mov_b64_e32 v[38:39], v[6:7]
	v_mov_b64_e32 v[36:37], v[4:5]
	v_mov_b64_e32 v[34:35], v[2:3]
	v_mov_b64_e32 v[32:33], v[0:1]
	v_mov_b64_e32 v[60:61], v[12:13]
	v_mov_b64_e32 v[58:59], v[10:11]
	v_mov_b64_e32 v[56:57], v[8:9]
	v_mov_b64_e32 v[54:55], v[6:7]
	v_mov_b64_e32 v[52:53], v[4:5]
	v_mov_b64_e32 v[50:51], v[2:3]
	v_mov_b64_e32 v[48:49], v[0:1]
	v_mov_b64_e32 v[76:77], v[12:13]
	v_mov_b64_e32 v[74:75], v[10:11]
	v_mov_b64_e32 v[72:73], v[8:9]
	v_mov_b64_e32 v[70:71], v[6:7]
	v_mov_b64_e32 v[68:69], v[4:5]
	v_mov_b64_e32 v[66:67], v[2:3]
	v_mov_b64_e32 v[64:65], v[0:1]
	v_mov_b64_e32 v[92:93], v[12:13]
	v_mov_b64_e32 v[90:91], v[10:11]
	v_mov_b64_e32 v[88:89], v[8:9]
	v_mov_b64_e32 v[86:87], v[6:7]
	v_mov_b64_e32 v[84:85], v[4:5]
	v_mov_b64_e32 v[82:83], v[2:3]
	v_mov_b64_e32 v[80:81], v[0:1]
	v_mov_b64_e32 v[108:109], v[12:13]
	v_mov_b64_e32 v[106:107], v[10:11]
	v_mov_b64_e32 v[104:105], v[8:9]
	v_mov_b64_e32 v[102:103], v[6:7]
	v_mov_b64_e32 v[100:101], v[4:5]
	v_mov_b64_e32 v[98:99], v[2:3]
	v_mov_b64_e32 v[96:97], v[0:1]
	v_mov_b64_e32 v[124:125], v[12:13]
	v_mov_b64_e32 v[122:123], v[10:11]
	v_mov_b64_e32 v[120:121], v[8:9]
	v_mov_b64_e32 v[118:119], v[6:7]
	v_mov_b64_e32 v[116:117], v[4:5]
	v_mov_b64_e32 v[114:115], v[2:3]
	v_mov_b64_e32 v[112:113], v[0:1]
	v_mov_b32_e32 v202, v179
	s_mov_b32 s88, 0
	v_lshrrev_b32_e32 v246, 8, v220
	s_nop 0
	v_readfirstlane_b32 s100, v246
	s_nop 3
	s_cmp_lg_u32 s100, 0
	s_cbranch_scc0 .Latt_prio_0
	s_setprio 1
.Latt_prio_0:
	s_barrier
	s_branch .LBB0_845

.LBB0_862:
	v_and_b32_e32 v129, 64, v193
	v_xor_b32_e32 v128, 32, v193
	v_add_u32_e32 v129, 64, v129
	v_cmp_lt_i32_e32 vcc, v128, v129
	s_add_i32 s4, s4, s60
	s_lshl_b64 s[14:15], s[4:5], 14
	v_cndmask_b32_e32 v128, v193, v128, vcc
	v_lshlrev_b32_e32 v194, 2, v128
	ds_bpermute_b32 v128, v194, v202
	s_add_u32 s14, s58, s14
	s_addc_u32 s15, s59, s15
	s_mov_b32 s4, 0
	s_mov_b32 s88, 2
	s_waitcnt lgkmcnt(0)
	v_add_f32_e32 v128, v202, v128
	v_rcp_f32_e32 v130, v128
	v_mov_b32_e32 v128, v176
	v_mul_f32_e32 v112, v112, v130
	v_lshlrev_b32_e32 v128, 4, v128
	v_mul_f32_e32 v113, v113, v130
	v_mul_f32_e32 v114, v114, v130
	v_mul_f32_e32 v115, v115, v130
	v_and_b32_e32 v178, 0x3f0, v128
	v_mul_f32_e32 v116, v116, v130
	v_mul_f32_e32 v117, v117, v130
	v_mul_f32_e32 v118, v118, v130
	v_mul_f32_e32 v119, v119, v130
	v_cvt_pk_bf16_f32 v112, v112, v113
	v_cvt_pk_bf16_f32 v113, v114, v115
	v_cvt_pk_bf16_f32 v114, v116, v117
	v_cvt_pk_bf16_f32 v115, v118, v119
	v_mul_f32_e32 v96, v96, v130
	v_mul_f32_e32 v97, v97, v130
	v_mul_f32_e32 v98, v98, v130
	v_mul_f32_e32 v99, v99, v130
	v_lshl_add_u64 v[128:129], s[14:15], 0, v[178:179]
	v_mul_f32_e32 v120, v120, v130
	v_mul_f32_e32 v121, v121, v130
	v_mul_f32_e32 v122, v122, v130
	v_mul_f32_e32 v123, v123, v130
	v_mul_f32_e32 v124, v124, v130
	v_mul_f32_e32 v125, v125, v130
	v_mul_f32_e32 v126, v126, v130
	v_mul_f32_e32 v127, v127, v130
	v_cvt_pk_bf16_f32 v116, v120, v121
	v_cvt_pk_bf16_f32 v117, v122, v123
	v_cvt_pk_bf16_f32 v118, v124, v125
	v_cvt_pk_bf16_f32 v119, v126, v127
	global_store_dwordx4 v178, v[112:115], s[14:15]
	global_store_dwordx4 v178, v[116:119], s[14:15] offset:1024
	v_mul_f32_e32 v100, v100, v130
	v_mul_f32_e32 v101, v101, v130
	v_mul_f32_e32 v102, v102, v130
	v_mul_f32_e32 v103, v103, v130
	v_cvt_pk_bf16_f32 v96, v96, v97
	v_cvt_pk_bf16_f32 v97, v98, v99
	v_cvt_pk_bf16_f32 v98, v100, v101
	v_cvt_pk_bf16_f32 v99, v102, v103
	v_mul_f32_e32 v80, v80, v130
	v_mul_f32_e32 v81, v81, v130
	v_mul_f32_e32 v82, v82, v130
	v_mul_f32_e32 v83, v83, v130
	v_mul_f32_e32 v84, v84, v130
	v_mul_f32_e32 v88, v88, v130
	v_mul_f32_e32 v104, v104, v130
	v_mul_f32_e32 v105, v105, v130
	v_mul_f32_e32 v106, v106, v130
	v_mul_f32_e32 v107, v107, v130
	v_mul_f32_e32 v108, v108, v130
	v_mul_f32_e32 v109, v109, v130
	v_mul_f32_e32 v110, v110, v130
	v_mul_f32_e32 v111, v111, v130
	v_cvt_pk_bf16_f32 v100, v104, v105
	v_cvt_pk_bf16_f32 v101, v106, v107
	v_cvt_pk_bf16_f32 v102, v108, v109
	v_cvt_pk_bf16_f32 v103, v110, v111
	global_store_dwordx4 v178, v[96:99], s[14:15] offset:2048
	global_store_dwordx4 v178, v[100:103], s[14:15] offset:3072
	v_mul_f32_e32 v85, v85, v130
	v_mul_f32_e32 v86, v86, v130
	v_mul_f32_e32 v87, v87, v130
	v_mul_f32_e32 v89, v89, v130
	v_cvt_pk_bf16_f32 v80, v80, v81
	v_cvt_pk_bf16_f32 v81, v82, v83
	v_cvt_pk_bf16_f32 v82, v84, v85
	v_cvt_pk_bf16_f32 v83, v86, v87
	v_cvt_pk_bf16_f32 v84, v88, v89
	v_add_co_u32_e32 v88, vcc, s73, v128
	v_mul_f32_e32 v90, v90, v130
	s_nop 0
	v_addc_co_u32_e32 v89, vcc, 0, v129, vcc
	v_mul_f32_e32 v91, v91, v130
	v_cvt_pk_bf16_f32 v85, v90, v91
	v_add_co_u32_e32 v90, vcc, s74, v128
	v_mul_f32_e32 v64, v64, v130
	s_nop 0
	v_addc_co_u32_e32 v91, vcc, 0, v129, vcc
	v_mul_f32_e32 v65, v65, v130
	v_mul_f32_e32 v66, v66, v130
	v_mul_f32_e32 v67, v67, v130
	v_mul_f32_e32 v92, v92, v130
	v_mul_f32_e32 v93, v93, v130
	v_mul_f32_e32 v94, v94, v130
	v_mul_f32_e32 v95, v95, v130
	v_cvt_pk_bf16_f32 v86, v92, v93
	v_cvt_pk_bf16_f32 v87, v94, v95
	global_store_dwordx4 v[90:91], v[80:83], off offset:-4096
	global_store_dwordx4 v[88:89], v[84:87], off offset:1024
	v_mul_f32_e32 v68, v68, v130
	v_mul_f32_e32 v69, v69, v130
	v_mul_f32_e32 v70, v70, v130
	v_mul_f32_e32 v71, v71, v130
	v_cvt_pk_bf16_f32 v64, v64, v65
	v_cvt_pk_bf16_f32 v65, v66, v67
	v_cvt_pk_bf16_f32 v66, v68, v69
	v_cvt_pk_bf16_f32 v67, v70, v71
	v_mul_f32_e32 v48, v48, v130
	v_mul_f32_e32 v49, v49, v130
	v_mul_f32_e32 v50, v50, v130
	v_mul_f32_e32 v51, v51, v130
	v_mul_f32_e32 v72, v72, v130
	v_mul_f32_e32 v73, v73, v130
	v_mul_f32_e32 v74, v74, v130
	v_mul_f32_e32 v75, v75, v130
	v_mul_f32_e32 v76, v76, v130
	v_mul_f32_e32 v77, v77, v130
	v_mul_f32_e32 v78, v78, v130
	v_mul_f32_e32 v79, v79, v130
	v_cvt_pk_bf16_f32 v68, v72, v73
	v_cvt_pk_bf16_f32 v69, v74, v75
	v_cvt_pk_bf16_f32 v70, v76, v77
	v_cvt_pk_bf16_f32 v71, v78, v79
	global_store_dwordx4 v[88:89], v[64:67], off offset:2048
	global_store_dwordx4 v[88:89], v[68:71], off offset:3072
	v_mul_f32_e32 v52, v52, v130
	v_mul_f32_e32 v53, v53, v130
	v_mul_f32_e32 v54, v54, v130
	v_mul_f32_e32 v55, v55, v130
	v_cvt_pk_bf16_f32 v48, v48, v49
	v_cvt_pk_bf16_f32 v49, v50, v51
	v_cvt_pk_bf16_f32 v50, v52, v53
	v_cvt_pk_bf16_f32 v51, v54, v55
	v_mul_f32_e32 v32, v32, v130
	v_mul_f32_e32 v33, v33, v130
	v_mul_f32_e32 v34, v34, v130
	v_mul_f32_e32 v35, v35, v130
	v_mul_f32_e32 v56, v56, v130
	v_mul_f32_e32 v57, v57, v130
	v_mul_f32_e32 v58, v58, v130
	v_mul_f32_e32 v59, v59, v130
	v_mul_f32_e32 v60, v60, v130
	v_mul_f32_e32 v61, v61, v130
	v_mul_f32_e32 v62, v62, v130
	v_mul_f32_e32 v63, v63, v130
	v_cvt_pk_bf16_f32 v52, v56, v57
	v_cvt_pk_bf16_f32 v53, v58, v59
	v_cvt_pk_bf16_f32 v54, v60, v61
	v_cvt_pk_bf16_f32 v55, v62, v63
	global_store_dwordx4 v[90:91], v[48:51], off
	global_store_dwordx4 v[90:91], v[52:55], off offset:1024
	v_mul_f32_e32 v36, v36, v130
	v_mul_f32_e32 v37, v37, v130
	v_mul_f32_e32 v38, v38, v130
	v_mul_f32_e32 v39, v39, v130
	v_cvt_pk_bf16_f32 v32, v32, v33
	v_cvt_pk_bf16_f32 v33, v34, v35
	v_cvt_pk_bf16_f32 v34, v36, v37
	v_cvt_pk_bf16_f32 v35, v38, v39
	v_mul_f32_e32 v16, v16, v130
	v_mul_f32_e32 v17, v17, v130
	v_mul_f32_e32 v18, v18, v130
	v_mul_f32_e32 v19, v19, v130
	v_mul_f32_e32 v20, v20, v130
	v_mul_f32_e32 v24, v24, v130
	v_mul_f32_e32 v40, v40, v130
	v_mul_f32_e32 v41, v41, v130
	v_mul_f32_e32 v42, v42, v130
	v_mul_f32_e32 v43, v43, v130
	v_mul_f32_e32 v44, v44, v130
	v_mul_f32_e32 v45, v45, v130
	v_mul_f32_e32 v46, v46, v130
	v_mul_f32_e32 v47, v47, v130
	v_cvt_pk_bf16_f32 v36, v40, v41
	v_cvt_pk_bf16_f32 v37, v42, v43
	v_cvt_pk_bf16_f32 v38, v44, v45
	v_cvt_pk_bf16_f32 v39, v46, v47
	global_store_dwordx4 v[90:91], v[32:35], off offset:2048
	global_store_dwordx4 v[90:91], v[36:39], off offset:3072
	v_mul_f32_e32 v21, v21, v130
	v_mul_f32_e32 v22, v22, v130
	v_mul_f32_e32 v23, v23, v130
	v_mul_f32_e32 v25, v25, v130
	v_cvt_pk_bf16_f32 v16, v16, v17
	v_cvt_pk_bf16_f32 v17, v18, v19
	v_cvt_pk_bf16_f32 v18, v20, v21
	v_cvt_pk_bf16_f32 v19, v22, v23
	v_cvt_pk_bf16_f32 v20, v24, v25
	v_add_co_u32_e32 v24, vcc, s75, v128
	v_mul_f32_e32 v0, v0, v130
	s_nop 0
	v_addc_co_u32_e32 v25, vcc, 0, v129, vcc
	v_mul_f32_e32 v1, v1, v130
	v_mul_f32_e32 v2, v2, v130
	v_mul_f32_e32 v3, v3, v130
	v_mul_f32_e32 v26, v26, v130
	v_mul_f32_e32 v27, v27, v130
	v_mul_f32_e32 v28, v28, v130
	v_mul_f32_e32 v29, v29, v130
	v_mul_f32_e32 v30, v30, v130
	v_mul_f32_e32 v31, v31, v130
	v_cvt_pk_bf16_f32 v21, v26, v27
	v_cvt_pk_bf16_f32 v22, v28, v29
	v_cvt_pk_bf16_f32 v23, v30, v31
	global_store_dwordx4 v[24:25], v[16:19], off
	global_store_dwordx4 v[24:25], v[20:23], off offset:1024
	v_mul_f32_e32 v4, v4, v130
	v_mul_f32_e32 v5, v5, v130
	v_mul_f32_e32 v6, v6, v130
	v_mul_f32_e32 v7, v7, v130
	v_mul_f32_e32 v8, v8, v130
	v_mul_f32_e32 v9, v9, v130
	v_mul_f32_e32 v10, v10, v130
	v_mul_f32_e32 v11, v11, v130
	v_mul_f32_e32 v12, v12, v130
	v_mul_f32_e32 v13, v13, v130
	v_mul_f32_e32 v14, v14, v130
	v_mul_f32_e32 v15, v15, v130
	v_cvt_pk_bf16_f32 v0, v0, v1
	v_cvt_pk_bf16_f32 v1, v2, v3
	v_cvt_pk_bf16_f32 v2, v4, v5
	v_cvt_pk_bf16_f32 v3, v6, v7
	v_cvt_pk_bf16_f32 v4, v8, v9
	v_cvt_pk_bf16_f32 v5, v10, v11
	v_cvt_pk_bf16_f32 v6, v12, v13
	v_cvt_pk_bf16_f32 v7, v14, v15
	global_store_dwordx4 v[24:25], v[0:3], off offset:2048
	global_store_dwordx4 v[24:25], v[4:7], off offset:3072
	s_nop 1
	v_mov_b32_e32 v4, v176
	s_add_u32 s42, s38, 0x100
	v_bfe_u32 v0, v4, 4, 2
	v_or_b32_e32 v1, s55, v0
	v_bitop3_b32 v0, v0, v4, s55 bitop3:0x36
	v_lshlrev_b32_e32 v2, 14, v1
	v_lshlrev_b32_e32 v0, 4, v0
	v_and_or_b32 v178, v0, s67, v2
	v_or_b32_e32 v0, 4, v1
	v_bitop3_b32 v1, v1, v4, 4 bitop3:0x36
	v_lshlrev_b32_e32 v0, 14, v0
	v_lshlrev_b32_e32 v1, 4, v1
	v_and_or_b32 v180, v1, s67, v0
	v_bfe_u32 v0, v4, 5, 1
	v_or_b32_e32 v1, s55, v0
	v_and_b32_e32 v2, 31, v4
	v_lshlrev_b32_e32 v3, 14, v1
	v_lshlrev_b32_e32 v0, 6, v0
	v_lshlrev_b32_e32 v5, 4, v2
	v_bitop3_b32 v182, v0, v3, v5 bitop3:0xde
	v_or_b32_e32 v0, 2, v1
	v_lshlrev_b32_e32 v3, 2, v0
	v_bitop3_b32 v3, v3, v2, 12 bitop3:0x6c
	v_lshlrev_b32_e32 v0, 14, v0
	s_addc_u32 s43, s39, 0
	v_lshl_or_b32 v184, v3, 4, v0
	v_or_b32_e32 v0, 6, v1
	v_lshlrev_b32_e32 v1, 2, v0
	s_cmp_lg_u32 0, -1
	v_bitop3_b32 v1, v1, v2, 12 bitop3:0x6c
	v_lshlrev_b32_e32 v0, 14, v0
	s_cselect_b32 s18, 0, 0
	v_lshl_or_b32 v188, v1, 4, v0
	v_lshl_add_u64 v[0:1], s[42:43], 0, v[178:179]
	s_add_i32 s19, s54, s18
	s_mov_b32 s34, m0
	s_mov_b32 m0, s19
	s_nop 0
	global_load_lds_dwordx4 v[0:1], off
	s_mov_b32 m0, s34
	v_mov_b32_e32 v181, v179
	s_add_i32 s18, s18, s33
	v_lshl_add_u64 v[0:1], s[42:43], 0, v[180:181]
	s_add_i32 s34, s19, 0x400
	s_mov_b32 s35, m0
	s_mov_b32 m0, s34
	s_nop 0
	global_load_lds_dwordx4 v[0:1], off
	s_mov_b32 m0, s35
	v_mov_b32_e32 v183, v179
	s_add_i32 s33, s18, 0xc000
	v_lshl_add_u64 v[0:1], s[16:17], 0, v[182:183]
	s_mov_b32 s34, m0
	s_mov_b32 m0, s33
	s_nop 0
	global_load_lds_dwordx4 v[0:1], off
	s_mov_b32 m0, s34
	v_mov_b32_e32 v185, v179
	s_add_i32 s33, s18, 0xc400
	v_or_b32_e32 v186, 0x10000, v182
	v_lshl_add_u64 v[0:1], s[16:17], 0, v[184:185]
	s_mov_b32 s34, m0
	s_mov_b32 m0, s33
	s_nop 0
	global_load_lds_dwordx4 v[0:1], off
	s_mov_b32 m0, s34
	v_mov_b32_e32 v187, v179
	s_add_i32 s33, s18, 0xc800
	v_lshl_add_u64 v[0:1], s[16:17], 0, v[186:187]
	s_mov_b32 s34, m0
	s_mov_b32 m0, s33
	s_nop 0
	global_load_lds_dwordx4 v[0:1], off
	s_mov_b32 m0, s34
	s_add_i32 s33, s18, 0xcc00
	v_mov_b32_e32 v189, v179
	s_add_u32 s54, s38, 0x100100
	v_lshl_add_u64 v[0:1], s[16:17], 0, v[188:189]
	s_addc_u32 s55, s39, 0
	s_mov_b32 s34, m0
	s_mov_b32 m0, s33
	s_nop 0
	global_load_lds_dwordx4 v[0:1], off
	s_mov_b32 m0, s34
	v_lshl_add_u64 v[0:1], s[54:55], 0, v[178:179]
	s_add_i32 s33, s19, 0x4000
	s_mov_b32 s34, m0
	s_mov_b32 m0, s33
	s_nop 0
	global_load_lds_dwordx4 v[0:1], off
	s_mov_b32 m0, s34
	v_lshl_add_u64 v[0:1], s[54:55], 0, v[180:181]
	s_addk_i32 s19, 0x4400
	s_mov_b32 s33, m0
	s_mov_b32 m0, s19
	s_nop 0
	global_load_lds_dwordx4 v[0:1], off
	s_mov_b32 m0, s33
	v_lshl_add_u64 v[0:1], s[10:11], 0, v[182:183]
	s_add_i32 s19, s18, 0x14000
	s_mov_b32 s33, m0
	s_mov_b32 m0, s19
	s_nop 0
	global_load_lds_dwordx4 v[0:1], off
	s_mov_b32 m0, s33
	v_lshl_add_u64 v[0:1], s[10:11], 0, v[184:185]
	s_add_i32 s19, s18, 0x14400
	s_mov_b32 s33, m0
	s_mov_b32 m0, s19
	s_nop 0
	global_load_lds_dwordx4 v[0:1], off
	s_mov_b32 m0, s33
	v_lshl_add_u64 v[0:1], s[10:11], 0, v[186:187]
	s_add_i32 s19, s18, 0x14800
	s_mov_b32 s33, m0
	s_mov_b32 m0, s19
	s_nop 0
	global_load_lds_dwordx4 v[0:1], off
	s_mov_b32 m0, s33
	v_lshl_add_u64 v[0:1], s[10:11], 0, v[188:189]
	s_add_i32 s18, s18, 0x14c00
	s_mov_b32 s19, m0
	s_mov_b32 m0, s18
	s_nop 0
	global_load_lds_dwordx4 v[0:1], off
	s_mov_b32 m0, s19
	v_or_b32_e32 v0, s80, v2
	v_mov_b32_e32 v1, s81
	v_lshlrev_b64 v[0:1], 14, v[0:1]
	v_lshrrev_b32_e32 v2, 1, v4
	v_lshl_add_u64 v[0:1], s[8:9], 0, v[0:1]
	v_and_b32_e32 v2, 16, v2
	v_mov_b32_e32 v3, v179
	v_lshl_add_u64 v[0:1], v[0:1], 0, v[2:3]
	global_load_dwordx4 v[144:147], v[0:1], off offset:256
	global_load_dwordx4 v[148:151], v[0:1], off offset:288
	global_load_dwordx4 v[152:155], v[0:1], off offset:320
	global_load_dwordx4 v[156:159], v[0:1], off offset:352
	global_load_dwordx4 v[160:163], v[0:1], off offset:384
	global_load_dwordx4 v[164:167], v[0:1], off offset:416
	global_load_dwordx4 v[168:171], v[0:1], off offset:448
	global_load_dwordx4 v[172:175], v[0:1], off offset:480
	v_lshrrev_b32_e32 v0, 5, v4
	v_and_b32_e32 v1, 15, v4
	v_bitop3_b32 v0, v0, v1, 1 bitop3:0x6c
	v_lshlrev_b32_e32 v1, 8, v4
	v_lshlrev_b32_e32 v0, 4, v0
	v_and_b32_e32 v1, 0x1f00, v1
	s_add_u32 s34, s65, s12
	v_mov_b32_e32 v14, v179
	v_mov_b32_e32 v15, v179
	v_or_b32_e32 v196, v0, v1
	v_bitop3_b32 v197, v0, 32, v1 bitop3:0x36
	v_bitop3_b32 v198, v0, 64, v1 bitop3:0x36
	v_bitop3_b32 v199, v0, s68, v1 bitop3:0x36
	v_bitop3_b32 v200, v0, s69, v1 bitop3:0x36
	v_bitop3_b32 v201, v0, s70, v1 bitop3:0x36
	v_bitop3_b32 v202, v0, s71, v1 bitop3:0x36
	v_bitop3_b32 v203, v0, s72, v1 bitop3:0x36
	s_waitcnt vmcnt(7)
	s_waitcnt vmcnt(6)
	s_waitcnt vmcnt(5)
	s_waitcnt vmcnt(4)
	s_waitcnt vmcnt(3)
	s_waitcnt vmcnt(2)
	s_waitcnt vmcnt(1)
	s_waitcnt vmcnt(0)
	s_waitcnt vmcnt(0)
	s_addc_u32 s35, s66, s13
	v_mov_b32_e32 v0, v179
	v_mov_b32_e32 v1, v179
	v_mov_b32_e32 v2, v179
	v_mov_b32_e32 v4, v179
	v_mov_b32_e32 v5, v179
	v_mov_b32_e32 v6, v179
	v_mov_b32_e32 v7, v179
	v_mov_b32_e32 v8, v179
	v_mov_b32_e32 v9, v179
	v_mov_b32_e32 v10, v179
	v_mov_b32_e32 v11, v179
	v_mov_b32_e32 v12, v179
	v_mov_b32_e32 v13, v179
	v_mov_b64_e32 v[30:31], v[14:15]
	v_mov_b64_e32 v[46:47], v[14:15]
	v_mov_b64_e32 v[62:63], v[14:15]
	v_mov_b64_e32 v[78:79], v[14:15]
	v_mov_b64_e32 v[94:95], v[14:15]
	v_mov_b64_e32 v[110:111], v[14:15]
	v_mov_b64_e32 v[126:127], v[14:15]
	v_mov_b32_e32 v190, 0xf149f2ca
	v_mov_b32_e32 v195, 0
	s_mov_b64 s[12:13], s[34:35]
	v_mov_b64_e32 v[28:29], v[12:13]
	v_mov_b64_e32 v[26:27], v[10:11]
	v_mov_b64_e32 v[24:25], v[8:9]
	v_mov_b64_e32 v[22:23], v[6:7]
	v_mov_b64_e32 v[20:21], v[4:5]
	v_mov_b64_e32 v[18:19], v[2:3]
	v_mov_b64_e32 v[16:17], v[0:1]
	v_mov_b64_e32 v[44:45], v[12:13]
	v_mov_b64_e32 v[42:43], v[10:11]
	v_mov_b64_e32 v[40:41], v[8:9]
	v_mov_b64_e32 v[38:39], v[6:7]
	v_mov_b64_e32 v[36:37], v[4:5]
	v_mov_b64_e32 v[34:35], v[2:3]
	v_mov_b64_e32 v[32:33], v[0:1]
	v_mov_b64_e32 v[60:61], v[12:13]
	v_mov_b64_e32 v[58:59], v[10:11]
	v_mov_b64_e32 v[56:57], v[8:9]
	v_mov_b64_e32 v[54:55], v[6:7]
	v_mov_b64_e32 v[52:53], v[4:5]
	v_mov_b64_e32 v[50:51], v[2:3]
	v_mov_b64_e32 v[48:49], v[0:1]
	v_mov_b64_e32 v[76:77], v[12:13]
	v_mov_b64_e32 v[74:75], v[10:11]
	v_mov_b64_e32 v[72:73], v[8:9]
	v_mov_b64_e32 v[70:71], v[6:7]
	v_mov_b64_e32 v[68:69], v[4:5]
	v_mov_b64_e32 v[66:67], v[2:3]
	v_mov_b64_e32 v[64:65], v[0:1]
	v_mov_b64_e32 v[92:93], v[12:13]
	v_mov_b64_e32 v[90:91], v[10:11]
	v_mov_b64_e32 v[88:89], v[8:9]
	v_mov_b64_e32 v[86:87], v[6:7]
	v_mov_b64_e32 v[84:85], v[4:5]
	v_mov_b64_e32 v[82:83], v[2:3]
	v_mov_b64_e32 v[80:81], v[0:1]
	v_mov_b64_e32 v[108:109], v[12:13]
	v_mov_b64_e32 v[106:107], v[10:11]
	v_mov_b64_e32 v[104:105], v[8:9]
	v_mov_b64_e32 v[102:103], v[6:7]
	v_mov_b64_e32 v[100:101], v[4:5]
	v_mov_b64_e32 v[98:99], v[2:3]
	v_mov_b64_e32 v[96:97], v[0:1]
	v_mov_b64_e32 v[124:125], v[12:13]
	v_mov_b64_e32 v[122:123], v[10:11]
	v_mov_b64_e32 v[120:121], v[8:9]
	v_mov_b64_e32 v[118:119], v[6:7]
	v_mov_b64_e32 v[116:117], v[4:5]
	v_mov_b64_e32 v[114:115], v[2:3]
	v_mov_b64_e32 v[112:113], v[0:1]
	s_mov_b32 s33, 0
	v_lshrrev_b32_e32 v246, 8, v220
	s_nop 0
	v_readfirstlane_b32 s100, v246
	s_nop 3
	s_cmp_lg_u32 s100, 0
	s_cbranch_scc0 .Latt_prio_1
	s_setprio 1

.LBB0_881:
	ds_bpermute_b32 v138, v194, v195
	v_mov_b32_e32 v153, v176
	v_mov_b32_e32 v149, s81
	v_lshlrev_b32_e32 v128, 4, v153
	v_and_b32_e32 v178, 0x3f0, v128
	v_lshl_add_u64 v[136:137], s[14:15], 0, v[178:179]
	s_waitcnt lgkmcnt(0)
	v_add_f32_e32 v152, v195, v138
	v_add_co_u32_e32 v138, vcc, s73, v136
	global_load_dwordx4 v[132:135], v178, s[14:15]
	global_load_dwordx4 v[128:131], v178, s[14:15] offset:1024
	global_load_dwordx4 v[144:147], v178, s[14:15] offset:2048
	global_load_dwordx4 v[140:143], v178, s[14:15] offset:3072
	v_addc_co_u32_e32 v139, vcc, 0, v137, vcc
	v_add_co_u32_e32 v150, vcc, s74, v136
	v_rcp_f32_e32 v152, v152
	s_nop 0
	v_addc_co_u32_e32 v151, vcc, 0, v137, vcc
	v_add_co_u32_e32 v154, vcc, s75, v136
	v_mul_f32_e32 v152, v177, v152
	s_nop 0
	v_addc_co_u32_e32 v155, vcc, 0, v137, vcc
	global_load_dwordx4 v[196:199], v[150:151], off offset:-4096
	global_load_dwordx4 v[200:203], v[138:139], off offset:1024
	global_load_dwordx4 v[204:207], v[138:139], off offset:2048
	global_load_dwordx4 v[208:211], v[138:139], off offset:3072
	s_nop 0
	global_load_dwordx4 v[136:139], v[154:155], off offset:3072
	v_and_or_b32 v148, v153, 31, s80
	s_lshl_b32 s4, s79, 1
	s_and_b32 s12, s77, 7
	s_lshl_b32 s79, s12, 8
	v_readfirstlane_b32 s12, v176
	s_ashr_i32 s86, s12, 6
	s_lshl_b32 s12, s78, 8
	s_lshl_b32 s13, s86, 5
	s_lshl_b32 s78, s78, 2
	s_add_i32 s80, s13, s12
	s_addk_i32 s79, 0x100
	s_add_i32 s78, s78, 4
	s_or_b32 s81, s80, 31
	s_lshl_b32 s83, s86, 3
	s_lshl_b32 s82, s86, 11
	s_lshl_b32 s33, s86, 12
	s_or_b32 s12, s40, s12
	s_ashr_i32 s14, s13, 31
	s_add_u32 s18, s12, s13
	s_addc_u32 s19, s41, s14
	s_cmp_lg_u32 0, -1
	s_cselect_b32 s12, 0, 0
	s_add_i32 s13, s12, 0xc000
	s_mov_b32 s84, 0
	s_mov_b32 s85, 2
	s_add_i32 s40, s82, s12
	s_add_i32 s41, s33, s13
	s_waitcnt vmcnt(8)
	v_lshlrev_b32_e32 v157, 16, v133
	v_lshlrev_b32_e32 v159, 16, v135
	s_waitcnt vmcnt(6)
	v_lshlrev_b32_e32 v164, 16, v144
	v_and_b32_e32 v144, 0xffff0000, v144
	v_lshlrev_b32_e32 v165, 16, v145
	v_lshlrev_b32_e32 v162, 16, v130
	v_and_b32_e32 v145, 0xffff0000, v145
	v_lshlrev_b32_e32 v168, 16, v146
	v_lshlrev_b32_e32 v169, 16, v147
	v_and_b32_e32 v147, 0xffff0000, v147
	v_fma_f32 v171, -v96, v152, v164
	v_fma_f32 v170, -v97, v152, v144
	v_fma_f32 v167, -v98, v152, v165
	s_waitcnt vmcnt(4)
	v_lshlrev_b32_e32 v96, 16, v196
	v_and_b32_e32 v97, 0xffff0000, v196
	v_lshlrev_b32_e32 v98, 16, v197
	v_fma_f32 v212, -v114, v152, v157
	v_fma_f32 v185, -v118, v152, v159
	v_fma_f32 v175, -v124, v152, v162
	v_fma_f32 v166, -v99, v152, v145
	v_fma_f32 v162, -v100, v152, v168
	v_fma_f32 v168, -v103, v152, v147
	v_fma_f32 v159, -v80, v152, v96
	v_fma_f32 v157, -v81, v152, v97
	v_fma_f32 v147, -v82, v152, v98
	global_load_dwordx4 v[96:99], v[150:151], off
	v_lshlrev_b32_e32 v160, 16, v128
	v_and_b32_e32 v146, 0xffff0000, v146
	v_lshlrev_b32_e32 v156, 16, v132
	v_lshlrev_b32_e32 v178, 16, v140
	v_lshlrev_b32_e32 v188, 16, v142
	v_and_b32_e32 v142, 0xffff0000, v142
	v_lshlrev_b32_e32 v189, 16, v143
	v_and_b32_e32 v143, 0xffff0000, v143
	v_fma_f32 v183, -v120, v152, v160
	v_fma_f32 v160, -v101, v152, v146
	v_fma_f32 v169, -v102, v152, v169
	v_lshlrev_b32_e32 v101, 16, v198
	v_and_b32_e32 v102, 0xffff0000, v198
	v_lshlrev_b32_e32 v161, 16, v129
	v_and_b32_e32 v130, 0xffff0000, v130
	v_lshlrev_b32_e32 v163, 16, v131
	v_and_b32_e32 v131, 0xffff0000, v131
	v_and_b32_e32 v140, 0xffff0000, v140
	v_lshlrev_b32_e32 v187, 16, v141
	v_and_b32_e32 v141, 0xffff0000, v141
	v_fma_f32 v190, -v112, v152, v156
	v_fma_f32 v165, -v104, v152, v178
	v_fma_f32 v156, -v109, v152, v142
	v_fma_f32 v144, -v111, v152, v143
	v_lshlrev_b32_e32 v103, 16, v199
	v_and_b32_e32 v104, 0xffff0000, v199
	v_fma_f32 v143, -v84, v152, v101
	v_fma_f32 v142, -v85, v152, v102
	s_waitcnt vmcnt(3)
	v_lshlrev_b32_e32 v84, 16, v204
	v_and_b32_e32 v85, 0xffff0000, v204
	v_fma_f32 v181, -v122, v152, v161
	v_fma_f32 v174, -v125, v152, v130
	v_fma_f32 v172, -v127, v152, v131
	v_fma_f32 v164, -v105, v152, v140
	v_fma_f32 v161, -v107, v152, v141
	v_fma_f32 v141, -v86, v152, v103
	v_fma_f32 v140, -v87, v152, v104
	v_fma_f32 v131, -v64, v152, v84
	v_fma_f32 v130, -v65, v152, v85
	global_load_dwordx4 v[84:87], v[150:151], off offset:2048
	v_and_b32_e32 v100, 0xffff0000, v197
	v_fma_f32 v146, -v83, v152, v100
	global_load_dwordx4 v[80:83], v[150:151], off offset:1024
	v_and_b32_e32 v132, 0xffff0000, v132
	v_fma_f32 v195, -v113, v152, v132
	v_mul_f32_e32 v215, v195, v195
	v_and_b32_e32 v133, 0xffff0000, v133
	v_fmac_f32_e32 v215, v190, v190
	v_lshlrev_b32_e32 v158, 16, v134
	v_fma_f32 v213, -v115, v152, v133
	v_fmac_f32_e32 v215, v212, v212
	v_and_b32_e32 v134, 0xffff0000, v134
	v_fma_f32 v214, -v116, v152, v158
	v_fmac_f32_e32 v215, v213, v213
	v_and_b32_e32 v135, 0xffff0000, v135
	v_fma_f32 v186, -v117, v152, v134
	v_fma_f32 v173, -v126, v152, v163
	v_fmac_f32_e32 v215, v214, v214
	v_fma_f32 v163, -v106, v152, v187
	v_lshlrev_b32_e32 v105, 16, v200
	v_and_b32_e32 v106, 0xffff0000, v200
	v_and_b32_e32 v128, 0xffff0000, v128
	v_fma_f32 v184, -v119, v152, v135
	v_fmac_f32_e32 v215, v186, v186
	v_fma_f32 v135, -v88, v152, v105
	v_fma_f32 v134, -v89, v152, v106
	v_lshlrev_b32_e32 v88, 16, v205
	v_and_b32_e32 v89, 0xffff0000, v205
	v_fma_f32 v182, -v121, v152, v128
	v_fmac_f32_e32 v215, v185, v185
	v_fma_f32 v128, -v66, v152, v88
	v_fma_f32 v126, -v67, v152, v89
	global_load_dwordx4 v[64:67], v[150:151], off offset:3072
	v_fmac_f32_e32 v215, v184, v184
	v_fmac_f32_e32 v215, v183, v183
	v_and_b32_e32 v129, 0xffff0000, v129
	v_fmac_f32_e32 v215, v182, v182
	v_fma_f32 v180, -v123, v152, v129
	v_fmac_f32_e32 v215, v181, v181
	v_fmac_f32_e32 v215, v180, v180
	v_fmac_f32_e32 v215, v175, v175
	v_fmac_f32_e32 v215, v174, v174
	v_fmac_f32_e32 v215, v173, v173
	global_load_dwordx4 v[196:199], v[154:155], off
	v_fmac_f32_e32 v215, v172, v172
	v_fmac_f32_e32 v215, v171, v171
	v_fmac_f32_e32 v215, v170, v170
	v_fmac_f32_e32 v215, v167, v167
	v_fmac_f32_e32 v215, v166, v166
	v_fma_f32 v158, -v108, v152, v188
	v_fma_f32 v145, -v110, v152, v189
	v_lshlrev_b32_e32 v107, 16, v201
	v_and_b32_e32 v108, 0xffff0000, v201
	v_lshlrev_b32_e32 v109, 16, v202
	v_and_b32_e32 v110, 0xffff0000, v202
	v_fmac_f32_e32 v215, v162, v162
	v_fma_f32 v133, -v90, v152, v107
	v_fma_f32 v132, -v91, v152, v108
	v_fma_f32 v129, -v92, v152, v109
	v_fma_f32 v127, -v93, v152, v110
	v_lshlrev_b32_e32 v90, 16, v206
	v_and_b32_e32 v91, 0xffff0000, v206
	v_lshlrev_b32_e32 v92, 16, v207
	v_and_b32_e32 v93, 0xffff0000, v207
	v_fmac_f32_e32 v215, v160, v160
	v_lshlrev_b32_e32 v111, 16, v203
	v_fma_f32 v123, -v68, v152, v90
	v_fma_f32 v122, -v69, v152, v91
	v_fma_f32 v121, -v70, v152, v92
	v_fma_f32 v120, -v71, v152, v93
	s_waitcnt vmcnt(4)
	v_lshlrev_b32_e32 v68, 16, v96
	v_and_b32_e32 v69, 0xffff0000, v96
	v_lshlrev_b32_e32 v70, 16, v97
	v_and_b32_e32 v71, 0xffff0000, v97
	v_fmac_f32_e32 v215, v169, v169
	v_fma_f32 v125, -v94, v152, v111
	v_fma_f32 v115, -v48, v152, v68
	v_fma_f32 v113, -v49, v152, v69
	v_fma_f32 v111, -v50, v152, v70
	v_fma_f32 v109, -v51, v152, v71
	global_load_dwordx4 v[48:51], v[154:155], off offset:1024
	v_fmac_f32_e32 v215, v168, v168
	v_fmac_f32_e32 v215, v165, v165
	v_fmac_f32_e32 v215, v164, v164
	v_fmac_f32_e32 v215, v163, v163
	v_fmac_f32_e32 v215, v161, v161
	v_and_b32_e32 v112, 0xffff0000, v203
	v_lshlrev_b32_e32 v94, 16, v208
	v_fmac_f32_e32 v215, v158, v158
	v_fma_f32 v124, -v95, v152, v112
	v_and_b32_e32 v95, 0xffff0000, v208
	v_lshlrev_b32_e32 v100, 16, v209
	v_and_b32_e32 v101, 0xffff0000, v209
	v_fma_f32 v119, -v72, v152, v94
	v_lshlrev_b32_e32 v72, 16, v98
	v_fmac_f32_e32 v215, v156, v156
	v_lshlrev_b32_e32 v104, 16, v211
	v_and_b32_e32 v105, 0xffff0000, v211
	v_fma_f32 v118, -v73, v152, v95
	v_fma_f32 v117, -v74, v152, v100
	v_fma_f32 v116, -v75, v152, v101
	v_and_b32_e32 v73, 0xffff0000, v98
	v_lshlrev_b32_e32 v74, 16, v99
	v_and_b32_e32 v75, 0xffff0000, v99
	v_fma_f32 v107, -v52, v152, v72
	s_waitcnt vmcnt(4)
	v_lshlrev_b32_e32 v52, 16, v84
	v_fmac_f32_e32 v215, v145, v145
	v_fma_f32 v110, -v78, v152, v104
	v_fma_f32 v108, -v79, v152, v105
	v_fma_f32 v106, -v53, v152, v73
	v_fma_f32 v105, -v54, v152, v74
	v_fma_f32 v104, -v55, v152, v75
	v_fma_f32 v99, -v32, v152, v52
	global_load_dwordx4 v[52:55], v[154:155], off offset:2048
	v_fmac_f32_e32 v215, v144, v144
	v_fmac_f32_e32 v215, v159, v159
	v_fmac_f32_e32 v215, v157, v157
	v_fmac_f32_e32 v215, v147, v147
	v_fmac_f32_e32 v215, v146, v146
	v_fmac_f32_e32 v215, v143, v143
	v_fmac_f32_e32 v215, v142, v142
	v_fmac_f32_e32 v215, v141, v141
	v_fmac_f32_e32 v215, v140, v140
	v_fmac_f32_e32 v215, v135, v135
	v_fmac_f32_e32 v215, v134, v134
	v_fmac_f32_e32 v215, v133, v133
	v_fmac_f32_e32 v215, v132, v132
	v_fmac_f32_e32 v215, v129, v129
	v_fmac_f32_e32 v215, v127, v127
	v_fmac_f32_e32 v215, v125, v125
	v_fmac_f32_e32 v215, v124, v124
	v_fmac_f32_e32 v215, v131, v131
	v_fmac_f32_e32 v215, v130, v130
	v_fmac_f32_e32 v215, v128, v128
	v_fmac_f32_e32 v215, v126, v126
	v_fmac_f32_e32 v215, v123, v123
	v_fmac_f32_e32 v215, v122, v122
	v_fmac_f32_e32 v215, v121, v121
	v_fmac_f32_e32 v215, v120, v120
	v_fmac_f32_e32 v215, v119, v119
	v_fmac_f32_e32 v215, v118, v118
	v_lshlrev_b32_e32 v102, 16, v210
	v_fmac_f32_e32 v215, v117, v117
	v_and_b32_e32 v103, 0xffff0000, v210
	v_fmac_f32_e32 v215, v116, v116
	v_fma_f32 v114, -v76, v152, v102
	v_fmac_f32_e32 v215, v114, v114
	v_fma_f32 v112, -v77, v152, v103
	v_fmac_f32_e32 v215, v112, v112
	v_fmac_f32_e32 v215, v110, v110
	v_fmac_f32_e32 v215, v108, v108
	v_fmac_f32_e32 v215, v115, v115
	v_fmac_f32_e32 v215, v113, v113
	v_fmac_f32_e32 v215, v111, v111
	v_fmac_f32_e32 v215, v109, v109
	v_fmac_f32_e32 v215, v107, v107
	v_fmac_f32_e32 v215, v106, v106
	s_waitcnt vmcnt(4)
	v_lshlrev_b32_e32 v76, 16, v80
	v_fmac_f32_e32 v215, v105, v105
	v_and_b32_e32 v77, 0xffff0000, v80
	v_fmac_f32_e32 v215, v104, v104
	v_fma_f32 v103, -v56, v152, v76
	v_lshlrev_b32_e32 v78, 16, v81
	v_fmac_f32_e32 v215, v103, v103
	v_fma_f32 v102, -v57, v152, v77
	v_and_b32_e32 v79, 0xffff0000, v81
	v_fmac_f32_e32 v215, v102, v102
	v_fma_f32 v101, -v58, v152, v78
	v_lshlrev_b32_e32 v80, 16, v82
	v_fmac_f32_e32 v215, v101, v101
	v_fma_f32 v100, -v59, v152, v79
	v_and_b32_e32 v81, 0xffff0000, v82
	v_fmac_f32_e32 v215, v100, v100
	v_fma_f32 v96, -v60, v152, v80
	v_lshlrev_b32_e32 v82, 16, v83
	v_fmac_f32_e32 v215, v96, v96
	v_fma_f32 v95, -v61, v152, v81
	v_and_b32_e32 v83, 0xffff0000, v83
	v_fmac_f32_e32 v215, v95, v95
	v_fma_f32 v92, -v62, v152, v82
	v_fmac_f32_e32 v215, v92, v92
	v_fma_f32 v91, -v63, v152, v83
	v_fmac_f32_e32 v215, v91, v91
	v_and_b32_e32 v56, 0xffff0000, v84
	v_lshlrev_b32_e32 v57, 16, v85
	v_fmac_f32_e32 v215, v99, v99
	v_fma_f32 v97, -v33, v152, v56
	v_and_b32_e32 v58, 0xffff0000, v85
	v_fmac_f32_e32 v215, v97, v97
	v_fma_f32 v94, -v34, v152, v57
	v_lshlrev_b32_e32 v59, 16, v86
	v_fmac_f32_e32 v215, v94, v94
	v_fma_f32 v93, -v35, v152, v58
	v_and_b32_e32 v60, 0xffff0000, v86
	v_fmac_f32_e32 v215, v93, v93
	v_fma_f32 v89, -v36, v152, v59
	v_lshlrev_b32_e32 v61, 16, v87
	v_fmac_f32_e32 v215, v89, v89
	v_fma_f32 v88, -v37, v152, v60
	v_and_b32_e32 v62, 0xffff0000, v87
	v_fmac_f32_e32 v215, v88, v88
	v_fma_f32 v87, -v38, v152, v61
	s_waitcnt vmcnt(3)
	v_lshlrev_b32_e32 v63, 16, v64
	v_fmac_f32_e32 v215, v87, v87
	v_fma_f32 v86, -v39, v152, v62
	v_and_b32_e32 v64, 0xffff0000, v64
	v_fmac_f32_e32 v215, v86, v86
	v_fma_f32 v85, -v40, v152, v63
	v_lshlrev_b32_e32 v68, 16, v65
	v_fmac_f32_e32 v215, v85, v85
	v_fma_f32 v84, -v41, v152, v64
	v_and_b32_e32 v65, 0xffff0000, v65
	v_fmac_f32_e32 v215, v84, v84
	v_fma_f32 v83, -v42, v152, v68
	v_lshlrev_b32_e32 v69, 16, v66
	v_fmac_f32_e32 v215, v83, v83
	v_fma_f32 v82, -v43, v152, v65
	v_and_b32_e32 v66, 0xffff0000, v66
	v_fmac_f32_e32 v215, v82, v82
	v_fma_f32 v80, -v44, v152, v69
	v_lshlrev_b32_e32 v70, 16, v67
	v_fmac_f32_e32 v215, v80, v80
	v_fma_f32 v78, -v45, v152, v66
	v_and_b32_e32 v67, 0xffff0000, v67
	v_fmac_f32_e32 v215, v78, v78
	v_fma_f32 v76, -v46, v152, v70
	v_fmac_f32_e32 v215, v76, v76
	v_fma_f32 v74, -v47, v152, v67
	s_waitcnt vmcnt(2)
	v_lshlrev_b32_e32 v32, 16, v196
	v_fmac_f32_e32 v215, v74, v74
	v_and_b32_e32 v33, 0xffff0000, v196
	v_fma_f32 v81, -v16, v152, v32
	v_lshlrev_b32_e32 v34, 16, v197
	v_fmac_f32_e32 v215, v81, v81
	v_fma_f32 v79, -v17, v152, v33
	v_and_b32_e32 v35, 0xffff0000, v197
	v_fmac_f32_e32 v215, v79, v79
	v_fma_f32 v77, -v18, v152, v34
	v_lshlrev_b32_e32 v36, 16, v198
	v_fmac_f32_e32 v215, v77, v77
	v_fma_f32 v75, -v19, v152, v35
	v_and_b32_e32 v37, 0xffff0000, v198
	v_fmac_f32_e32 v215, v75, v75
	v_fma_f32 v73, -v20, v152, v36
	v_lshlrev_b32_e32 v38, 16, v199
	v_fmac_f32_e32 v215, v73, v73
	v_fma_f32 v72, -v21, v152, v37
	v_and_b32_e32 v39, 0xffff0000, v199
	v_fmac_f32_e32 v215, v72, v72
	v_fma_f32 v71, -v22, v152, v38
	s_waitcnt vmcnt(1)
	v_lshlrev_b32_e32 v40, 16, v48
	v_fmac_f32_e32 v215, v71, v71
	v_fma_f32 v70, -v23, v152, v39
	v_and_b32_e32 v41, 0xffff0000, v48
	v_fmac_f32_e32 v215, v70, v70
	v_fma_f32 v69, -v24, v152, v40
	v_lshlrev_b32_e32 v42, 16, v49
	v_fmac_f32_e32 v215, v69, v69
	v_fma_f32 v68, -v25, v152, v41
	v_and_b32_e32 v43, 0xffff0000, v49
	v_fmac_f32_e32 v215, v68, v68
	v_fma_f32 v67, -v26, v152, v42
	v_lshlrev_b32_e32 v44, 16, v50
	v_fmac_f32_e32 v215, v67, v67
	v_fma_f32 v66, -v27, v152, v43
	v_and_b32_e32 v45, 0xffff0000, v50
	v_fmac_f32_e32 v215, v66, v66
	v_fma_f32 v65, -v28, v152, v44
	v_lshlrev_b32_e32 v46, 16, v51
	v_fmac_f32_e32 v215, v65, v65
	v_fma_f32 v64, -v29, v152, v45
	v_and_b32_e32 v47, 0xffff0000, v51
	v_fmac_f32_e32 v215, v64, v64
	v_fma_f32 v63, -v30, v152, v46
	v_fmac_f32_e32 v215, v63, v63
	v_fma_f32 v62, -v31, v152, v47
	s_waitcnt vmcnt(0)
	v_lshlrev_b32_e32 v16, 16, v52
	v_fmac_f32_e32 v215, v62, v62
	v_and_b32_e32 v17, 0xffff0000, v52
	v_fma_f32 v61, -v0, v152, v16
	v_lshlrev_b32_e32 v18, 16, v53
	v_lshlrev_b32_e32 v20, 16, v54
	v_and_b32_e32 v21, 0xffff0000, v54
	v_fmac_f32_e32 v215, v61, v61
	v_fma_f32 v60, -v1, v152, v17
	v_and_b32_e32 v1, 0xffff0000, v55
	v_lshlrev_b32_e32 v0, 16, v55
	v_and_b32_e32 v19, 0xffff0000, v53
	v_fmac_f32_e32 v215, v60, v60
	v_fma_f32 v59, -v2, v152, v18
	v_fma_f32 v57, -v4, v152, v20
	v_fma_f32 v56, -v5, v152, v21
	v_pk_fma_f32 v[0:1], v[6:7], v[152:153], v[0:1] op_sel_hi:[1,0,1] neg_lo:[1,0,0] neg_hi:[1,0,0]
	v_lshlrev_b64 v[4:5], 14, v[148:149]
	v_lshrrev_b32_e32 v6, 3, v153
	v_fmac_f32_e32 v215, v59, v59
	v_fma_f32 v58, -v3, v152, v19
	v_lshl_add_u64 v[4:5], s[2:3], 0, v[4:5]
	v_and_b32_e32 v90, 4, v6
	v_fmac_f32_e32 v215, v58, v58
	v_lshl_add_u64 v[4:5], v[4:5], 0, s[4:5]
	v_lshlrev_b32_e32 v178, 1, v90
	v_fmac_f32_e32 v215, v57, v57
	v_lshl_add_u64 v[4:5], v[4:5], 0, v[178:179]
	v_fmac_f32_e32 v215, v56, v56
	v_pk_mul_f32 v[2:3], v[0:1], v[0:1]
	v_add_co_u32_e32 v148, vcc, s75, v4
	v_add_f32_e32 v2, v2, v215
	s_waitcnt vmcnt(0)
	s_nop 0
	v_addc_co_u32_e32 v149, vcc, 0, v5, vcc
	global_load_dwordx2 v[150:151], v[148:149], off
	v_add_f32_e32 v6, v3, v2
	v_and_b32_e32 v3, 0xffff0000, v136
	v_lshlrev_b32_e32 v2, 16, v136
	v_pk_fma_f32 v[16:17], v[8:9], v[152:153], v[2:3] op_sel_hi:[1,0,1] neg_lo:[1,0,0] neg_hi:[1,0,0]
	s_nop 0
	v_pk_mul_f32 v[2:3], v[16:17], v[16:17]
	s_nop 0
	v_add_f32_e32 v2, v2, v6
	v_add_f32_e32 v6, v3, v2
	v_and_b32_e32 v3, 0xffff0000, v137
	v_lshlrev_b32_e32 v2, 16, v137
	v_pk_fma_f32 v[8:9], v[10:11], v[152:153], v[2:3] op_sel_hi:[1,0,1] neg_lo:[1,0,0] neg_hi:[1,0,0]
	v_and_b32_e32 v11, 0xffff0000, v139
	v_pk_mul_f32 v[2:3], v[8:9], v[8:9]
	s_nop 0
	v_add_f32_e32 v2, v2, v6
	v_add_f32_e32 v10, v3, v2
	v_and_b32_e32 v3, 0xffff0000, v138
	v_lshlrev_b32_e32 v2, 16, v138
	v_pk_fma_f32 v[6:7], v[12:13], v[152:153], v[2:3] op_sel_hi:[1,0,1] neg_lo:[1,0,0] neg_hi:[1,0,0]
	s_nop 0
	v_pk_mul_f32 v[2:3], v[6:7], v[6:7]
	s_nop 0
	v_add_f32_e32 v2, v2, v10
	v_add_f32_e32 v12, v3, v2
	v_lshl_add_u64 v[2:3], v[4:5], 0, s[6:7]
	global_load_dwordx2 v[154:155], v[2:3], off offset:16
	v_lshlrev_b32_e32 v10, 16, v139
	v_pk_fma_f32 v[4:5], v[14:15], v[152:153], v[10:11] op_sel_hi:[1,0,1] neg_lo:[1,0,0] neg_hi:[1,0,0]
	global_load_dwordx2 v[152:153], v[2:3], off offset:32
	global_load_dwordx2 v[188:189], v[2:3], off offset:48
	global_load_dwordx2 v[196:197], v[2:3], off offset:64
	global_load_dwordx2 v[198:199], v[2:3], off offset:80
	global_load_dwordx2 v[200:201], v[2:3], off offset:96
	global_load_dwordx2 v[202:203], v[2:3], off offset:112
	global_load_dwordx2 v[204:205], v[2:3], off offset:128
	global_load_dwordx2 v[206:207], v[2:3], off offset:144
	global_load_dwordx2 v[54:55], v[2:3], off offset:160
	global_load_dwordx2 v[52:53], v[2:3], off offset:176
	global_load_dwordx2 v[50:51], v[2:3], off offset:192
	global_load_dwordx2 v[48:49], v[2:3], off offset:208
	global_load_dwordx2 v[46:47], v[2:3], off offset:224
	global_load_dwordx2 v[44:45], v[2:3], off offset:240
	global_load_dwordx2 v[42:43], v[2:3], off offset:256
	global_load_dwordx2 v[40:41], v[2:3], off offset:272
	global_load_dwordx2 v[38:39], v[2:3], off offset:288
	global_load_dwordx2 v[36:37], v[2:3], off offset:304
	global_load_dwordx2 v[34:35], v[2:3], off offset:320
	global_load_dwordx2 v[32:33], v[2:3], off offset:336
	global_load_dwordx2 v[30:31], v[2:3], off offset:352
	global_load_dwordx2 v[28:29], v[2:3], off offset:368
	global_load_dwordx2 v[26:27], v[2:3], off offset:384
	global_load_dwordx2 v[24:25], v[2:3], off offset:400
	global_load_dwordx2 v[22:23], v[2:3], off offset:416
	global_load_dwordx2 v[20:21], v[2:3], off offset:432
	global_load_dwordx2 v[18:19], v[2:3], off offset:448
	v_pk_mul_f32 v[10:11], v[4:5], v[4:5]
	s_nop 0
	v_add_f32_e32 v10, v10, v12
	v_add_f32_e32 v10, v11, v10
	ds_bpermute_b32 v11, v194, v10
	s_waitcnt lgkmcnt(0)
	v_add_f32_e32 v10, v10, v11
	v_fmamk_f32 v10, v10, 0x3b800000, v191
	v_mul_f32_e32 v11, 0x4b800000, v10
	v_cmp_gt_f32_e32 vcc, s76, v10
	s_nop 1
	v_cndmask_b32_e32 v10, v10, v11, vcc
	v_rsq_f32_e32 v10, v10
	s_nop 0
	v_mul_f32_e32 v11, 0x45800000, v10
	v_cndmask_b32_e32 v178, v10, v11, vcc
	v_lshl_add_u32 v10, v90, 2, 0
	v_add_u32_e32 v98, 0x24000, v10
	ds_read_b128 v[136:139], v98
	v_mul_f32_e32 v90, 0x3f24fd5c, v178
	v_mul_f32_e32 v178, v190, v90
	global_load_dwordx2 v[14:15], v[2:3], off offset:464
	global_load_dwordx2 v[12:13], v[2:3], off offset:480
	global_load_dwordx2 v[10:11], v[2:3], off offset:496
	v_mul_f32_e32 v143, v143, v90
	s_waitcnt lgkmcnt(0)
	v_mul_f32_e32 v136, v136, v178
	v_mul_f32_e32 v142, v142, v90
	v_mul_f32_e32 v135, v135, v90
	v_mul_f32_e32 v134, v134, v90
	v_mul_f32_e32 v133, v133, v90
	v_mul_f32_e32 v132, v132, v90
	v_mul_f32_e32 v0, v0, v90
	v_mul_f32_e32 v1, v1, v90
	s_waitcnt vmcnt(31)
	v_lshlrev_b32_e32 v178, 16, v150
	v_mul_f32_e32 v136, v136, v178
	v_mul_f32_e32 v178, v195, v90
	v_mul_f32_e32 v137, v137, v178
	v_and_b32_e32 v150, 0xffff0000, v150
	v_mul_f32_e32 v137, v137, v150
	v_cvt_pk_bf16_f32 v150, v136, v137
	v_mul_f32_e32 v136, v212, v90
	v_mul_f32_e32 v136, v138, v136
	v_lshlrev_b32_e32 v137, 16, v151
	v_mul_f32_e32 v136, v136, v137
	v_mul_f32_e32 v137, v213, v90
	v_mul_f32_e32 v137, v139, v137
	v_and_b32_e32 v138, 0xffff0000, v151
	v_mul_f32_e32 v137, v137, v138
	v_cvt_pk_bf16_f32 v151, v136, v137
	ds_read_b128 v[136:139], v98 offset:32
	global_store_dwordx2 v[148:149], v[150:151], off
	v_mul_f32_e32 v148, v214, v90
	s_waitcnt lgkmcnt(0)
	v_mul_f32_e32 v136, v136, v148
	s_waitcnt vmcnt(31)
	v_lshlrev_b32_e32 v148, 16, v154
	v_mul_f32_e32 v136, v136, v148
	v_mul_f32_e32 v148, v186, v90
	v_mul_f32_e32 v137, v137, v148
	v_and_b32_e32 v148, 0xffff0000, v154
	v_mul_f32_e32 v137, v137, v148
	v_cvt_pk_bf16_f32 v148, v136, v137
	v_mul_f32_e32 v136, v185, v90
	v_mul_f32_e32 v136, v138, v136
	v_lshlrev_b32_e32 v137, 16, v155
	v_mul_f32_e32 v136, v136, v137
	v_mul_f32_e32 v137, v184, v90
	v_mul_f32_e32 v137, v139, v137
	v_and_b32_e32 v138, 0xffff0000, v155
	v_mul_f32_e32 v137, v137, v138
	v_cvt_pk_bf16_f32 v149, v136, v137
	ds_read_b128 v[136:139], v98 offset:64
	global_store_dwordx2 v[2:3], v[148:149], off offset:16
	v_mul_f32_e32 v148, v183, v90
	s_waitcnt lgkmcnt(0)
	v_mul_f32_e32 v136, v136, v148
	s_waitcnt vmcnt(31)
	v_lshlrev_b32_e32 v148, 16, v152
	v_mul_f32_e32 v136, v136, v148
	v_mul_f32_e32 v148, v182, v90
	v_mul_f32_e32 v137, v137, v148
	v_and_b32_e32 v148, 0xffff0000, v152
	v_mul_f32_e32 v137, v137, v148
	v_cvt_pk_bf16_f32 v148, v136, v137
	v_mul_f32_e32 v136, v181, v90
	v_mul_f32_e32 v136, v138, v136
	v_lshlrev_b32_e32 v137, 16, v153
	v_mul_f32_e32 v136, v136, v137
	v_mul_f32_e32 v137, v180, v90
	v_mul_f32_e32 v137, v139, v137
	v_and_b32_e32 v138, 0xffff0000, v153
	v_mul_f32_e32 v137, v137, v138
	v_cvt_pk_bf16_f32 v149, v136, v137
	ds_read_b128 v[136:139], v98 offset:96
	global_store_dwordx2 v[2:3], v[148:149], off offset:32
	v_mul_f32_e32 v148, v175, v90
	s_waitcnt lgkmcnt(0)
	v_mul_f32_e32 v136, v136, v148
	s_waitcnt vmcnt(31)
	v_lshlrev_b32_e32 v148, 16, v188
	v_mul_f32_e32 v136, v136, v148
	v_mul_f32_e32 v148, v174, v90
	v_mul_f32_e32 v137, v137, v148
	v_and_b32_e32 v148, 0xffff0000, v188
	v_mul_f32_e32 v137, v137, v148
	v_cvt_pk_bf16_f32 v148, v136, v137
	v_mul_f32_e32 v136, v173, v90
	v_mul_f32_e32 v136, v138, v136
	v_lshlrev_b32_e32 v137, 16, v189
	v_mul_f32_e32 v136, v136, v137
	v_mul_f32_e32 v137, v172, v90
	v_mul_f32_e32 v137, v139, v137
	v_and_b32_e32 v138, 0xffff0000, v189
	v_mul_f32_e32 v137, v137, v138
	v_cvt_pk_bf16_f32 v149, v136, v137
	ds_read_b128 v[136:139], v98 offset:128
	global_store_dwordx2 v[2:3], v[148:149], off offset:48
	v_mul_f32_e32 v148, v171, v90
	s_waitcnt lgkmcnt(0)
	v_mul_f32_e32 v136, v136, v148
	s_waitcnt vmcnt(31)
	v_lshlrev_b32_e32 v148, 16, v196
	v_mul_f32_e32 v136, v136, v148
	v_mul_f32_e32 v148, v170, v90
	v_mul_f32_e32 v137, v137, v148
	v_and_b32_e32 v148, 0xffff0000, v196
	v_mul_f32_e32 v137, v137, v148
	v_cvt_pk_bf16_f32 v148, v136, v137
	v_mul_f32_e32 v136, v167, v90
	v_mul_f32_e32 v136, v138, v136
	v_lshlrev_b32_e32 v137, 16, v197
	v_mul_f32_e32 v136, v136, v137
	v_mul_f32_e32 v137, v166, v90
	v_mul_f32_e32 v137, v139, v137
	v_and_b32_e32 v138, 0xffff0000, v197
	v_mul_f32_e32 v137, v137, v138
	v_cvt_pk_bf16_f32 v149, v136, v137
	ds_read_b128 v[136:139], v98 offset:160
	global_store_dwordx2 v[2:3], v[148:149], off offset:64
	v_mul_f32_e32 v148, v162, v90
	s_waitcnt lgkmcnt(0)
	v_mul_f32_e32 v136, v136, v148
	s_waitcnt vmcnt(31)
	v_lshlrev_b32_e32 v148, 16, v198
	v_mul_f32_e32 v136, v136, v148
	v_mul_f32_e32 v148, v160, v90
	v_mul_f32_e32 v137, v137, v148
	v_and_b32_e32 v148, 0xffff0000, v198
	v_mul_f32_e32 v137, v137, v148
	v_cvt_pk_bf16_f32 v148, v136, v137
	v_mul_f32_e32 v136, v169, v90
	v_mul_f32_e32 v136, v138, v136
	v_lshlrev_b32_e32 v137, 16, v199
	v_mul_f32_e32 v136, v136, v137
	v_mul_f32_e32 v137, v168, v90
	v_mul_f32_e32 v137, v139, v137
	v_and_b32_e32 v138, 0xffff0000, v199
	v_mul_f32_e32 v137, v137, v138
	v_cvt_pk_bf16_f32 v149, v136, v137
	ds_read_b128 v[136:139], v98 offset:192
	global_store_dwordx2 v[2:3], v[148:149], off offset:80
	v_mul_f32_e32 v148, v165, v90
	s_waitcnt lgkmcnt(0)
	v_mul_f32_e32 v136, v136, v148
	s_waitcnt vmcnt(31)
	v_lshlrev_b32_e32 v148, 16, v200
	v_mul_f32_e32 v136, v136, v148
	v_mul_f32_e32 v148, v164, v90
	v_mul_f32_e32 v137, v137, v148
	v_and_b32_e32 v148, 0xffff0000, v200
	v_mul_f32_e32 v137, v137, v148
	v_cvt_pk_bf16_f32 v148, v136, v137
	v_mul_f32_e32 v136, v163, v90
	v_mul_f32_e32 v136, v138, v136
	v_lshlrev_b32_e32 v137, 16, v201
	v_mul_f32_e32 v136, v136, v137
	v_mul_f32_e32 v137, v161, v90
	v_mul_f32_e32 v137, v139, v137
	v_and_b32_e32 v138, 0xffff0000, v201
	v_mul_f32_e32 v137, v137, v138
	v_cvt_pk_bf16_f32 v149, v136, v137
	ds_read_b128 v[136:139], v98 offset:224
	global_store_dwordx2 v[2:3], v[148:149], off offset:96
	v_mul_f32_e32 v148, v158, v90
	s_waitcnt lgkmcnt(0)
	v_mul_f32_e32 v136, v136, v148
	s_waitcnt vmcnt(31)
	v_lshlrev_b32_e32 v148, 16, v202
	v_mul_f32_e32 v136, v136, v148
	v_mul_f32_e32 v148, v156, v90
	v_mul_f32_e32 v137, v137, v148
	v_and_b32_e32 v148, 0xffff0000, v202
	v_mul_f32_e32 v137, v137, v148
	v_cvt_pk_bf16_f32 v148, v136, v137
	v_mul_f32_e32 v136, v145, v90
	v_mul_f32_e32 v136, v138, v136
	v_lshlrev_b32_e32 v137, 16, v203
	v_mul_f32_e32 v136, v136, v137
	v_mul_f32_e32 v137, v144, v90
	v_mul_f32_e32 v137, v139, v137
	v_and_b32_e32 v138, 0xffff0000, v203
	v_mul_f32_e32 v137, v137, v138
	v_cvt_pk_bf16_f32 v149, v136, v137
	ds_read_b128 v[136:139], v98 offset:256
	v_mul_f32_e32 v144, v159, v90
	global_store_dwordx2 v[2:3], v[148:149], off offset:112
	s_waitcnt lgkmcnt(0)
	v_mul_f32_e32 v136, v136, v144
	s_waitcnt vmcnt(31)
	v_lshlrev_b32_e32 v144, 16, v204
	v_mul_f32_e32 v136, v136, v144
	v_mul_f32_e32 v144, v157, v90
	v_mul_f32_e32 v137, v137, v144
	v_and_b32_e32 v144, 0xffff0000, v204
	v_mul_f32_e32 v137, v137, v144
	v_cvt_pk_bf16_f32 v144, v136, v137
	v_mul_f32_e32 v136, v147, v90
	v_mul_f32_e32 v136, v138, v136
	v_lshlrev_b32_e32 v137, 16, v205
	v_mul_f32_e32 v136, v136, v137
	v_mul_f32_e32 v137, v146, v90
	v_mul_f32_e32 v137, v139, v137
	v_and_b32_e32 v138, 0xffff0000, v205
	v_mul_f32_e32 v137, v137, v138
	v_cvt_pk_bf16_f32 v145, v136, v137
	ds_read_b128 v[136:139], v98 offset:288
	global_store_dwordx2 v[2:3], v[144:145], off offset:128
	s_waitcnt lgkmcnt(0)
	v_mul_f32_e32 v136, v136, v143
	s_waitcnt vmcnt(31)
	v_lshlrev_b32_e32 v143, 16, v206
	v_mul_f32_e32 v136, v136, v143
	v_mul_f32_e32 v137, v137, v142
	v_and_b32_e32 v142, 0xffff0000, v206
	v_mul_f32_e32 v137, v137, v142
	v_cvt_pk_bf16_f32 v142, v136, v137
	v_mul_f32_e32 v136, v141, v90
	v_mul_f32_e32 v136, v138, v136
	v_lshlrev_b32_e32 v137, 16, v207
	v_mul_f32_e32 v136, v136, v137
	v_mul_f32_e32 v137, v140, v90
	v_mul_f32_e32 v137, v139, v137
	v_and_b32_e32 v138, 0xffff0000, v207
	v_mul_f32_e32 v137, v137, v138
	v_cvt_pk_bf16_f32 v143, v136, v137
	ds_read_b128 v[136:139], v98 offset:320
	global_store_dwordx2 v[2:3], v[142:143], off offset:144
	s_waitcnt lgkmcnt(0)
	v_mul_f32_e32 v135, v136, v135
	s_waitcnt vmcnt(31)
	v_lshlrev_b32_e32 v136, 16, v54
	v_mul_f32_e32 v134, v137, v134
	v_and_b32_e32 v54, 0xffff0000, v54
	v_mul_f32_e32 v54, v134, v54
	v_mul_f32_e32 v133, v138, v133
	v_lshlrev_b32_e32 v134, 16, v55
	v_mul_f32_e32 v132, v139, v132
	v_and_b32_e32 v55, 0xffff0000, v55
	v_mul_f32_e32 v135, v135, v136
	v_mul_f32_e32 v133, v133, v134
	v_mul_f32_e32 v55, v132, v55
	v_cvt_pk_bf16_f32 v54, v135, v54
	v_cvt_pk_bf16_f32 v55, v133, v55
	ds_read_b128 v[132:135], v98 offset:352
	global_store_dwordx2 v[2:3], v[54:55], off offset:160
	v_mul_f32_e32 v54, v129, v90
	s_waitcnt vmcnt(31)
	v_lshlrev_b32_e32 v55, 16, v52
	v_and_b32_e32 v52, 0xffff0000, v52
	s_waitcnt lgkmcnt(0)
	v_mul_f32_e32 v54, v132, v54
	v_mul_f32_e32 v54, v54, v55
	v_mul_f32_e32 v55, v127, v90
	v_mul_f32_e32 v55, v133, v55
	v_mul_f32_e32 v52, v55, v52
	v_cvt_pk_bf16_f32 v132, v54, v52
	v_mul_f32_e32 v52, v125, v90
	v_mul_f32_e32 v52, v134, v52
	v_lshlrev_b32_e32 v54, 16, v53
	v_mul_f32_e32 v52, v52, v54
	v_mul_f32_e32 v54, v124, v90
	v_mul_f32_e32 v54, v135, v54
	v_and_b32_e32 v53, 0xffff0000, v53
	v_mul_f32_e32 v53, v54, v53
	v_cvt_pk_bf16_f32 v133, v52, v53
	ds_read_b128 v[52:55], v98 offset:384
	v_mul_f32_e32 v124, v131, v90
	global_store_dwordx2 v[2:3], v[132:133], off offset:176
	s_waitcnt lgkmcnt(0)
	v_mul_f32_e32 v52, v52, v124
	s_waitcnt vmcnt(31)
	v_lshlrev_b32_e32 v124, 16, v50
	v_mul_f32_e32 v52, v52, v124
	v_mul_f32_e32 v124, v130, v90
	v_mul_f32_e32 v53, v53, v124
	v_and_b32_e32 v50, 0xffff0000, v50
	v_mul_f32_e32 v50, v53, v50
	v_cvt_pk_bf16_f32 v124, v52, v50
	v_mul_f32_e32 v50, v128, v90
	v_mul_f32_e32 v50, v54, v50
	v_lshlrev_b32_e32 v52, 16, v51
	v_mul_f32_e32 v50, v50, v52
	v_mul_f32_e32 v52, v126, v90
	v_mul_f32_e32 v52, v55, v52
	v_and_b32_e32 v51, 0xffff0000, v51
	v_mul_f32_e32 v51, v52, v51
	v_cvt_pk_bf16_f32 v125, v50, v51
	ds_read_b128 v[50:53], v98 offset:416
	v_mul_f32_e32 v54, v123, v90
	global_store_dwordx2 v[2:3], v[124:125], off offset:192
	s_waitcnt lgkmcnt(0)
	v_mul_f32_e32 v50, v50, v54
	s_waitcnt vmcnt(31)
	v_lshlrev_b32_e32 v54, 16, v48
	v_mul_f32_e32 v50, v50, v54
	v_mul_f32_e32 v54, v122, v90
	v_mul_f32_e32 v51, v51, v54
	v_and_b32_e32 v48, 0xffff0000, v48
	v_mul_f32_e32 v48, v51, v48
	v_cvt_pk_bf16_f32 v54, v50, v48
	v_mul_f32_e32 v48, v121, v90
	v_mul_f32_e32 v48, v52, v48
	v_lshlrev_b32_e32 v50, 16, v49
	v_mul_f32_e32 v48, v48, v50
	v_mul_f32_e32 v50, v120, v90
	v_mul_f32_e32 v50, v53, v50
	v_and_b32_e32 v49, 0xffff0000, v49
	v_mul_f32_e32 v49, v50, v49
	v_cvt_pk_bf16_f32 v55, v48, v49
	ds_read_b128 v[48:51], v98 offset:448
	v_mul_f32_e32 v52, v119, v90
	global_store_dwordx2 v[2:3], v[54:55], off offset:208
	s_waitcnt lgkmcnt(0)
	v_mul_f32_e32 v48, v48, v52
	s_waitcnt vmcnt(31)
	v_lshlrev_b32_e32 v52, 16, v46
	v_mul_f32_e32 v48, v48, v52
	v_mul_f32_e32 v52, v118, v90
	v_mul_f32_e32 v49, v49, v52
	v_and_b32_e32 v46, 0xffff0000, v46
	v_mul_f32_e32 v46, v49, v46
	v_cvt_pk_bf16_f32 v52, v48, v46
	v_mul_f32_e32 v46, v117, v90
	v_mul_f32_e32 v46, v50, v46
	v_lshlrev_b32_e32 v48, 16, v47
	v_mul_f32_e32 v46, v46, v48
	v_mul_f32_e32 v48, v116, v90
	v_mul_f32_e32 v48, v51, v48
	v_and_b32_e32 v47, 0xffff0000, v47
	v_mul_f32_e32 v47, v48, v47
	v_cvt_pk_bf16_f32 v53, v46, v47
	ds_read_b128 v[46:49], v98 offset:480
	v_mul_f32_e32 v50, v114, v90
	global_store_dwordx2 v[2:3], v[52:53], off offset:224
	s_waitcnt lgkmcnt(0)
	v_mul_f32_e32 v46, v46, v50
	s_waitcnt vmcnt(31)
	v_lshlrev_b32_e32 v50, 16, v44
	v_mul_f32_e32 v46, v46, v50
	v_mul_f32_e32 v50, v112, v90
	v_mul_f32_e32 v47, v47, v50
	v_and_b32_e32 v44, 0xffff0000, v44
	v_mul_f32_e32 v44, v47, v44
	v_cvt_pk_bf16_f32 v50, v46, v44
	v_mul_f32_e32 v44, v110, v90
	v_mul_f32_e32 v44, v48, v44
	v_lshlrev_b32_e32 v46, 16, v45
	v_mul_f32_e32 v44, v44, v46
	v_mul_f32_e32 v46, v108, v90
	v_mul_f32_e32 v46, v49, v46
	v_and_b32_e32 v45, 0xffff0000, v45
	v_mul_f32_e32 v45, v46, v45
	v_cvt_pk_bf16_f32 v51, v44, v45
	ds_read_b128 v[44:47], v98 offset:512
	v_mul_f32_e32 v48, v115, v90
	global_store_dwordx2 v[2:3], v[50:51], off offset:240
	s_waitcnt lgkmcnt(0)
	v_mul_f32_e32 v44, v44, v48
	s_waitcnt vmcnt(31)
	v_lshlrev_b32_e32 v48, 16, v42
	v_mul_f32_e32 v44, v44, v48
	v_mul_f32_e32 v48, v113, v90
	v_mul_f32_e32 v45, v45, v48
	v_and_b32_e32 v42, 0xffff0000, v42
	v_mul_f32_e32 v42, v45, v42
	v_cvt_pk_bf16_f32 v48, v44, v42
	v_mul_f32_e32 v42, v111, v90
	v_mul_f32_e32 v42, v46, v42
	v_lshlrev_b32_e32 v44, 16, v43
	v_mul_f32_e32 v42, v42, v44
	v_mul_f32_e32 v44, v109, v90
	v_mul_f32_e32 v44, v47, v44
	v_and_b32_e32 v43, 0xffff0000, v43
	v_mul_f32_e32 v43, v44, v43
	v_cvt_pk_bf16_f32 v49, v42, v43
	ds_read_b128 v[42:45], v98 offset:544
	v_mul_f32_e32 v46, v107, v90
	global_store_dwordx2 v[2:3], v[48:49], off offset:256
	s_waitcnt lgkmcnt(0)
	v_mul_f32_e32 v42, v42, v46
	s_waitcnt vmcnt(31)
	v_lshlrev_b32_e32 v46, 16, v40
	v_mul_f32_e32 v42, v42, v46
	v_mul_f32_e32 v46, v106, v90
	v_mul_f32_e32 v43, v43, v46
	v_and_b32_e32 v40, 0xffff0000, v40
	v_mul_f32_e32 v40, v43, v40
	v_cvt_pk_bf16_f32 v46, v42, v40
	v_mul_f32_e32 v40, v105, v90
	v_mul_f32_e32 v40, v44, v40
	v_lshlrev_b32_e32 v42, 16, v41
	v_mul_f32_e32 v40, v40, v42
	v_mul_f32_e32 v42, v104, v90
	v_mul_f32_e32 v42, v45, v42
	v_and_b32_e32 v41, 0xffff0000, v41
	v_mul_f32_e32 v41, v42, v41
	v_cvt_pk_bf16_f32 v47, v40, v41
	ds_read_b128 v[40:43], v98 offset:576
	v_mul_f32_e32 v44, v103, v90
	global_store_dwordx2 v[2:3], v[46:47], off offset:272
	s_waitcnt lgkmcnt(0)
	v_mul_f32_e32 v40, v40, v44
	s_waitcnt vmcnt(31)
	v_lshlrev_b32_e32 v44, 16, v38
	v_mul_f32_e32 v40, v40, v44
	v_mul_f32_e32 v44, v102, v90
	v_mul_f32_e32 v41, v41, v44
	v_and_b32_e32 v38, 0xffff0000, v38
	v_mul_f32_e32 v38, v41, v38
	v_cvt_pk_bf16_f32 v44, v40, v38
	v_mul_f32_e32 v38, v101, v90
	v_mul_f32_e32 v38, v42, v38
	v_lshlrev_b32_e32 v40, 16, v39
	v_mul_f32_e32 v38, v38, v40
	v_mul_f32_e32 v40, v100, v90
	v_mul_f32_e32 v40, v43, v40
	v_and_b32_e32 v39, 0xffff0000, v39
	v_mul_f32_e32 v39, v40, v39
	v_cvt_pk_bf16_f32 v45, v38, v39
	ds_read_b128 v[38:41], v98 offset:608
	v_mul_f32_e32 v42, v96, v90
	global_store_dwordx2 v[2:3], v[44:45], off offset:288
	s_waitcnt lgkmcnt(0)
	v_mul_f32_e32 v38, v38, v42
	s_waitcnt vmcnt(31)
	v_lshlrev_b32_e32 v42, 16, v36
	v_mul_f32_e32 v38, v38, v42
	v_mul_f32_e32 v42, v95, v90
	v_mul_f32_e32 v39, v39, v42
	v_and_b32_e32 v36, 0xffff0000, v36
	v_mul_f32_e32 v36, v39, v36
	v_cvt_pk_bf16_f32 v42, v38, v36
	v_mul_f32_e32 v36, v92, v90
	v_mul_f32_e32 v36, v40, v36
	v_lshlrev_b32_e32 v38, 16, v37
	v_mul_f32_e32 v36, v36, v38
	v_mul_f32_e32 v38, v91, v90
	v_mul_f32_e32 v38, v41, v38
	v_and_b32_e32 v37, 0xffff0000, v37
	v_mul_f32_e32 v37, v38, v37
	v_cvt_pk_bf16_f32 v43, v36, v37
	ds_read_b128 v[36:39], v98 offset:640
	v_mul_f32_e32 v40, v99, v90
	global_store_dwordx2 v[2:3], v[42:43], off offset:304
	s_waitcnt lgkmcnt(0)
	v_mul_f32_e32 v36, v36, v40
	s_waitcnt vmcnt(31)
	v_lshlrev_b32_e32 v40, 16, v34
	v_mul_f32_e32 v36, v36, v40
	v_mul_f32_e32 v40, v97, v90
	v_mul_f32_e32 v37, v37, v40
	v_and_b32_e32 v34, 0xffff0000, v34
	v_mul_f32_e32 v34, v37, v34
	v_cvt_pk_bf16_f32 v40, v36, v34
	v_mul_f32_e32 v34, v94, v90
	v_mul_f32_e32 v34, v38, v34
	v_lshlrev_b32_e32 v36, 16, v35
	v_mul_f32_e32 v34, v34, v36
	v_mul_f32_e32 v36, v93, v90
	v_mul_f32_e32 v36, v39, v36
	v_and_b32_e32 v35, 0xffff0000, v35
	v_mul_f32_e32 v35, v36, v35
	v_cvt_pk_bf16_f32 v41, v34, v35
	ds_read_b128 v[34:37], v98 offset:672
	v_mul_f32_e32 v38, v89, v90
	global_store_dwordx2 v[2:3], v[40:41], off offset:320
	s_waitcnt lgkmcnt(0)
	v_mul_f32_e32 v34, v34, v38
	s_waitcnt vmcnt(31)
	v_lshlrev_b32_e32 v38, 16, v32
	v_mul_f32_e32 v34, v34, v38
	v_mul_f32_e32 v38, v88, v90
	v_mul_f32_e32 v35, v35, v38
	v_and_b32_e32 v32, 0xffff0000, v32
	v_mul_f32_e32 v32, v35, v32
	v_cvt_pk_bf16_f32 v38, v34, v32
	v_mul_f32_e32 v32, v87, v90
	v_mul_f32_e32 v32, v36, v32
	v_lshlrev_b32_e32 v34, 16, v33
	v_mul_f32_e32 v32, v32, v34
	v_mul_f32_e32 v34, v86, v90
	v_mul_f32_e32 v34, v37, v34
	v_and_b32_e32 v33, 0xffff0000, v33
	v_mul_f32_e32 v33, v34, v33
	v_cvt_pk_bf16_f32 v39, v32, v33
	ds_read_b128 v[32:35], v98 offset:704
	v_mul_f32_e32 v36, v85, v90
	global_store_dwordx2 v[2:3], v[38:39], off offset:336
	s_waitcnt lgkmcnt(0)
	v_mul_f32_e32 v32, v32, v36
	s_waitcnt vmcnt(31)
	v_lshlrev_b32_e32 v36, 16, v30
	v_mul_f32_e32 v32, v32, v36
	v_mul_f32_e32 v36, v84, v90
	v_mul_f32_e32 v33, v33, v36
	v_and_b32_e32 v30, 0xffff0000, v30
	v_mul_f32_e32 v30, v33, v30
	v_cvt_pk_bf16_f32 v36, v32, v30
	v_mul_f32_e32 v30, v83, v90
	v_mul_f32_e32 v30, v34, v30
	v_lshlrev_b32_e32 v32, 16, v31
	v_mul_f32_e32 v30, v30, v32
	v_mul_f32_e32 v32, v82, v90
	v_mul_f32_e32 v32, v35, v32
	v_and_b32_e32 v31, 0xffff0000, v31
	v_mul_f32_e32 v31, v32, v31
	v_cvt_pk_bf16_f32 v37, v30, v31
	ds_read_b128 v[30:33], v98 offset:736
	v_mul_f32_e32 v34, v80, v90
	global_store_dwordx2 v[2:3], v[36:37], off offset:352
	s_waitcnt lgkmcnt(0)
	v_mul_f32_e32 v30, v30, v34
	s_waitcnt vmcnt(31)
	v_lshlrev_b32_e32 v34, 16, v28
	v_mul_f32_e32 v30, v30, v34
	v_mul_f32_e32 v34, v78, v90
	v_mul_f32_e32 v31, v31, v34
	v_and_b32_e32 v28, 0xffff0000, v28
	v_mul_f32_e32 v28, v31, v28
	v_cvt_pk_bf16_f32 v34, v30, v28
	v_mul_f32_e32 v28, v76, v90
	v_mul_f32_e32 v28, v32, v28
	v_lshlrev_b32_e32 v30, 16, v29
	v_mul_f32_e32 v28, v28, v30
	v_mul_f32_e32 v30, v74, v90
	v_mul_f32_e32 v30, v33, v30
	v_and_b32_e32 v29, 0xffff0000, v29
	v_mul_f32_e32 v29, v30, v29
	v_cvt_pk_bf16_f32 v35, v28, v29
	ds_read_b128 v[28:31], v98 offset:768
	v_mul_f32_e32 v32, v81, v90
	global_store_dwordx2 v[2:3], v[34:35], off offset:368
	s_waitcnt lgkmcnt(0)
	v_mul_f32_e32 v28, v32, v28
	s_waitcnt vmcnt(31)
	v_lshlrev_b32_e32 v32, 16, v26
	v_mul_f32_e32 v28, v28, v32
	v_mul_f32_e32 v32, v79, v90
	v_mul_f32_e32 v29, v32, v29
	v_and_b32_e32 v26, 0xffff0000, v26
	v_mul_f32_e32 v26, v29, v26
	v_cvt_pk_bf16_f32 v32, v28, v26
	v_mul_f32_e32 v26, v77, v90
	v_mul_f32_e32 v26, v26, v30
	v_lshlrev_b32_e32 v28, 16, v27
	v_mul_f32_e32 v26, v26, v28
	v_mul_f32_e32 v28, v75, v90
	v_mul_f32_e32 v28, v28, v31
	v_and_b32_e32 v27, 0xffff0000, v27
	v_mul_f32_e32 v27, v28, v27
	v_cvt_pk_bf16_f32 v33, v26, v27
	ds_read_b128 v[26:29], v98 offset:800
	v_mul_f32_e32 v30, v73, v90
	global_store_dwordx2 v[2:3], v[32:33], off offset:384
	s_waitcnt lgkmcnt(0)
	v_mul_f32_e32 v26, v30, v26
	s_waitcnt vmcnt(31)
	v_lshlrev_b32_e32 v30, 16, v24
	v_mul_f32_e32 v26, v26, v30
	v_mul_f32_e32 v30, v72, v90
	v_mul_f32_e32 v27, v30, v27
	v_and_b32_e32 v24, 0xffff0000, v24
	v_mul_f32_e32 v24, v27, v24
	v_cvt_pk_bf16_f32 v30, v26, v24
	v_mul_f32_e32 v24, v71, v90
	v_mul_f32_e32 v24, v24, v28
	v_lshlrev_b32_e32 v26, 16, v25
	v_mul_f32_e32 v24, v24, v26
	v_mul_f32_e32 v26, v70, v90
	v_mul_f32_e32 v26, v26, v29
	v_and_b32_e32 v25, 0xffff0000, v25
	v_mul_f32_e32 v25, v26, v25
	v_cvt_pk_bf16_f32 v31, v24, v25
	ds_read_b128 v[24:27], v98 offset:832
	v_mul_f32_e32 v28, v69, v90
	global_store_dwordx2 v[2:3], v[30:31], off offset:400
	s_waitcnt lgkmcnt(0)
	v_mul_f32_e32 v24, v28, v24
	s_waitcnt vmcnt(31)
	v_lshlrev_b32_e32 v28, 16, v22
	v_mul_f32_e32 v24, v24, v28
	v_mul_f32_e32 v28, v68, v90
	v_mul_f32_e32 v25, v28, v25
	v_and_b32_e32 v22, 0xffff0000, v22
	v_mul_f32_e32 v22, v25, v22
	v_cvt_pk_bf16_f32 v28, v24, v22
	v_mul_f32_e32 v22, v67, v90
	v_mul_f32_e32 v22, v22, v26
	v_lshlrev_b32_e32 v24, 16, v23
	v_mul_f32_e32 v22, v22, v24
	v_mul_f32_e32 v24, v66, v90
	v_mul_f32_e32 v24, v24, v27
	v_and_b32_e32 v23, 0xffff0000, v23
	v_mul_f32_e32 v23, v24, v23
	v_cvt_pk_bf16_f32 v29, v22, v23
	ds_read_b128 v[22:25], v98 offset:864
	v_mul_f32_e32 v26, v65, v90
	global_store_dwordx2 v[2:3], v[28:29], off offset:416
	s_waitcnt lgkmcnt(0)
	v_mul_f32_e32 v22, v26, v22
	s_waitcnt vmcnt(31)
	v_lshlrev_b32_e32 v26, 16, v20
	v_mul_f32_e32 v22, v22, v26
	v_mul_f32_e32 v26, v64, v90
	v_mul_f32_e32 v23, v26, v23
	v_and_b32_e32 v20, 0xffff0000, v20
	v_mul_f32_e32 v20, v23, v20
	v_cvt_pk_bf16_f32 v26, v22, v20
	v_mul_f32_e32 v20, v63, v90
	v_mul_f32_e32 v20, v20, v24
	v_lshlrev_b32_e32 v22, 16, v21
	v_mul_f32_e32 v20, v20, v22
	v_mul_f32_e32 v22, v62, v90
	v_mul_f32_e32 v22, v22, v25
	v_and_b32_e32 v21, 0xffff0000, v21
	v_mul_f32_e32 v21, v22, v21
	v_cvt_pk_bf16_f32 v27, v20, v21
	ds_read_b128 v[20:23], v98 offset:896
	v_mul_f32_e32 v24, v61, v90
	global_store_dwordx2 v[2:3], v[26:27], off offset:432
	s_waitcnt lgkmcnt(0)
	v_mul_f32_e32 v20, v24, v20
	s_waitcnt vmcnt(31)
	v_lshlrev_b32_e32 v24, 16, v18
	v_mul_f32_e32 v20, v20, v24
	v_mul_f32_e32 v24, v60, v90
	v_mul_f32_e32 v21, v24, v21
	v_and_b32_e32 v18, 0xffff0000, v18
	v_mul_f32_e32 v18, v21, v18
	v_cvt_pk_bf16_f32 v24, v20, v18
	v_mul_f32_e32 v18, v59, v90
	v_mul_f32_e32 v18, v18, v22
	v_lshlrev_b32_e32 v20, 16, v19
	v_mul_f32_e32 v18, v18, v20
	v_mul_f32_e32 v20, v58, v90
	v_mul_f32_e32 v20, v20, v23
	v_and_b32_e32 v19, 0xffff0000, v19
	v_mul_f32_e32 v19, v20, v19
	v_cvt_pk_bf16_f32 v25, v18, v19
	ds_read_b128 v[18:21], v98 offset:928
	v_mul_f32_e32 v22, v57, v90
	global_store_dwordx2 v[2:3], v[24:25], off offset:448
	s_waitcnt lgkmcnt(0)
	v_mul_f32_e32 v18, v22, v18
	s_waitcnt vmcnt(31)
	v_lshlrev_b32_e32 v22, 16, v14
	v_mul_f32_e32 v18, v18, v22
	v_mul_f32_e32 v22, v56, v90
	v_mul_f32_e32 v19, v22, v19
	v_and_b32_e32 v14, 0xffff0000, v14
	v_mul_f32_e32 v14, v19, v14
	v_cvt_pk_bf16_f32 v14, v18, v14
	v_mul_f32_e32 v0, v0, v20
	v_lshlrev_b32_e32 v18, 16, v15
	v_mul_f32_e32 v1, v1, v21
	v_and_b32_e32 v15, 0xffff0000, v15
	v_mul_f32_e32 v0, v0, v18
	v_mul_f32_e32 v1, v1, v15
	v_cvt_pk_bf16_f32 v15, v0, v1
	ds_read_b128 v[18:21], v98 offset:960
	v_mul_f32_e32 v0, v16, v90
	s_waitcnt vmcnt(30)
	v_lshlrev_b32_e32 v1, 16, v12
	v_and_b32_e32 v12, 0xffff0000, v12
	global_store_dwordx2 v[2:3], v[14:15], off offset:464
	s_waitcnt lgkmcnt(0)
	v_mul_f32_e32 v0, v0, v18
	v_mul_f32_e32 v0, v0, v1
	v_mul_f32_e32 v1, v17, v90
	v_mul_f32_e32 v1, v1, v19
	v_mul_f32_e32 v1, v1, v12
	v_cvt_pk_bf16_f32 v0, v0, v1
	v_mul_f32_e32 v1, v8, v90
	v_mul_f32_e32 v1, v1, v20
	v_lshlrev_b32_e32 v8, 16, v13
	v_mul_f32_e32 v1, v1, v8
	v_mul_f32_e32 v8, v9, v90
	v_mul_f32_e32 v8, v8, v21
	v_and_b32_e32 v9, 0xffff0000, v13
	v_mul_f32_e32 v8, v8, v9
	v_cvt_pk_bf16_f32 v1, v1, v8
	ds_read_b128 v[12:15], v98 offset:992
	global_store_dwordx2 v[2:3], v[0:1], off offset:480
	v_mul_f32_e32 v0, v6, v90
	s_waitcnt vmcnt(31)
	v_lshlrev_b32_e32 v1, 16, v10
	v_and_b32_e32 v6, 0xffff0000, v10
	s_waitcnt lgkmcnt(0)
	v_mul_f32_e32 v0, v0, v12
	v_mul_f32_e32 v0, v0, v1
	v_mul_f32_e32 v1, v7, v90
	v_mul_f32_e32 v1, v1, v13
	v_mul_f32_e32 v1, v1, v6
	v_cvt_pk_bf16_f32 v0, v0, v1
	v_mul_f32_e32 v1, v4, v90
	v_mul_f32_e32 v1, v1, v14
	v_lshlrev_b32_e32 v4, 16, v11
	v_mul_f32_e32 v1, v1, v4
	v_mul_f32_e32 v4, v5, v90
	v_mul_f32_e32 v4, v4, v15
	v_and_b32_e32 v5, 0xffff0000, v11
	v_mul_f32_e32 v4, v4, v5
	v_cvt_pk_bf16_f32 v1, v1, v4
	global_store_dwordx2 v[2:3], v[0:1], off offset:496
	v_mov_b32_e32 v4, v176
	v_mov_b32_e32 v181, v179
	v_bfe_u32 v0, v4, 4, 2
	v_or_b32_e32 v1, s83, v0
	v_bitop3_b32 v0, v0, v4, s83 bitop3:0x36
	v_lshlrev_b32_e32 v2, 14, v1
	v_lshlrev_b32_e32 v0, 4, v0
	v_and_or_b32 v178, v0, s67, v2
	v_or_b32_e32 v0, 4, v1
	v_bitop3_b32 v1, v1, v4, 4 bitop3:0x36
	v_lshlrev_b32_e32 v0, 14, v0
	v_lshlrev_b32_e32 v1, 4, v1
	v_and_or_b32 v180, v1, s67, v0
	v_bfe_u32 v0, v4, 5, 1
	v_or_b32_e32 v1, s83, v0
	v_and_b32_e32 v2, 31, v4
	v_lshlrev_b32_e32 v3, 14, v1
	v_lshlrev_b32_e32 v0, 6, v0
	v_lshlrev_b32_e32 v5, 4, v2
	v_bitop3_b32 v182, v0, v3, v5 bitop3:0xde
	v_or_b32_e32 v0, 2, v1
	v_lshlrev_b32_e32 v3, 2, v0
	v_bitop3_b32 v3, v3, v2, 12 bitop3:0x6c
	v_lshlrev_b32_e32 v0, 14, v0
	v_lshl_or_b32 v184, v3, 4, v0
	v_or_b32_e32 v0, 6, v1
	v_lshlrev_b32_e32 v1, 2, v0
	v_bitop3_b32 v1, v1, v2, 12 bitop3:0x6c
	v_lshlrev_b32_e32 v0, 14, v0
	v_lshl_or_b32 v188, v1, 4, v0
	v_lshl_add_u64 v[0:1], s[38:39], 0, v[178:179]
	s_mov_b32 s13, m0
	s_mov_b32 m0, s40
	s_nop 0
	global_load_lds_dwordx4 v[0:1], off
	s_mov_b32 m0, s13
	v_lshl_add_u64 v[0:1], s[38:39], 0, v[180:181]
	v_mov_b32_e32 v183, v179
	s_add_i32 s13, s40, 0x400
	s_mov_b32 s14, m0
	s_mov_b32 m0, s13
	s_nop 0
	global_load_lds_dwordx4 v[0:1], off
	s_mov_b32 m0, s14
	v_lshl_add_u64 v[0:1], s[16:17], 0, v[182:183]
	v_mov_b32_e32 v185, v179
	v_or_b32_e32 v186, 0x10000, v182
	s_mov_b32 s13, m0
	s_mov_b32 m0, s41
	s_nop 0
	global_load_lds_dwordx4 v[0:1], off
	s_mov_b32 m0, s13
	v_lshl_add_u64 v[0:1], s[16:17], 0, v[184:185]
	s_add_i32 s12, s12, s33
	v_mov_b32_e32 v187, v179
	s_add_i32 s13, s12, 0xc400
	s_mov_b32 s14, m0
	s_mov_b32 m0, s13
	s_nop 0
	global_load_lds_dwordx4 v[0:1], off
	s_mov_b32 m0, s14
	v_lshl_add_u64 v[0:1], s[16:17], 0, v[186:187]
	v_mov_b32_e32 v189, v179
	s_add_i32 s13, s12, 0xc800
	s_mov_b32 s14, m0
	s_mov_b32 m0, s13
	s_nop 0
	global_load_lds_dwordx4 v[0:1], off
	s_mov_b32 m0, s14
	v_lshl_add_u64 v[0:1], s[16:17], 0, v[188:189]
	s_add_i32 s13, s12, 0xcc00
	s_mov_b32 s14, m0
	s_mov_b32 m0, s13
	s_nop 0
	global_load_lds_dwordx4 v[0:1], off
	s_mov_b32 m0, s14
	v_lshl_add_u64 v[0:1], s[52:53], 0, v[178:179]
	s_add_i32 s13, s40, 0x4000
	s_mov_b32 s14, m0
	s_mov_b32 m0, s13
	s_nop 0
	global_load_lds_dwordx4 v[0:1], off
	s_mov_b32 m0, s14
	v_lshl_add_u64 v[0:1], s[52:53], 0, v[180:181]
	s_add_i32 s13, s40, 0x4400
	s_mov_b32 s14, m0
	s_mov_b32 m0, s13
	s_nop 0
	global_load_lds_dwordx4 v[0:1], off
	s_mov_b32 m0, s14
	v_lshl_add_u64 v[0:1], s[10:11], 0, v[182:183]
	s_add_i32 s13, s12, 0x14000
	s_mov_b32 s14, m0
	s_mov_b32 m0, s13
	s_nop 0
	global_load_lds_dwordx4 v[0:1], off
	s_mov_b32 m0, s14
	v_lshl_add_u64 v[0:1], s[10:11], 0, v[184:185]
	s_add_i32 s13, s12, 0x14400
	s_mov_b32 s14, m0
	s_mov_b32 m0, s13
	s_nop 0
	global_load_lds_dwordx4 v[0:1], off
	s_mov_b32 m0, s14
	v_lshl_add_u64 v[0:1], s[10:11], 0, v[186:187]
	s_add_i32 s13, s12, 0x14800
	s_mov_b32 s14, m0
	s_mov_b32 m0, s13
	s_nop 0
	global_load_lds_dwordx4 v[0:1], off
	s_mov_b32 m0, s14
	v_lshl_add_u64 v[0:1], s[10:11], 0, v[188:189]
	s_add_i32 s12, s12, 0x14c00
	s_mov_b32 s13, m0
	s_mov_b32 m0, s12
	s_nop 0
	global_load_lds_dwordx4 v[0:1], off
	s_mov_b32 m0, s13
	v_or_b32_e32 v0, s18, v2
	v_mov_b32_e32 v1, s19
	v_lshlrev_b64 v[0:1], 14, v[0:1]
	v_lshrrev_b32_e32 v2, 1, v4
	v_lshl_add_u64 v[0:1], s[8:9], 0, v[0:1]
	v_and_b32_e32 v2, 16, v2
	v_mov_b32_e32 v3, v179
	v_lshl_add_u64 v[0:1], v[0:1], 0, v[2:3]
	global_load_dwordx4 v[144:147], v[0:1], off
	global_load_dwordx4 v[148:151], v[0:1], off offset:32
	global_load_dwordx4 v[152:155], v[0:1], off offset:64
	global_load_dwordx4 v[156:159], v[0:1], off offset:96
	global_load_dwordx4 v[160:163], v[0:1], off offset:128
	global_load_dwordx4 v[164:167], v[0:1], off offset:160
	global_load_dwordx4 v[168:171], v[0:1], off offset:192
	global_load_dwordx4 v[172:175], v[0:1], off offset:224
	v_lshrrev_b32_e32 v0, 5, v4
	v_and_b32_e32 v1, 15, v4
	v_bitop3_b32 v0, v0, v1, 1 bitop3:0x6c
	v_lshlrev_b32_e32 v1, 8, v4
	v_lshlrev_b32_e32 v0, 4, v0
	v_and_b32_e32 v1, 0x1f00, v1
	v_mov_b32_e32 v14, v179
	v_mov_b32_e32 v15, v179
	v_or_b32_e32 v195, v0, v1
	v_bitop3_b32 v196, v0, 32, v1 bitop3:0x36
	v_bitop3_b32 v197, v0, 64, v1 bitop3:0x36
	v_bitop3_b32 v198, v0, s68, v1 bitop3:0x36
	v_bitop3_b32 v199, v0, s69, v1 bitop3:0x36
	v_bitop3_b32 v200, v0, s70, v1 bitop3:0x36
	v_bitop3_b32 v201, v0, s71, v1 bitop3:0x36
	v_bitop3_b32 v202, v0, s72, v1 bitop3:0x36
	v_mov_b32_e32 v0, v179
	v_mov_b32_e32 v1, v179
	v_mov_b32_e32 v2, v179
	v_mov_b32_e32 v4, v179
	v_mov_b32_e32 v5, v179
	v_mov_b32_e32 v6, v179
	v_mov_b32_e32 v7, v179
	v_mov_b32_e32 v8, v179
	s_waitcnt vmcnt(7)
	s_waitcnt vmcnt(6)
	s_waitcnt vmcnt(5)
	s_waitcnt vmcnt(4)
	s_waitcnt vmcnt(3)
	s_waitcnt vmcnt(2)
	s_waitcnt vmcnt(1)
	s_waitcnt vmcnt(0)
	s_waitcnt vmcnt(0)
	v_mov_b32_e32 v9, v179
	v_mov_b32_e32 v10, v179
	v_mov_b32_e32 v11, v179
	v_mov_b32_e32 v12, v179
	v_mov_b32_e32 v13, v179
	v_mov_b64_e32 v[30:31], v[14:15]
	v_mov_b64_e32 v[46:47], v[14:15]
	v_mov_b64_e32 v[62:63], v[14:15]
	v_mov_b64_e32 v[78:79], v[14:15]
	v_mov_b64_e32 v[94:95], v[14:15]
	v_mov_b64_e32 v[110:111], v[14:15]
	v_mov_b64_e32 v[126:127], v[14:15]
	v_mov_b32_e32 v190, 0xf149f2ca
	v_mov_b32_e32 v203, 0
	v_mov_b64_e32 v[28:29], v[12:13]
	v_mov_b64_e32 v[26:27], v[10:11]
	v_mov_b64_e32 v[24:25], v[8:9]
	v_mov_b64_e32 v[22:23], v[6:7]
	v_mov_b64_e32 v[20:21], v[4:5]
	v_mov_b64_e32 v[18:19], v[2:3]
	v_mov_b64_e32 v[16:17], v[0:1]
	v_mov_b64_e32 v[44:45], v[12:13]
	v_mov_b64_e32 v[42:43], v[10:11]
	v_mov_b64_e32 v[40:41], v[8:9]
	v_mov_b64_e32 v[38:39], v[6:7]
	v_mov_b64_e32 v[36:37], v[4:5]
	v_mov_b64_e32 v[34:35], v[2:3]
	v_mov_b64_e32 v[32:33], v[0:1]
	v_mov_b64_e32 v[60:61], v[12:13]
	v_mov_b64_e32 v[58:59], v[10:11]
	v_mov_b64_e32 v[56:57], v[8:9]
	v_mov_b64_e32 v[54:55], v[6:7]
	v_mov_b64_e32 v[52:53], v[4:5]
	v_mov_b64_e32 v[50:51], v[2:3]
	v_mov_b64_e32 v[48:49], v[0:1]
	v_mov_b64_e32 v[76:77], v[12:13]
	v_mov_b64_e32 v[74:75], v[10:11]
	v_mov_b64_e32 v[72:73], v[8:9]
	v_mov_b64_e32 v[70:71], v[6:7]
	v_mov_b64_e32 v[68:69], v[4:5]
	v_mov_b64_e32 v[66:67], v[2:3]
	v_mov_b64_e32 v[64:65], v[0:1]
	v_mov_b64_e32 v[92:93], v[12:13]
	v_mov_b64_e32 v[90:91], v[10:11]
	v_mov_b64_e32 v[88:89], v[8:9]
	v_mov_b64_e32 v[86:87], v[6:7]
	v_mov_b64_e32 v[84:85], v[4:5]
	v_mov_b64_e32 v[82:83], v[2:3]
	v_mov_b64_e32 v[80:81], v[0:1]
	v_mov_b64_e32 v[108:109], v[12:13]
	v_mov_b64_e32 v[106:107], v[10:11]
	v_mov_b64_e32 v[104:105], v[8:9]
	v_mov_b64_e32 v[102:103], v[6:7]
	v_mov_b64_e32 v[100:101], v[4:5]
	v_mov_b64_e32 v[98:99], v[2:3]
	v_mov_b64_e32 v[96:97], v[0:1]
	v_mov_b64_e32 v[124:125], v[12:13]
	v_mov_b64_e32 v[122:123], v[10:11]
	v_mov_b64_e32 v[120:121], v[8:9]
	v_mov_b64_e32 v[118:119], v[6:7]
	v_mov_b64_e32 v[116:117], v[4:5]
	v_mov_b64_e32 v[114:115], v[2:3]
	v_mov_b64_e32 v[112:113], v[0:1]
	s_mov_b32 s38, 0
	v_lshrrev_b32_e32 v246, 8, v220
	s_nop 0
	v_readfirstlane_b32 s100, v246
	s_nop 3
	s_cmp_lg_u32 s100, 0
	s_cbranch_scc0 .Latt_prio_2
	s_setprio 1

.LBB0_900:
	ds_bpermute_b32 v128, v194, v203
	s_add_i32 s12, s86, s60
	s_mov_b32 s13, s5
	s_lshl_b64 s[12:13], s[12:13], 14
	s_add_u32 s12, s58, s12
	s_waitcnt lgkmcnt(0)
	v_add_f32_e32 v128, v203, v128
	v_rcp_f32_e32 v130, v128
	v_mov_b32_e32 v128, v176
	s_addc_u32 s13, s59, s13
	v_lshlrev_b32_e32 v128, 4, v128
	v_mul_f32_e32 v112, v112, v130
	v_mul_f32_e32 v113, v113, v130
	v_mul_f32_e32 v114, v114, v130
	v_mul_f32_e32 v115, v115, v130
	v_and_b32_e32 v178, 0x3f0, v128
	v_mul_f32_e32 v116, v116, v130
	v_mul_f32_e32 v117, v117, v130
	v_mul_f32_e32 v118, v118, v130
	v_mul_f32_e32 v119, v119, v130
	v_cvt_pk_bf16_f32 v112, v112, v113
	v_cvt_pk_bf16_f32 v113, v114, v115
	v_cvt_pk_bf16_f32 v114, v116, v117
	v_cvt_pk_bf16_f32 v115, v118, v119
	v_mul_f32_e32 v96, v96, v130
	v_mul_f32_e32 v97, v97, v130
	v_mul_f32_e32 v98, v98, v130
	v_mul_f32_e32 v99, v99, v130
	v_lshl_add_u64 v[128:129], s[12:13], 0, v[178:179]
	v_mul_f32_e32 v120, v120, v130
	v_mul_f32_e32 v121, v121, v130
	v_mul_f32_e32 v122, v122, v130
	v_mul_f32_e32 v123, v123, v130
	v_mul_f32_e32 v124, v124, v130
	v_mul_f32_e32 v125, v125, v130
	v_mul_f32_e32 v126, v126, v130
	v_mul_f32_e32 v127, v127, v130
	v_cvt_pk_bf16_f32 v116, v120, v121
	v_cvt_pk_bf16_f32 v117, v122, v123
	v_cvt_pk_bf16_f32 v118, v124, v125
	v_cvt_pk_bf16_f32 v119, v126, v127
	global_store_dwordx4 v178, v[112:115], s[12:13]
	global_store_dwordx4 v178, v[116:119], s[12:13] offset:1024
	v_mul_f32_e32 v100, v100, v130
	v_mul_f32_e32 v101, v101, v130
	v_mul_f32_e32 v102, v102, v130
	v_mul_f32_e32 v103, v103, v130
	v_cvt_pk_bf16_f32 v96, v96, v97
	v_cvt_pk_bf16_f32 v97, v98, v99
	v_cvt_pk_bf16_f32 v98, v100, v101
	v_cvt_pk_bf16_f32 v99, v102, v103
	v_mul_f32_e32 v80, v80, v130
	v_mul_f32_e32 v81, v81, v130
	v_mul_f32_e32 v82, v82, v130
	v_mul_f32_e32 v83, v83, v130
	v_mul_f32_e32 v84, v84, v130
	v_mul_f32_e32 v88, v88, v130
	v_mul_f32_e32 v104, v104, v130
	v_mul_f32_e32 v105, v105, v130
	v_mul_f32_e32 v106, v106, v130
	v_mul_f32_e32 v107, v107, v130
	v_mul_f32_e32 v108, v108, v130
	v_mul_f32_e32 v109, v109, v130
	v_mul_f32_e32 v110, v110, v130
	v_mul_f32_e32 v111, v111, v130
	v_cvt_pk_bf16_f32 v100, v104, v105
	v_cvt_pk_bf16_f32 v101, v106, v107
	v_cvt_pk_bf16_f32 v102, v108, v109
	v_cvt_pk_bf16_f32 v103, v110, v111
	global_store_dwordx4 v178, v[96:99], s[12:13] offset:2048
	global_store_dwordx4 v178, v[100:103], s[12:13] offset:3072
	v_mul_f32_e32 v85, v85, v130
	v_mul_f32_e32 v86, v86, v130
	v_mul_f32_e32 v87, v87, v130
	v_mul_f32_e32 v89, v89, v130
	v_cvt_pk_bf16_f32 v80, v80, v81
	v_cvt_pk_bf16_f32 v81, v82, v83
	v_cvt_pk_bf16_f32 v82, v84, v85
	v_cvt_pk_bf16_f32 v83, v86, v87
	v_cvt_pk_bf16_f32 v84, v88, v89
	v_add_co_u32_e32 v88, vcc, s73, v128
	v_mul_f32_e32 v90, v90, v130
	s_nop 0
	v_addc_co_u32_e32 v89, vcc, 0, v129, vcc
	v_mul_f32_e32 v91, v91, v130
	v_cvt_pk_bf16_f32 v85, v90, v91
	v_add_co_u32_e32 v90, vcc, s74, v128
	v_mul_f32_e32 v64, v64, v130
	s_nop 0
	v_addc_co_u32_e32 v91, vcc, 0, v129, vcc
	v_mul_f32_e32 v65, v65, v130
	v_mul_f32_e32 v66, v66, v130
	v_mul_f32_e32 v67, v67, v130
	v_mul_f32_e32 v92, v92, v130
	v_mul_f32_e32 v93, v93, v130
	v_mul_f32_e32 v94, v94, v130
	v_mul_f32_e32 v95, v95, v130
	v_cvt_pk_bf16_f32 v86, v92, v93
	v_cvt_pk_bf16_f32 v87, v94, v95
	global_store_dwordx4 v[90:91], v[80:83], off offset:-4096
	global_store_dwordx4 v[88:89], v[84:87], off offset:1024
	v_mul_f32_e32 v68, v68, v130
	v_mul_f32_e32 v69, v69, v130
	v_mul_f32_e32 v70, v70, v130
	v_mul_f32_e32 v71, v71, v130
	v_cvt_pk_bf16_f32 v64, v64, v65
	v_cvt_pk_bf16_f32 v65, v66, v67
	v_cvt_pk_bf16_f32 v66, v68, v69
	v_cvt_pk_bf16_f32 v67, v70, v71
	v_mul_f32_e32 v48, v48, v130
	v_mul_f32_e32 v49, v49, v130
	v_mul_f32_e32 v50, v50, v130
	v_mul_f32_e32 v51, v51, v130
	v_mul_f32_e32 v72, v72, v130
	v_mul_f32_e32 v73, v73, v130
	v_mul_f32_e32 v74, v74, v130
	v_mul_f32_e32 v75, v75, v130
	v_mul_f32_e32 v76, v76, v130
	v_mul_f32_e32 v77, v77, v130
	v_mul_f32_e32 v78, v78, v130
	v_mul_f32_e32 v79, v79, v130
	v_cvt_pk_bf16_f32 v68, v72, v73
	v_cvt_pk_bf16_f32 v69, v74, v75
	v_cvt_pk_bf16_f32 v70, v76, v77
	v_cvt_pk_bf16_f32 v71, v78, v79
	global_store_dwordx4 v[88:89], v[64:67], off offset:2048
	global_store_dwordx4 v[88:89], v[68:71], off offset:3072
	v_mul_f32_e32 v52, v52, v130
	v_mul_f32_e32 v53, v53, v130
	v_mul_f32_e32 v54, v54, v130
	v_mul_f32_e32 v55, v55, v130
	v_cvt_pk_bf16_f32 v48, v48, v49
	v_cvt_pk_bf16_f32 v49, v50, v51
	v_cvt_pk_bf16_f32 v50, v52, v53
	v_cvt_pk_bf16_f32 v51, v54, v55
	v_mul_f32_e32 v32, v32, v130
	v_mul_f32_e32 v33, v33, v130
	v_mul_f32_e32 v34, v34, v130
	v_mul_f32_e32 v35, v35, v130
	v_mul_f32_e32 v56, v56, v130
	v_mul_f32_e32 v57, v57, v130
	v_mul_f32_e32 v58, v58, v130
	v_mul_f32_e32 v59, v59, v130
	v_mul_f32_e32 v60, v60, v130
	v_mul_f32_e32 v61, v61, v130
	v_mul_f32_e32 v62, v62, v130
	v_mul_f32_e32 v63, v63, v130
	v_cvt_pk_bf16_f32 v52, v56, v57
	v_cvt_pk_bf16_f32 v53, v58, v59
	v_cvt_pk_bf16_f32 v54, v60, v61
	v_cvt_pk_bf16_f32 v55, v62, v63
	global_store_dwordx4 v[90:91], v[48:51], off
	global_store_dwordx4 v[90:91], v[52:55], off offset:1024
	v_mul_f32_e32 v36, v36, v130
	v_mul_f32_e32 v37, v37, v130
	v_mul_f32_e32 v38, v38, v130
	v_mul_f32_e32 v39, v39, v130
	v_cvt_pk_bf16_f32 v32, v32, v33
	v_cvt_pk_bf16_f32 v33, v34, v35
	v_cvt_pk_bf16_f32 v34, v36, v37
	v_cvt_pk_bf16_f32 v35, v38, v39
	v_mul_f32_e32 v16, v16, v130
	v_mul_f32_e32 v17, v17, v130
	v_mul_f32_e32 v18, v18, v130
	v_mul_f32_e32 v19, v19, v130
	v_mul_f32_e32 v20, v20, v130
	v_mul_f32_e32 v24, v24, v130
	v_mul_f32_e32 v40, v40, v130
	v_mul_f32_e32 v41, v41, v130
	v_mul_f32_e32 v42, v42, v130
	v_mul_f32_e32 v43, v43, v130
	v_mul_f32_e32 v44, v44, v130
	v_mul_f32_e32 v45, v45, v130
	v_mul_f32_e32 v46, v46, v130
	v_mul_f32_e32 v47, v47, v130
	v_cvt_pk_bf16_f32 v36, v40, v41
	v_cvt_pk_bf16_f32 v37, v42, v43
	v_cvt_pk_bf16_f32 v38, v44, v45
	v_cvt_pk_bf16_f32 v39, v46, v47
	global_store_dwordx4 v[90:91], v[32:35], off offset:2048
	global_store_dwordx4 v[90:91], v[36:39], off offset:3072
	v_mul_f32_e32 v21, v21, v130
	v_mul_f32_e32 v22, v22, v130
	v_mul_f32_e32 v23, v23, v130
	v_mul_f32_e32 v25, v25, v130
	v_cvt_pk_bf16_f32 v16, v16, v17
	v_cvt_pk_bf16_f32 v17, v18, v19
	v_cvt_pk_bf16_f32 v18, v20, v21
	v_cvt_pk_bf16_f32 v19, v22, v23
	v_cvt_pk_bf16_f32 v20, v24, v25
	v_add_co_u32_e32 v24, vcc, s75, v128
	v_mul_f32_e32 v0, v0, v130
	s_nop 0
	v_addc_co_u32_e32 v25, vcc, 0, v129, vcc
	v_mul_f32_e32 v1, v1, v130
	v_mul_f32_e32 v2, v2, v130
	v_mul_f32_e32 v3, v3, v130
	s_mov_b32 s14, 0
	v_mul_f32_e32 v26, v26, v130
	v_mul_f32_e32 v27, v27, v130
	v_mul_f32_e32 v28, v28, v130
	v_mul_f32_e32 v29, v29, v130
	v_mul_f32_e32 v30, v30, v130
	v_mul_f32_e32 v31, v31, v130
	v_cvt_pk_bf16_f32 v21, v26, v27
	v_cvt_pk_bf16_f32 v22, v28, v29
	v_cvt_pk_bf16_f32 v23, v30, v31
	global_store_dwordx4 v[24:25], v[16:19], off
	global_store_dwordx4 v[24:25], v[20:23], off offset:1024
	v_mul_f32_e32 v4, v4, v130
	v_mul_f32_e32 v5, v5, v130
	v_mul_f32_e32 v6, v6, v130
	v_mul_f32_e32 v7, v7, v130
	v_mul_f32_e32 v8, v8, v130
	v_mul_f32_e32 v9, v9, v130
	v_mul_f32_e32 v10, v10, v130
	v_mul_f32_e32 v11, v11, v130
	v_mul_f32_e32 v12, v12, v130
	v_mul_f32_e32 v13, v13, v130
	v_mul_f32_e32 v14, v14, v130
	v_mul_f32_e32 v15, v15, v130
	v_cvt_pk_bf16_f32 v0, v0, v1
	v_cvt_pk_bf16_f32 v1, v2, v3
	v_cvt_pk_bf16_f32 v2, v4, v5
	v_cvt_pk_bf16_f32 v3, v6, v7
	v_cvt_pk_bf16_f32 v4, v8, v9
	v_cvt_pk_bf16_f32 v5, v10, v11
	v_cvt_pk_bf16_f32 v6, v12, v13
	v_cvt_pk_bf16_f32 v7, v14, v15
	global_store_dwordx4 v[24:25], v[0:3], off offset:2048
	global_store_dwordx4 v[24:25], v[4:7], off offset:3072
	s_nop 1
	v_mov_b32_e32 v4, v176
	s_cmp_lg_u32 0, -1
	v_bfe_u32 v0, v4, 4, 2
	v_or_b32_e32 v1, s83, v0
	v_bitop3_b32 v0, v0, v4, s83 bitop3:0x36
	v_lshlrev_b32_e32 v2, 14, v1
	v_lshlrev_b32_e32 v0, 4, v0
	v_and_or_b32 v178, v0, s67, v2
	v_or_b32_e32 v0, 4, v1
	v_bitop3_b32 v1, v1, v4, 4 bitop3:0x36
	v_lshlrev_b32_e32 v0, 14, v0
	v_lshlrev_b32_e32 v1, 4, v1
	v_and_or_b32 v180, v1, s67, v0
	v_bfe_u32 v0, v4, 5, 1
	v_or_b32_e32 v1, s83, v0
	v_and_b32_e32 v2, 31, v4
	v_lshlrev_b32_e32 v3, 14, v1
	v_lshlrev_b32_e32 v0, 6, v0
	v_lshlrev_b32_e32 v5, 4, v2
	v_bitop3_b32 v182, v0, v3, v5 bitop3:0xde
	v_or_b32_e32 v0, 2, v1
	v_lshlrev_b32_e32 v3, 2, v0
	v_bitop3_b32 v3, v3, v2, 12 bitop3:0x6c
	v_lshlrev_b32_e32 v0, 14, v0
	v_lshl_or_b32 v184, v3, 4, v0
	v_or_b32_e32 v0, 6, v1
	v_lshlrev_b32_e32 v1, 2, v0
	v_bitop3_b32 v1, v1, v2, 12 bitop3:0x6c
	v_lshlrev_b32_e32 v0, 14, v0
	v_lshl_or_b32 v188, v1, 4, v0
	v_lshl_add_u64 v[0:1], s[42:43], 0, v[178:179]
	s_cselect_b32 s15, 0, 0
	v_mov_b32_e32 v181, v179
	s_add_i32 s22, s82, s15
	s_mov_b32 s23, m0
	s_mov_b32 m0, s22
	s_nop 0
	global_load_lds_dwordx4 v[0:1], off
	s_mov_b32 m0, s23
	v_lshl_add_u64 v[0:1], s[42:43], 0, v[180:181]
	v_mov_b32_e32 v183, v179
	s_add_i32 s23, s22, 0x400
	s_mov_b32 s38, m0
	s_mov_b32 m0, s23
	s_nop 0
	global_load_lds_dwordx4 v[0:1], off
	s_mov_b32 m0, s38
	v_lshl_add_u64 v[0:1], s[16:17], 0, v[182:183]
	s_add_i32 s15, s15, s33
	v_mov_b32_e32 v185, v179
	v_or_b32_e32 v186, 0x10000, v182
	s_add_i32 s23, s15, 0xc000
	s_mov_b32 s33, m0
	s_mov_b32 m0, s23
	s_nop 0
	global_load_lds_dwordx4 v[0:1], off
	s_mov_b32 m0, s33
	v_lshl_add_u64 v[0:1], s[16:17], 0, v[184:185]
	v_mov_b32_e32 v187, v179
	s_add_i32 s23, s15, 0xc400
	s_mov_b32 s33, m0
	s_mov_b32 m0, s23
	s_nop 0
	global_load_lds_dwordx4 v[0:1], off
	s_mov_b32 m0, s33
	v_lshl_add_u64 v[0:1], s[16:17], 0, v[186:187]
	v_mov_b32_e32 v189, v179
	s_add_i32 s23, s15, 0xc800
	s_mov_b32 s33, m0
	s_mov_b32 m0, s23
	s_nop 0
	global_load_lds_dwordx4 v[0:1], off
	s_mov_b32 m0, s33
	v_lshl_add_u64 v[0:1], s[16:17], 0, v[188:189]
	s_add_i32 s16, s15, 0xcc00
	s_mov_b32 s17, m0
	s_mov_b32 m0, s16
	s_nop 0
	global_load_lds_dwordx4 v[0:1], off
	s_mov_b32 m0, s17
	v_lshl_add_u64 v[0:1], s[54:55], 0, v[178:179]
	s_add_i32 s16, s22, 0x4000
	s_mov_b32 s17, m0
	s_mov_b32 m0, s16
	s_nop 0
	global_load_lds_dwordx4 v[0:1], off
	s_mov_b32 m0, s17
	v_lshl_add_u64 v[0:1], s[54:55], 0, v[180:181]
	s_addk_i32 s22, 0x4400
	s_mov_b32 s16, m0
	s_mov_b32 m0, s22
	s_nop 0
	global_load_lds_dwordx4 v[0:1], off
	s_mov_b32 m0, s16
	v_lshl_add_u64 v[0:1], s[10:11], 0, v[182:183]
	s_add_i32 s16, s15, 0x14000
	s_mov_b32 s17, m0
	s_mov_b32 m0, s16
	s_nop 0
	global_load_lds_dwordx4 v[0:1], off
	s_mov_b32 m0, s17
	v_lshl_add_u64 v[0:1], s[10:11], 0, v[184:185]
	s_add_i32 s16, s15, 0x14400
	s_mov_b32 s17, m0
	s_mov_b32 m0, s16
	s_nop 0
	global_load_lds_dwordx4 v[0:1], off
	s_mov_b32 m0, s17
	v_lshl_add_u64 v[0:1], s[10:11], 0, v[186:187]
	s_add_i32 s16, s15, 0x14800
	s_mov_b32 s17, m0
	s_mov_b32 m0, s16
	s_nop 0
	global_load_lds_dwordx4 v[0:1], off
	s_mov_b32 m0, s17
	v_lshl_add_u64 v[0:1], s[10:11], 0, v[188:189]
	s_add_i32 s15, s15, 0x14c00
	s_mov_b32 s10, m0
	s_mov_b32 m0, s15
	s_nop 0
	global_load_lds_dwordx4 v[0:1], off
	s_mov_b32 m0, s10
	v_or_b32_e32 v0, s18, v2
	v_mov_b32_e32 v1, s19
	v_lshlrev_b64 v[0:1], 14, v[0:1]
	v_lshrrev_b32_e32 v2, 1, v4
	v_lshl_add_u64 v[0:1], s[8:9], 0, v[0:1]
	v_and_b32_e32 v2, 16, v2
	v_mov_b32_e32 v3, v179
	v_lshl_add_u64 v[0:1], v[0:1], 0, v[2:3]
	global_load_dwordx4 v[144:147], v[0:1], off offset:256
	global_load_dwordx4 v[148:151], v[0:1], off offset:288
	global_load_dwordx4 v[152:155], v[0:1], off offset:320
	global_load_dwordx4 v[156:159], v[0:1], off offset:352
	global_load_dwordx4 v[160:163], v[0:1], off offset:384
	global_load_dwordx4 v[164:167], v[0:1], off offset:416
	global_load_dwordx4 v[168:171], v[0:1], off offset:448
	global_load_dwordx4 v[172:175], v[0:1], off offset:480
	v_lshrrev_b32_e32 v0, 5, v4
	v_and_b32_e32 v1, 15, v4
	v_bitop3_b32 v0, v0, v1, 1 bitop3:0x6c
	v_lshlrev_b32_e32 v1, 8, v4
	v_lshlrev_b32_e32 v0, 4, v0
	v_and_b32_e32 v1, 0x1f00, v1
	v_mov_b32_e32 v14, v179
	v_mov_b32_e32 v15, v179
	v_or_b32_e32 v196, v0, v1
	v_bitop3_b32 v197, v0, 32, v1 bitop3:0x36
	v_bitop3_b32 v198, v0, 64, v1 bitop3:0x36
	v_bitop3_b32 v199, v0, s68, v1 bitop3:0x36
	v_bitop3_b32 v200, v0, s69, v1 bitop3:0x36
	v_bitop3_b32 v201, v0, s70, v1 bitop3:0x36
	v_bitop3_b32 v202, v0, s71, v1 bitop3:0x36
	v_bitop3_b32 v203, v0, s72, v1 bitop3:0x36
	v_mov_b32_e32 v0, v179
	v_mov_b32_e32 v1, v179
	v_mov_b32_e32 v2, v179
	v_mov_b32_e32 v4, v179
	s_waitcnt vmcnt(7)
	s_waitcnt vmcnt(6)
	s_waitcnt vmcnt(5)
	s_waitcnt vmcnt(4)
	s_waitcnt vmcnt(3)
	s_waitcnt vmcnt(2)
	s_waitcnt vmcnt(1)
	s_waitcnt vmcnt(0)
	s_waitcnt vmcnt(0)
	v_mov_b32_e32 v5, v179
	v_mov_b32_e32 v6, v179
	v_mov_b32_e32 v7, v179
	v_mov_b32_e32 v8, v179
	v_mov_b32_e32 v9, v179
	v_mov_b32_e32 v10, v179
	v_mov_b32_e32 v11, v179
	v_mov_b32_e32 v12, v179
	v_mov_b32_e32 v13, v179
	v_mov_b64_e32 v[30:31], v[14:15]
	v_mov_b64_e32 v[46:47], v[14:15]
	v_mov_b64_e32 v[62:63], v[14:15]
	v_mov_b64_e32 v[78:79], v[14:15]
	v_mov_b64_e32 v[94:95], v[14:15]
	v_mov_b64_e32 v[110:111], v[14:15]
	v_mov_b64_e32 v[126:127], v[14:15]
	s_mov_b32 s10, 2
	v_mov_b32_e32 v190, 0xf149f2ca
	v_mov_b32_e32 v195, 0
	v_mov_b64_e32 v[28:29], v[12:13]
	v_mov_b64_e32 v[26:27], v[10:11]
	v_mov_b64_e32 v[24:25], v[8:9]
	v_mov_b64_e32 v[22:23], v[6:7]
	v_mov_b64_e32 v[20:21], v[4:5]
	v_mov_b64_e32 v[18:19], v[2:3]
	v_mov_b64_e32 v[16:17], v[0:1]
	v_mov_b64_e32 v[44:45], v[12:13]
	v_mov_b64_e32 v[42:43], v[10:11]
	v_mov_b64_e32 v[40:41], v[8:9]
	v_mov_b64_e32 v[38:39], v[6:7]
	v_mov_b64_e32 v[36:37], v[4:5]
	v_mov_b64_e32 v[34:35], v[2:3]
	v_mov_b64_e32 v[32:33], v[0:1]
	v_mov_b64_e32 v[60:61], v[12:13]
	v_mov_b64_e32 v[58:59], v[10:11]
	v_mov_b64_e32 v[56:57], v[8:9]
	v_mov_b64_e32 v[54:55], v[6:7]
	v_mov_b64_e32 v[52:53], v[4:5]
	v_mov_b64_e32 v[50:51], v[2:3]
	v_mov_b64_e32 v[48:49], v[0:1]
	v_mov_b64_e32 v[76:77], v[12:13]
	v_mov_b64_e32 v[74:75], v[10:11]
	v_mov_b64_e32 v[72:73], v[8:9]
	v_mov_b64_e32 v[70:71], v[6:7]
	v_mov_b64_e32 v[68:69], v[4:5]
	v_mov_b64_e32 v[66:67], v[2:3]
	v_mov_b64_e32 v[64:65], v[0:1]
	v_mov_b64_e32 v[92:93], v[12:13]
	v_mov_b64_e32 v[90:91], v[10:11]
	v_mov_b64_e32 v[88:89], v[8:9]
	v_mov_b64_e32 v[86:87], v[6:7]
	v_mov_b64_e32 v[84:85], v[4:5]
	v_mov_b64_e32 v[82:83], v[2:3]
	v_mov_b64_e32 v[80:81], v[0:1]
	v_mov_b64_e32 v[108:109], v[12:13]
	v_mov_b64_e32 v[106:107], v[10:11]
	v_mov_b64_e32 v[104:105], v[8:9]
	v_mov_b64_e32 v[102:103], v[6:7]
	v_mov_b64_e32 v[100:101], v[4:5]
	v_mov_b64_e32 v[98:99], v[2:3]
	v_mov_b64_e32 v[96:97], v[0:1]
	v_mov_b64_e32 v[124:125], v[12:13]
	v_mov_b64_e32 v[122:123], v[10:11]
	v_mov_b64_e32 v[120:121], v[8:9]
	v_mov_b64_e32 v[118:119], v[6:7]
	v_mov_b64_e32 v[116:117], v[4:5]
	v_mov_b64_e32 v[114:115], v[2:3]
	v_mov_b64_e32 v[112:113], v[0:1]
	s_mov_b32 s11, 0
	v_lshrrev_b32_e32 v246, 8, v220
	s_nop 0
	v_readfirstlane_b32 s100, v246
	s_nop 3
	s_cmp_lg_u32 s100, 0
	s_cbranch_scc0 .Latt_prio_3
	s_setprio 1

.LBB0_1797:
	s_lshl_b32 s4, s49, 1
	s_and_b32 s14, s4, 0xe00
	s_and_b32 s66, s53, 7
	v_readfirstlane_b32 s4, v176
	s_xor_b32 s9, s66, 15
	s_ashr_i32 s4, s4, 6
	s_ashr_i32 s8, s53, 6
	s_lshl_b32 s75, s9, 8
	s_lshl_b32 s15, s4, 5
	s_lshl_b32 s70, s9, 2
	s_add_i32 s71, s15, s75
	s_ashr_i32 s9, s8, 31
	s_add_i32 s70, s70, 4
	s_or_b32 s72, s71, 31
	s_lshl_b64 s[36:37], s[8:9], 12
	s_lshl_b64 s[12:13], s[8:9], 26
	s_add_u32 s8, s2, s12
	s_addc_u32 s9, s3, s13
	s_lshl_b32 s10, s53, 5
	s_and_b32 s67, s10, 0x700
	s_lshl_b32 s10, s67, 1
	s_add_u32 s18, s8, s10
	s_addc_u32 s19, s9, 0
	s_add_u32 s34, s18, 0x1000
	s_addc_u32 s35, s19, 0
	s_add_u32 s16, s18, 0x2000
	s_addc_u32 s17, s19, 0
	s_add_u32 s8, s2, s10
	s_addc_u32 s9, s3, 0
	s_lshl_b32 s43, s4, 3
	s_lshl_b32 s42, s4, 11
	s_lshl_b32 s33, s4, 12
	s_add_u32 s10, s18, 0x102000
	s_addc_u32 s11, s19, 0
	s_or_b32 s20, s36, s75
	s_ashr_i32 s21, s15, 31
	s_add_u32 s68, s20, s15
	s_addc_u32 s69, s37, s21
	s_cmp_lg_u32 0, -1
	s_cselect_b32 s15, 0, 0
	s_add_i32 s20, s15, 0xc000
	s_add_i32 s73, s42, s15
	s_add_i32 s74, s33, s20
	v_mov_b32_e32 v4, v176
	v_mov_b32_e32 v181, v179
	v_bfe_u32 v0, v4, 4, 2
	v_or_b32_e32 v1, s43, v0
	v_bitop3_b32 v0, v0, v4, s43 bitop3:0x36
	v_lshlrev_b32_e32 v2, 14, v1
	v_lshlrev_b32_e32 v0, 4, v0
	v_and_or_b32 v178, v0, s55, v2
	v_or_b32_e32 v0, 4, v1
	v_bitop3_b32 v1, v1, v4, 4 bitop3:0x36
	v_lshlrev_b32_e32 v0, 14, v0
	v_lshlrev_b32_e32 v1, 4, v1
	v_and_or_b32 v180, v1, s55, v0
	v_bfe_u32 v0, v4, 5, 1
	v_or_b32_e32 v1, s43, v0
	v_and_b32_e32 v2, 31, v4
	v_lshlrev_b32_e32 v3, 14, v1
	v_lshlrev_b32_e32 v0, 6, v0
	v_lshlrev_b32_e32 v5, 4, v2
	v_bitop3_b32 v182, v0, v3, v5 bitop3:0xde
	v_or_b32_e32 v0, 2, v1
	v_lshlrev_b32_e32 v3, 2, v0
	v_bitop3_b32 v3, v3, v2, 12 bitop3:0x6c
	v_lshlrev_b32_e32 v0, 14, v0
	v_lshl_or_b32 v184, v3, 4, v0
	v_or_b32_e32 v0, 6, v1
	v_lshlrev_b32_e32 v1, 2, v0
	v_bitop3_b32 v1, v1, v2, 12 bitop3:0x6c
	v_lshlrev_b32_e32 v0, 14, v0
	v_lshl_or_b32 v188, v1, 4, v0
	v_lshl_add_u64 v[0:1], s[34:35], 0, v[178:179]
	s_mov_b32 s20, m0
	s_mov_b32 m0, s73
	s_nop 0
	global_load_lds_dwordx4 v[0:1], off
	s_mov_b32 m0, s20
	v_lshl_add_u64 v[0:1], s[34:35], 0, v[180:181]
	s_add_i32 s20, s73, 0x400
	s_mov_b32 s21, m0
	s_mov_b32 m0, s20
	s_nop 0
	global_load_lds_dwordx4 v[0:1], off
	s_mov_b32 m0, s21
	v_mov_b32_e32 v183, v179
	v_lshl_add_u64 v[0:1], s[16:17], 0, v[182:183]
	s_mov_b32 s20, m0
	s_mov_b32 m0, s74
	s_nop 0
	global_load_lds_dwordx4 v[0:1], off
	s_mov_b32 m0, s20
	s_add_i32 s15, s15, s33
	v_mov_b32_e32 v185, v179
	s_add_i32 s20, s15, 0xc400
	v_or_b32_e32 v186, 0x10000, v182
	v_lshl_add_u64 v[0:1], s[16:17], 0, v[184:185]
	s_mov_b32 s21, m0
	s_mov_b32 m0, s20
	s_nop 0
	global_load_lds_dwordx4 v[0:1], off
	s_mov_b32 m0, s21
	v_mov_b32_e32 v187, v179
	s_add_i32 s20, s15, 0xc800
	v_lshl_add_u64 v[0:1], s[16:17], 0, v[186:187]
	s_mov_b32 s21, m0
	s_mov_b32 m0, s20
	s_nop 0
	global_load_lds_dwordx4 v[0:1], off
	s_mov_b32 m0, s21
	s_add_i32 s20, s15, 0xcc00
	v_mov_b32_e32 v189, v179
	s_add_u32 s40, s18, 0x101000
	v_lshl_add_u64 v[0:1], s[16:17], 0, v[188:189]
	s_addc_u32 s41, s19, 0
	s_mov_b32 s21, m0
	s_mov_b32 m0, s20
	s_nop 0
	global_load_lds_dwordx4 v[0:1], off
	s_mov_b32 m0, s21
	v_lshl_add_u64 v[0:1], s[40:41], 0, v[178:179]
	s_add_i32 s18, s73, 0x4000
	s_mov_b32 s19, m0
	s_mov_b32 m0, s18
	s_nop 0
	global_load_lds_dwordx4 v[0:1], off
	s_mov_b32 m0, s19
	v_lshl_add_u64 v[0:1], s[40:41], 0, v[180:181]
	s_add_i32 s18, s73, 0x4400
	s_mov_b32 s19, m0
	s_mov_b32 m0, s18
	s_nop 0
	global_load_lds_dwordx4 v[0:1], off
	s_mov_b32 m0, s19
	v_lshl_add_u64 v[0:1], s[10:11], 0, v[182:183]
	s_add_i32 s18, s15, 0x14000
	s_mov_b32 s19, m0
	s_mov_b32 m0, s18
	s_nop 0
	global_load_lds_dwordx4 v[0:1], off
	s_mov_b32 m0, s19
	v_lshl_add_u64 v[0:1], s[10:11], 0, v[184:185]
	s_add_i32 s18, s15, 0x14400
	s_mov_b32 s19, m0
	s_mov_b32 m0, s18
	s_nop 0
	global_load_lds_dwordx4 v[0:1], off
	s_mov_b32 m0, s19
	v_lshl_add_u64 v[0:1], s[10:11], 0, v[186:187]
	s_add_i32 s18, s15, 0x14800
	s_mov_b32 s19, m0
	s_mov_b32 m0, s18
	s_nop 0
	global_load_lds_dwordx4 v[0:1], off
	s_mov_b32 m0, s19
	v_lshl_add_u64 v[0:1], s[10:11], 0, v[188:189]
	s_add_i32 s15, s15, 0x14c00
	s_mov_b32 s18, m0
	s_mov_b32 m0, s15
	s_nop 0
	global_load_lds_dwordx4 v[0:1], off
	s_mov_b32 m0, s18
	v_or_b32_e32 v0, s68, v2
	v_mov_b32_e32 v1, s69
	v_lshlrev_b64 v[0:1], 14, v[0:1]
	v_lshrrev_b32_e32 v2, 1, v4
	v_lshl_add_u64 v[0:1], s[8:9], 0, v[0:1]
	v_and_b32_e32 v2, 16, v2
	v_mov_b32_e32 v3, v179
	v_lshl_add_u64 v[0:1], v[0:1], 0, v[2:3]
	global_load_dwordx4 v[144:147], v[0:1], off
	global_load_dwordx4 v[148:151], v[0:1], off offset:32
	global_load_dwordx4 v[152:155], v[0:1], off offset:64
	global_load_dwordx4 v[156:159], v[0:1], off offset:96
	global_load_dwordx4 v[160:163], v[0:1], off offset:128
	global_load_dwordx4 v[164:167], v[0:1], off offset:160
	global_load_dwordx4 v[168:171], v[0:1], off offset:192
	global_load_dwordx4 v[172:175], v[0:1], off offset:224
	v_lshrrev_b32_e32 v0, 5, v4
	v_and_b32_e32 v1, 15, v4
	v_bitop3_b32 v0, v0, v1, 1 bitop3:0x6c
	v_lshlrev_b32_e32 v1, 8, v4
	s_addk_i32 s75, 0x100
	s_or_b32 s12, s12, s14
	v_lshlrev_b32_e32 v0, 4, v0
	v_and_b32_e32 v1, 0x1f00, v1
	s_add_u32 s20, s47, s12
	v_mov_b32_e32 v14, v179
	v_mov_b32_e32 v15, v179
	v_or_b32_e32 v194, v0, v1
	v_bitop3_b32 v195, v0, 32, v1 bitop3:0x36
	v_bitop3_b32 v196, v0, 64, v1 bitop3:0x36
	v_bitop3_b32 v197, v0, s56, v1 bitop3:0x36
	v_bitop3_b32 v198, v0, s57, v1 bitop3:0x36
	v_bitop3_b32 v199, v0, s58, v1 bitop3:0x36
	v_bitop3_b32 v200, v0, s59, v1 bitop3:0x36
	v_bitop3_b32 v201, v0, s60, v1 bitop3:0x36
	s_addc_u32 s21, s48, s13
	v_mov_b32_e32 v0, v179
	v_mov_b32_e32 v1, v179
	v_mov_b32_e32 v2, v179
	v_mov_b32_e32 v4, v179
	s_waitcnt vmcnt(7)
	s_waitcnt vmcnt(6)
	s_waitcnt vmcnt(5)
	s_waitcnt vmcnt(4)
	s_waitcnt vmcnt(3)
	s_waitcnt vmcnt(2)
	s_waitcnt vmcnt(1)
	s_waitcnt vmcnt(0)
	s_waitcnt vmcnt(0)
	v_mov_b32_e32 v5, v179
	v_mov_b32_e32 v6, v179
	v_mov_b32_e32 v7, v179
	v_mov_b32_e32 v8, v179
	v_mov_b32_e32 v9, v179
	v_mov_b32_e32 v10, v179
	v_mov_b32_e32 v11, v179
	v_mov_b32_e32 v12, v179
	v_mov_b32_e32 v13, v179
	v_mov_b64_e32 v[30:31], v[14:15]
	v_mov_b64_e32 v[46:47], v[14:15]
	v_mov_b64_e32 v[62:63], v[14:15]
	v_mov_b64_e32 v[78:79], v[14:15]
	v_mov_b64_e32 v[94:95], v[14:15]
	v_mov_b64_e32 v[110:111], v[14:15]
	v_mov_b64_e32 v[126:127], v[14:15]
	v_mov_b32_e32 v190, 0xf149f2ca
	s_mov_b32 s38, 2
	s_mov_b64 s[14:15], s[20:21]
	s_mov_b32 s39, 0
	v_mov_b64_e32 v[28:29], v[12:13]
	v_mov_b64_e32 v[26:27], v[10:11]
	v_mov_b64_e32 v[24:25], v[8:9]
	v_mov_b64_e32 v[22:23], v[6:7]
	v_mov_b64_e32 v[20:21], v[4:5]
	v_mov_b64_e32 v[18:19], v[2:3]
	v_mov_b64_e32 v[16:17], v[0:1]
	v_mov_b64_e32 v[44:45], v[12:13]
	v_mov_b64_e32 v[42:43], v[10:11]
	v_mov_b64_e32 v[40:41], v[8:9]
	v_mov_b64_e32 v[38:39], v[6:7]
	v_mov_b64_e32 v[36:37], v[4:5]
	v_mov_b64_e32 v[34:35], v[2:3]
	v_mov_b64_e32 v[32:33], v[0:1]
	v_mov_b64_e32 v[60:61], v[12:13]
	v_mov_b64_e32 v[58:59], v[10:11]
	v_mov_b64_e32 v[56:57], v[8:9]
	v_mov_b64_e32 v[54:55], v[6:7]
	v_mov_b64_e32 v[52:53], v[4:5]
	v_mov_b64_e32 v[50:51], v[2:3]
	v_mov_b64_e32 v[48:49], v[0:1]
	v_mov_b64_e32 v[76:77], v[12:13]
	v_mov_b64_e32 v[74:75], v[10:11]
	v_mov_b64_e32 v[72:73], v[8:9]
	v_mov_b64_e32 v[70:71], v[6:7]
	v_mov_b64_e32 v[68:69], v[4:5]
	v_mov_b64_e32 v[66:67], v[2:3]
	v_mov_b64_e32 v[64:65], v[0:1]
	v_mov_b64_e32 v[92:93], v[12:13]
	v_mov_b64_e32 v[90:91], v[10:11]
	v_mov_b64_e32 v[88:89], v[8:9]
	v_mov_b64_e32 v[86:87], v[6:7]
	v_mov_b64_e32 v[84:85], v[4:5]
	v_mov_b64_e32 v[82:83], v[2:3]
	v_mov_b64_e32 v[80:81], v[0:1]
	v_mov_b64_e32 v[108:109], v[12:13]
	v_mov_b64_e32 v[106:107], v[10:11]
	v_mov_b64_e32 v[104:105], v[8:9]
	v_mov_b64_e32 v[102:103], v[6:7]
	v_mov_b64_e32 v[100:101], v[4:5]
	v_mov_b64_e32 v[98:99], v[2:3]
	v_mov_b64_e32 v[96:97], v[0:1]
	v_mov_b64_e32 v[124:125], v[12:13]
	v_mov_b64_e32 v[122:123], v[10:11]
	v_mov_b64_e32 v[120:121], v[8:9]
	v_mov_b64_e32 v[118:119], v[6:7]
	v_mov_b64_e32 v[116:117], v[4:5]
	v_mov_b64_e32 v[114:115], v[2:3]
	v_mov_b64_e32 v[112:113], v[0:1]
	v_mov_b32_e32 v202, v179
	s_mov_b32 s76, 0
	v_lshrrev_b32_e32 v246, 8, v220
	s_nop 0
	v_readfirstlane_b32 s100, v246
	s_nop 3
	s_cmp_lg_u32 s100, 0
	s_cbranch_scc0 .Latt_prio_4
	s_setprio 1

.LBB0_1816:
	v_and_b32_e32 v129, 64, v193
	v_xor_b32_e32 v128, 32, v193
	v_add_u32_e32 v129, 64, v129
	v_cmp_lt_i32_e32 vcc, v128, v129
	s_add_i32 s4, s4, s46
	s_lshl_b64 s[14:15], s[4:5], 14
	v_cndmask_b32_e32 v128, v193, v128, vcc
	v_lshlrev_b32_e32 v194, 2, v128
	ds_bpermute_b32 v128, v194, v202
	s_add_u32 s14, s44, s14
	s_addc_u32 s15, s45, s15
	s_mov_b32 s4, 0
	s_mov_b32 s76, 2
	s_waitcnt lgkmcnt(0)
	v_add_f32_e32 v128, v202, v128
	v_rcp_f32_e32 v130, v128
	v_mov_b32_e32 v128, v176
	v_mul_f32_e32 v112, v112, v130
	v_lshlrev_b32_e32 v128, 4, v128
	v_mul_f32_e32 v113, v113, v130
	v_mul_f32_e32 v114, v114, v130
	v_mul_f32_e32 v115, v115, v130
	v_and_b32_e32 v178, 0x3f0, v128
	v_mul_f32_e32 v116, v116, v130
	v_mul_f32_e32 v117, v117, v130
	v_mul_f32_e32 v118, v118, v130
	v_mul_f32_e32 v119, v119, v130
	v_cvt_pk_bf16_f32 v112, v112, v113
	v_cvt_pk_bf16_f32 v113, v114, v115
	v_cvt_pk_bf16_f32 v114, v116, v117
	v_cvt_pk_bf16_f32 v115, v118, v119
	v_mul_f32_e32 v96, v96, v130
	v_mul_f32_e32 v97, v97, v130
	v_mul_f32_e32 v98, v98, v130
	v_mul_f32_e32 v99, v99, v130
	v_lshl_add_u64 v[128:129], s[14:15], 0, v[178:179]
	v_mul_f32_e32 v120, v120, v130
	v_mul_f32_e32 v121, v121, v130
	v_mul_f32_e32 v122, v122, v130
	v_mul_f32_e32 v123, v123, v130
	v_mul_f32_e32 v124, v124, v130
	v_mul_f32_e32 v125, v125, v130
	v_mul_f32_e32 v126, v126, v130
	v_mul_f32_e32 v127, v127, v130
	v_cvt_pk_bf16_f32 v116, v120, v121
	v_cvt_pk_bf16_f32 v117, v122, v123
	v_cvt_pk_bf16_f32 v118, v124, v125
	v_cvt_pk_bf16_f32 v119, v126, v127
	global_store_dwordx4 v178, v[112:115], s[14:15]
	global_store_dwordx4 v178, v[116:119], s[14:15] offset:1024
	v_mul_f32_e32 v100, v100, v130
	v_mul_f32_e32 v101, v101, v130
	v_mul_f32_e32 v102, v102, v130
	v_mul_f32_e32 v103, v103, v130
	v_cvt_pk_bf16_f32 v96, v96, v97
	v_cvt_pk_bf16_f32 v97, v98, v99
	v_cvt_pk_bf16_f32 v98, v100, v101
	v_cvt_pk_bf16_f32 v99, v102, v103
	v_mul_f32_e32 v80, v80, v130
	v_mul_f32_e32 v81, v81, v130
	v_mul_f32_e32 v82, v82, v130
	v_mul_f32_e32 v83, v83, v130
	v_mul_f32_e32 v84, v84, v130
	v_mul_f32_e32 v88, v88, v130
	v_mul_f32_e32 v104, v104, v130
	v_mul_f32_e32 v105, v105, v130
	v_mul_f32_e32 v106, v106, v130
	v_mul_f32_e32 v107, v107, v130
	v_mul_f32_e32 v108, v108, v130
	v_mul_f32_e32 v109, v109, v130
	v_mul_f32_e32 v110, v110, v130
	v_mul_f32_e32 v111, v111, v130
	v_cvt_pk_bf16_f32 v100, v104, v105
	v_cvt_pk_bf16_f32 v101, v106, v107
	v_cvt_pk_bf16_f32 v102, v108, v109
	v_cvt_pk_bf16_f32 v103, v110, v111
	global_store_dwordx4 v178, v[96:99], s[14:15] offset:2048
	global_store_dwordx4 v178, v[100:103], s[14:15] offset:3072
	v_mul_f32_e32 v85, v85, v130
	v_mul_f32_e32 v86, v86, v130
	v_mul_f32_e32 v87, v87, v130
	v_mul_f32_e32 v89, v89, v130
	v_cvt_pk_bf16_f32 v80, v80, v81
	v_cvt_pk_bf16_f32 v81, v82, v83
	v_cvt_pk_bf16_f32 v82, v84, v85
	v_cvt_pk_bf16_f32 v83, v86, v87
	v_cvt_pk_bf16_f32 v84, v88, v89
	v_add_co_u32_e32 v88, vcc, s61, v128
	v_mul_f32_e32 v90, v90, v130
	s_nop 0
	v_addc_co_u32_e32 v89, vcc, 0, v129, vcc
	v_mul_f32_e32 v91, v91, v130
	v_cvt_pk_bf16_f32 v85, v90, v91
	v_add_co_u32_e32 v90, vcc, s62, v128
	v_mul_f32_e32 v64, v64, v130
	s_nop 0
	v_addc_co_u32_e32 v91, vcc, 0, v129, vcc
	v_mul_f32_e32 v65, v65, v130
	v_mul_f32_e32 v66, v66, v130
	v_mul_f32_e32 v67, v67, v130
	v_mul_f32_e32 v92, v92, v130
	v_mul_f32_e32 v93, v93, v130
	v_mul_f32_e32 v94, v94, v130
	v_mul_f32_e32 v95, v95, v130
	v_cvt_pk_bf16_f32 v86, v92, v93
	v_cvt_pk_bf16_f32 v87, v94, v95
	global_store_dwordx4 v[90:91], v[80:83], off offset:-4096
	global_store_dwordx4 v[88:89], v[84:87], off offset:1024
	v_mul_f32_e32 v68, v68, v130
	v_mul_f32_e32 v69, v69, v130
	v_mul_f32_e32 v70, v70, v130
	v_mul_f32_e32 v71, v71, v130
	v_cvt_pk_bf16_f32 v64, v64, v65
	v_cvt_pk_bf16_f32 v65, v66, v67
	v_cvt_pk_bf16_f32 v66, v68, v69
	v_cvt_pk_bf16_f32 v67, v70, v71
	v_mul_f32_e32 v48, v48, v130
	v_mul_f32_e32 v49, v49, v130
	v_mul_f32_e32 v50, v50, v130
	v_mul_f32_e32 v51, v51, v130
	v_mul_f32_e32 v72, v72, v130
	v_mul_f32_e32 v73, v73, v130
	v_mul_f32_e32 v74, v74, v130
	v_mul_f32_e32 v75, v75, v130
	v_mul_f32_e32 v76, v76, v130
	v_mul_f32_e32 v77, v77, v130
	v_mul_f32_e32 v78, v78, v130
	v_mul_f32_e32 v79, v79, v130
	v_cvt_pk_bf16_f32 v68, v72, v73
	v_cvt_pk_bf16_f32 v69, v74, v75
	v_cvt_pk_bf16_f32 v70, v76, v77
	v_cvt_pk_bf16_f32 v71, v78, v79
	global_store_dwordx4 v[88:89], v[64:67], off offset:2048
	global_store_dwordx4 v[88:89], v[68:71], off offset:3072
	v_mul_f32_e32 v52, v52, v130
	v_mul_f32_e32 v53, v53, v130
	v_mul_f32_e32 v54, v54, v130
	v_mul_f32_e32 v55, v55, v130
	v_cvt_pk_bf16_f32 v48, v48, v49
	v_cvt_pk_bf16_f32 v49, v50, v51
	v_cvt_pk_bf16_f32 v50, v52, v53
	v_cvt_pk_bf16_f32 v51, v54, v55
	v_mul_f32_e32 v32, v32, v130
	v_mul_f32_e32 v33, v33, v130
	v_mul_f32_e32 v34, v34, v130
	v_mul_f32_e32 v35, v35, v130
	v_mul_f32_e32 v56, v56, v130
	v_mul_f32_e32 v57, v57, v130
	v_mul_f32_e32 v58, v58, v130
	v_mul_f32_e32 v59, v59, v130
	v_mul_f32_e32 v60, v60, v130
	v_mul_f32_e32 v61, v61, v130
	v_mul_f32_e32 v62, v62, v130
	v_mul_f32_e32 v63, v63, v130
	v_cvt_pk_bf16_f32 v52, v56, v57
	v_cvt_pk_bf16_f32 v53, v58, v59
	v_cvt_pk_bf16_f32 v54, v60, v61
	v_cvt_pk_bf16_f32 v55, v62, v63
	global_store_dwordx4 v[90:91], v[48:51], off
	global_store_dwordx4 v[90:91], v[52:55], off offset:1024
	v_mul_f32_e32 v36, v36, v130
	v_mul_f32_e32 v37, v37, v130
	v_mul_f32_e32 v38, v38, v130
	v_mul_f32_e32 v39, v39, v130
	v_cvt_pk_bf16_f32 v32, v32, v33
	v_cvt_pk_bf16_f32 v33, v34, v35
	v_cvt_pk_bf16_f32 v34, v36, v37
	v_cvt_pk_bf16_f32 v35, v38, v39
	v_mul_f32_e32 v16, v16, v130
	v_mul_f32_e32 v17, v17, v130
	v_mul_f32_e32 v18, v18, v130
	v_mul_f32_e32 v19, v19, v130
	v_mul_f32_e32 v20, v20, v130
	v_mul_f32_e32 v24, v24, v130
	v_mul_f32_e32 v40, v40, v130
	v_mul_f32_e32 v41, v41, v130
	v_mul_f32_e32 v42, v42, v130
	v_mul_f32_e32 v43, v43, v130
	v_mul_f32_e32 v44, v44, v130
	v_mul_f32_e32 v45, v45, v130
	v_mul_f32_e32 v46, v46, v130
	v_mul_f32_e32 v47, v47, v130
	v_cvt_pk_bf16_f32 v36, v40, v41
	v_cvt_pk_bf16_f32 v37, v42, v43
	v_cvt_pk_bf16_f32 v38, v44, v45
	v_cvt_pk_bf16_f32 v39, v46, v47
	global_store_dwordx4 v[90:91], v[32:35], off offset:2048
	global_store_dwordx4 v[90:91], v[36:39], off offset:3072
	v_mul_f32_e32 v21, v21, v130
	v_mul_f32_e32 v22, v22, v130
	v_mul_f32_e32 v23, v23, v130
	v_mul_f32_e32 v25, v25, v130
	v_cvt_pk_bf16_f32 v16, v16, v17
	v_cvt_pk_bf16_f32 v17, v18, v19
	v_cvt_pk_bf16_f32 v18, v20, v21
	v_cvt_pk_bf16_f32 v19, v22, v23
	v_cvt_pk_bf16_f32 v20, v24, v25
	v_add_co_u32_e32 v24, vcc, s63, v128
	v_mul_f32_e32 v0, v0, v130
	s_nop 0
	v_addc_co_u32_e32 v25, vcc, 0, v129, vcc
	v_mul_f32_e32 v1, v1, v130
	v_mul_f32_e32 v2, v2, v130
	v_mul_f32_e32 v3, v3, v130
	v_mul_f32_e32 v26, v26, v130
	v_mul_f32_e32 v27, v27, v130
	v_mul_f32_e32 v28, v28, v130
	v_mul_f32_e32 v29, v29, v130
	v_mul_f32_e32 v30, v30, v130
	v_mul_f32_e32 v31, v31, v130
	v_cvt_pk_bf16_f32 v21, v26, v27
	v_cvt_pk_bf16_f32 v22, v28, v29
	v_cvt_pk_bf16_f32 v23, v30, v31
	global_store_dwordx4 v[24:25], v[16:19], off
	global_store_dwordx4 v[24:25], v[20:23], off offset:1024
	v_mul_f32_e32 v4, v4, v130
	v_mul_f32_e32 v5, v5, v130
	v_mul_f32_e32 v6, v6, v130
	v_mul_f32_e32 v7, v7, v130
	v_mul_f32_e32 v8, v8, v130
	v_mul_f32_e32 v9, v9, v130
	v_mul_f32_e32 v10, v10, v130
	v_mul_f32_e32 v11, v11, v130
	v_mul_f32_e32 v12, v12, v130
	v_mul_f32_e32 v13, v13, v130
	v_mul_f32_e32 v14, v14, v130
	v_mul_f32_e32 v15, v15, v130
	v_cvt_pk_bf16_f32 v0, v0, v1
	v_cvt_pk_bf16_f32 v1, v2, v3
	v_cvt_pk_bf16_f32 v2, v4, v5
	v_cvt_pk_bf16_f32 v3, v6, v7
	v_cvt_pk_bf16_f32 v4, v8, v9
	v_cvt_pk_bf16_f32 v5, v10, v11
	v_cvt_pk_bf16_f32 v6, v12, v13
	v_cvt_pk_bf16_f32 v7, v14, v15
	global_store_dwordx4 v[24:25], v[0:3], off offset:2048
	global_store_dwordx4 v[24:25], v[4:7], off offset:3072
	s_nop 1
	v_mov_b32_e32 v4, v176
	s_add_u32 s38, s34, 0x100
	v_bfe_u32 v0, v4, 4, 2
	v_or_b32_e32 v1, s43, v0
	v_bitop3_b32 v0, v0, v4, s43 bitop3:0x36
	v_lshlrev_b32_e32 v2, 14, v1
	v_lshlrev_b32_e32 v0, 4, v0
	v_and_or_b32 v178, v0, s55, v2
	v_or_b32_e32 v0, 4, v1
	v_bitop3_b32 v1, v1, v4, 4 bitop3:0x36
	v_lshlrev_b32_e32 v0, 14, v0
	v_lshlrev_b32_e32 v1, 4, v1
	v_and_or_b32 v180, v1, s55, v0
	v_bfe_u32 v0, v4, 5, 1
	v_or_b32_e32 v1, s43, v0
	v_and_b32_e32 v2, 31, v4
	v_lshlrev_b32_e32 v3, 14, v1
	v_lshlrev_b32_e32 v0, 6, v0
	v_lshlrev_b32_e32 v5, 4, v2
	v_bitop3_b32 v182, v0, v3, v5 bitop3:0xde
	v_or_b32_e32 v0, 2, v1
	v_lshlrev_b32_e32 v3, 2, v0
	v_bitop3_b32 v3, v3, v2, 12 bitop3:0x6c
	v_lshlrev_b32_e32 v0, 14, v0
	s_addc_u32 s39, s35, 0
	v_lshl_or_b32 v184, v3, 4, v0
	v_or_b32_e32 v0, 6, v1
	v_lshlrev_b32_e32 v1, 2, v0
	s_cmp_lg_u32 0, -1
	v_bitop3_b32 v1, v1, v2, 12 bitop3:0x6c
	v_lshlrev_b32_e32 v0, 14, v0
	s_cselect_b32 s18, 0, 0
	v_lshl_or_b32 v188, v1, 4, v0
	v_lshl_add_u64 v[0:1], s[38:39], 0, v[178:179]
	s_add_i32 s19, s42, s18
	s_mov_b32 s22, m0
	s_mov_b32 m0, s19
	s_nop 0
	global_load_lds_dwordx4 v[0:1], off
	s_mov_b32 m0, s22
	v_mov_b32_e32 v181, v179
	s_add_i32 s22, s19, 0x400
	s_add_i32 s18, s18, s33
	v_lshl_add_u64 v[0:1], s[38:39], 0, v[180:181]
	s_mov_b32 s23, m0
	s_mov_b32 m0, s22
	s_nop 0
	global_load_lds_dwordx4 v[0:1], off
	s_mov_b32 m0, s23
	v_mov_b32_e32 v183, v179
	s_add_i32 s22, s18, 0xc000
	v_lshl_add_u64 v[0:1], s[16:17], 0, v[182:183]
	s_mov_b32 s23, m0
	s_mov_b32 m0, s22
	s_nop 0
	global_load_lds_dwordx4 v[0:1], off
	s_mov_b32 m0, s23
	v_mov_b32_e32 v185, v179
	s_add_i32 s22, s18, 0xc400
	v_or_b32_e32 v186, 0x10000, v182
	v_lshl_add_u64 v[0:1], s[16:17], 0, v[184:185]
	s_mov_b32 s23, m0
	s_mov_b32 m0, s22
	s_nop 0
	global_load_lds_dwordx4 v[0:1], off
	s_mov_b32 m0, s23
	v_mov_b32_e32 v187, v179
	s_add_i32 s22, s18, 0xc800
	v_lshl_add_u64 v[0:1], s[16:17], 0, v[186:187]
	s_mov_b32 s23, m0
	s_mov_b32 m0, s22
	s_nop 0
	global_load_lds_dwordx4 v[0:1], off
	s_mov_b32 m0, s23
	s_add_i32 s22, s18, 0xcc00
	v_mov_b32_e32 v189, v179
	s_add_u32 s42, s34, 0x100100
	v_lshl_add_u64 v[0:1], s[16:17], 0, v[188:189]
	s_addc_u32 s43, s35, 0
	s_mov_b32 s23, m0
	s_mov_b32 m0, s22
	s_nop 0
	global_load_lds_dwordx4 v[0:1], off
	s_mov_b32 m0, s23
	v_lshl_add_u64 v[0:1], s[42:43], 0, v[178:179]
	s_add_i32 s22, s19, 0x4000
	s_mov_b32 s23, m0
	s_mov_b32 m0, s22
	s_nop 0
	global_load_lds_dwordx4 v[0:1], off
	s_mov_b32 m0, s23
	v_lshl_add_u64 v[0:1], s[42:43], 0, v[180:181]
	s_addk_i32 s19, 0x4400
	s_mov_b32 s22, m0
	s_mov_b32 m0, s19
	s_nop 0
	global_load_lds_dwordx4 v[0:1], off
	s_mov_b32 m0, s22
	v_lshl_add_u64 v[0:1], s[10:11], 0, v[182:183]
	s_add_i32 s19, s18, 0x14000
	s_mov_b32 s22, m0
	s_mov_b32 m0, s19
	s_nop 0
	global_load_lds_dwordx4 v[0:1], off
	s_mov_b32 m0, s22
	v_lshl_add_u64 v[0:1], s[10:11], 0, v[184:185]
	s_add_i32 s19, s18, 0x14400
	s_mov_b32 s22, m0
	s_mov_b32 m0, s19
	s_nop 0
	global_load_lds_dwordx4 v[0:1], off
	s_mov_b32 m0, s22
	v_lshl_add_u64 v[0:1], s[10:11], 0, v[186:187]
	s_add_i32 s19, s18, 0x14800
	s_mov_b32 s22, m0
	s_mov_b32 m0, s19
	s_nop 0
	global_load_lds_dwordx4 v[0:1], off
	s_mov_b32 m0, s22
	v_lshl_add_u64 v[0:1], s[10:11], 0, v[188:189]
	s_add_i32 s18, s18, 0x14c00
	s_mov_b32 s19, m0
	s_mov_b32 m0, s18
	s_nop 0
	global_load_lds_dwordx4 v[0:1], off
	s_mov_b32 m0, s19
	v_or_b32_e32 v0, s68, v2
	v_mov_b32_e32 v1, s69
	v_lshlrev_b64 v[0:1], 14, v[0:1]
	v_lshrrev_b32_e32 v2, 1, v4
	v_lshl_add_u64 v[0:1], s[8:9], 0, v[0:1]
	v_and_b32_e32 v2, 16, v2
	v_mov_b32_e32 v3, v179
	v_lshl_add_u64 v[0:1], v[0:1], 0, v[2:3]
	global_load_dwordx4 v[144:147], v[0:1], off offset:256
	global_load_dwordx4 v[148:151], v[0:1], off offset:288
	global_load_dwordx4 v[152:155], v[0:1], off offset:320
	global_load_dwordx4 v[156:159], v[0:1], off offset:352
	global_load_dwordx4 v[160:163], v[0:1], off offset:384
	global_load_dwordx4 v[164:167], v[0:1], off offset:416
	global_load_dwordx4 v[168:171], v[0:1], off offset:448
	global_load_dwordx4 v[172:175], v[0:1], off offset:480
	v_lshrrev_b32_e32 v0, 5, v4
	v_and_b32_e32 v1, 15, v4
	v_bitop3_b32 v0, v0, v1, 1 bitop3:0x6c
	v_lshlrev_b32_e32 v1, 8, v4
	v_lshlrev_b32_e32 v0, 4, v0
	v_and_b32_e32 v1, 0x1f00, v1
	s_add_u32 s22, s51, s12
	v_mov_b32_e32 v14, v179
	v_mov_b32_e32 v15, v179
	v_or_b32_e32 v196, v0, v1
	v_bitop3_b32 v197, v0, 32, v1 bitop3:0x36
	v_bitop3_b32 v198, v0, 64, v1 bitop3:0x36
	v_bitop3_b32 v199, v0, s56, v1 bitop3:0x36
	v_bitop3_b32 v200, v0, s57, v1 bitop3:0x36
	v_bitop3_b32 v201, v0, s58, v1 bitop3:0x36
	v_bitop3_b32 v202, v0, s59, v1 bitop3:0x36
	v_bitop3_b32 v203, v0, s60, v1 bitop3:0x36
	s_addc_u32 s23, s54, s13
	s_waitcnt vmcnt(7)
	s_waitcnt vmcnt(6)
	s_waitcnt vmcnt(5)
	s_waitcnt vmcnt(4)
	s_waitcnt vmcnt(3)
	s_waitcnt vmcnt(2)
	s_waitcnt vmcnt(1)
	s_waitcnt vmcnt(0)
	s_waitcnt vmcnt(0)
	v_mov_b32_e32 v0, v179
	v_mov_b32_e32 v1, v179
	v_mov_b32_e32 v2, v179
	v_mov_b32_e32 v4, v179
	v_mov_b32_e32 v5, v179
	v_mov_b32_e32 v6, v179
	v_mov_b32_e32 v7, v179
	v_mov_b32_e32 v8, v179
	v_mov_b32_e32 v9, v179
	v_mov_b32_e32 v10, v179
	v_mov_b32_e32 v11, v179
	v_mov_b32_e32 v12, v179
	v_mov_b32_e32 v13, v179
	v_mov_b64_e32 v[30:31], v[14:15]
	v_mov_b64_e32 v[46:47], v[14:15]
	v_mov_b64_e32 v[62:63], v[14:15]
	v_mov_b64_e32 v[78:79], v[14:15]
	v_mov_b64_e32 v[94:95], v[14:15]
	v_mov_b64_e32 v[110:111], v[14:15]
	v_mov_b64_e32 v[126:127], v[14:15]
	v_mov_b32_e32 v190, 0xf149f2ca
	v_mov_b32_e32 v195, 0
	s_mov_b64 s[12:13], s[22:23]
	v_mov_b64_e32 v[28:29], v[12:13]
	v_mov_b64_e32 v[26:27], v[10:11]
	v_mov_b64_e32 v[24:25], v[8:9]
	v_mov_b64_e32 v[22:23], v[6:7]
	v_mov_b64_e32 v[20:21], v[4:5]
	v_mov_b64_e32 v[18:19], v[2:3]
	v_mov_b64_e32 v[16:17], v[0:1]
	v_mov_b64_e32 v[44:45], v[12:13]
	v_mov_b64_e32 v[42:43], v[10:11]
	v_mov_b64_e32 v[40:41], v[8:9]
	v_mov_b64_e32 v[38:39], v[6:7]
	v_mov_b64_e32 v[36:37], v[4:5]
	v_mov_b64_e32 v[34:35], v[2:3]
	v_mov_b64_e32 v[32:33], v[0:1]
	v_mov_b64_e32 v[60:61], v[12:13]
	v_mov_b64_e32 v[58:59], v[10:11]
	v_mov_b64_e32 v[56:57], v[8:9]
	v_mov_b64_e32 v[54:55], v[6:7]
	v_mov_b64_e32 v[52:53], v[4:5]
	v_mov_b64_e32 v[50:51], v[2:3]
	v_mov_b64_e32 v[48:49], v[0:1]
	v_mov_b64_e32 v[76:77], v[12:13]
	v_mov_b64_e32 v[74:75], v[10:11]
	v_mov_b64_e32 v[72:73], v[8:9]
	v_mov_b64_e32 v[70:71], v[6:7]
	v_mov_b64_e32 v[68:69], v[4:5]
	v_mov_b64_e32 v[66:67], v[2:3]
	v_mov_b64_e32 v[64:65], v[0:1]
	v_mov_b64_e32 v[92:93], v[12:13]
	v_mov_b64_e32 v[90:91], v[10:11]
	v_mov_b64_e32 v[88:89], v[8:9]
	v_mov_b64_e32 v[86:87], v[6:7]
	v_mov_b64_e32 v[84:85], v[4:5]
	v_mov_b64_e32 v[82:83], v[2:3]
	v_mov_b64_e32 v[80:81], v[0:1]
	v_mov_b64_e32 v[108:109], v[12:13]
	v_mov_b64_e32 v[106:107], v[10:11]
	v_mov_b64_e32 v[104:105], v[8:9]
	v_mov_b64_e32 v[102:103], v[6:7]
	v_mov_b64_e32 v[100:101], v[4:5]
	v_mov_b64_e32 v[98:99], v[2:3]
	v_mov_b64_e32 v[96:97], v[0:1]
	v_mov_b64_e32 v[124:125], v[12:13]
	v_mov_b64_e32 v[122:123], v[10:11]
	v_mov_b64_e32 v[120:121], v[8:9]
	v_mov_b64_e32 v[118:119], v[6:7]
	v_mov_b64_e32 v[116:117], v[4:5]
	v_mov_b64_e32 v[114:115], v[2:3]
	v_mov_b64_e32 v[112:113], v[0:1]
	s_mov_b32 s33, 0
	v_lshrrev_b32_e32 v246, 8, v220
	s_nop 0
	v_readfirstlane_b32 s100, v246
	s_nop 3
	s_cmp_lg_u32 s100, 0
	s_cbranch_scc0 .Latt_prio_5
	s_setprio 1

.LBB0_1835:
	ds_bpermute_b32 v138, v194, v195
	v_mov_b32_e32 v153, v176
	v_mov_b32_e32 v149, s69
	v_lshlrev_b32_e32 v128, 4, v153
	v_and_b32_e32 v178, 0x3f0, v128
	v_lshl_add_u64 v[136:137], s[14:15], 0, v[178:179]
	s_waitcnt lgkmcnt(0)
	v_add_f32_e32 v152, v195, v138
	v_add_co_u32_e32 v138, vcc, s61, v136
	global_load_dwordx4 v[132:135], v178, s[14:15]
	global_load_dwordx4 v[128:131], v178, s[14:15] offset:1024
	global_load_dwordx4 v[144:147], v178, s[14:15] offset:2048
	global_load_dwordx4 v[140:143], v178, s[14:15] offset:3072
	v_addc_co_u32_e32 v139, vcc, 0, v137, vcc
	v_add_co_u32_e32 v150, vcc, s62, v136
	v_rcp_f32_e32 v152, v152
	s_nop 0
	v_addc_co_u32_e32 v151, vcc, 0, v137, vcc
	v_add_co_u32_e32 v154, vcc, s63, v136
	v_mul_f32_e32 v152, v177, v152
	s_nop 0
	v_addc_co_u32_e32 v155, vcc, 0, v137, vcc
	global_load_dwordx4 v[196:199], v[150:151], off offset:-4096
	global_load_dwordx4 v[200:203], v[138:139], off offset:1024
	global_load_dwordx4 v[204:207], v[138:139], off offset:2048
	global_load_dwordx4 v[208:211], v[138:139], off offset:3072
	s_nop 0
	global_load_dwordx4 v[136:139], v[154:155], off offset:3072
	v_and_or_b32 v148, v153, 31, s68
	s_lshl_b32 s4, s67, 1
	s_and_b32 s12, s65, 7
	s_lshl_b32 s67, s12, 8
	v_readfirstlane_b32 s12, v176
	s_ashr_i32 s74, s12, 6
	s_lshl_b32 s12, s66, 8
	s_lshl_b32 s13, s74, 5
	s_lshl_b32 s66, s66, 2
	s_add_i32 s68, s13, s12
	s_addk_i32 s67, 0x100
	s_add_i32 s66, s66, 4
	s_or_b32 s69, s68, 31
	s_lshl_b32 s71, s74, 3
	s_lshl_b32 s70, s74, 11
	s_lshl_b32 s33, s74, 12
	s_or_b32 s12, s36, s12
	s_ashr_i32 s14, s13, 31
	s_add_u32 s18, s12, s13
	s_addc_u32 s19, s37, s14
	s_cmp_lg_u32 0, -1
	s_cselect_b32 s12, 0, 0
	s_add_i32 s13, s12, 0xc000
	s_mov_b32 s72, 0
	s_mov_b32 s73, 2
	s_add_i32 s36, s70, s12
	s_add_i32 s37, s33, s13
	s_waitcnt vmcnt(8)
	v_lshlrev_b32_e32 v157, 16, v133
	v_lshlrev_b32_e32 v159, 16, v135
	s_waitcnt vmcnt(6)
	v_lshlrev_b32_e32 v164, 16, v144
	v_and_b32_e32 v144, 0xffff0000, v144
	v_lshlrev_b32_e32 v165, 16, v145
	v_lshlrev_b32_e32 v162, 16, v130
	v_and_b32_e32 v145, 0xffff0000, v145
	v_lshlrev_b32_e32 v168, 16, v146
	v_lshlrev_b32_e32 v169, 16, v147
	v_and_b32_e32 v147, 0xffff0000, v147
	v_fma_f32 v171, -v96, v152, v164
	v_fma_f32 v170, -v97, v152, v144
	v_fma_f32 v167, -v98, v152, v165
	s_waitcnt vmcnt(4)
	v_lshlrev_b32_e32 v96, 16, v196
	v_and_b32_e32 v97, 0xffff0000, v196
	v_lshlrev_b32_e32 v98, 16, v197
	v_fma_f32 v212, -v114, v152, v157
	v_fma_f32 v185, -v118, v152, v159
	v_fma_f32 v175, -v124, v152, v162
	v_fma_f32 v166, -v99, v152, v145
	v_fma_f32 v162, -v100, v152, v168
	v_fma_f32 v168, -v103, v152, v147
	v_fma_f32 v159, -v80, v152, v96
	v_fma_f32 v157, -v81, v152, v97
	v_fma_f32 v147, -v82, v152, v98
	global_load_dwordx4 v[96:99], v[150:151], off
	v_lshlrev_b32_e32 v160, 16, v128
	v_and_b32_e32 v146, 0xffff0000, v146
	v_lshlrev_b32_e32 v156, 16, v132
	v_lshlrev_b32_e32 v178, 16, v140
	v_lshlrev_b32_e32 v188, 16, v142
	v_and_b32_e32 v142, 0xffff0000, v142
	v_lshlrev_b32_e32 v189, 16, v143
	v_and_b32_e32 v143, 0xffff0000, v143
	v_fma_f32 v183, -v120, v152, v160
	v_fma_f32 v160, -v101, v152, v146
	v_fma_f32 v169, -v102, v152, v169
	v_lshlrev_b32_e32 v101, 16, v198
	v_and_b32_e32 v102, 0xffff0000, v198
	v_lshlrev_b32_e32 v161, 16, v129
	v_and_b32_e32 v130, 0xffff0000, v130
	v_lshlrev_b32_e32 v163, 16, v131
	v_and_b32_e32 v131, 0xffff0000, v131
	v_and_b32_e32 v140, 0xffff0000, v140
	v_lshlrev_b32_e32 v187, 16, v141
	v_and_b32_e32 v141, 0xffff0000, v141
	v_fma_f32 v190, -v112, v152, v156
	v_fma_f32 v165, -v104, v152, v178
	v_fma_f32 v156, -v109, v152, v142
	v_fma_f32 v144, -v111, v152, v143
	v_lshlrev_b32_e32 v103, 16, v199
	v_and_b32_e32 v104, 0xffff0000, v199
	v_fma_f32 v143, -v84, v152, v101
	v_fma_f32 v142, -v85, v152, v102
	s_waitcnt vmcnt(3)
	v_lshlrev_b32_e32 v84, 16, v204
	v_and_b32_e32 v85, 0xffff0000, v204
	v_fma_f32 v181, -v122, v152, v161
	v_fma_f32 v174, -v125, v152, v130
	v_fma_f32 v172, -v127, v152, v131
	v_fma_f32 v164, -v105, v152, v140
	v_fma_f32 v161, -v107, v152, v141
	v_fma_f32 v141, -v86, v152, v103
	v_fma_f32 v140, -v87, v152, v104
	v_fma_f32 v131, -v64, v152, v84
	v_fma_f32 v130, -v65, v152, v85
	global_load_dwordx4 v[84:87], v[150:151], off offset:2048
	v_and_b32_e32 v100, 0xffff0000, v197
	v_fma_f32 v146, -v83, v152, v100
	global_load_dwordx4 v[80:83], v[150:151], off offset:1024
	v_and_b32_e32 v132, 0xffff0000, v132
	v_fma_f32 v195, -v113, v152, v132
	v_mul_f32_e32 v215, v195, v195
	v_and_b32_e32 v133, 0xffff0000, v133
	v_fmac_f32_e32 v215, v190, v190
	v_lshlrev_b32_e32 v158, 16, v134
	v_fma_f32 v213, -v115, v152, v133
	v_fmac_f32_e32 v215, v212, v212
	v_and_b32_e32 v134, 0xffff0000, v134
	v_fma_f32 v214, -v116, v152, v158
	v_fmac_f32_e32 v215, v213, v213
	v_and_b32_e32 v135, 0xffff0000, v135
	v_fma_f32 v186, -v117, v152, v134
	v_fma_f32 v173, -v126, v152, v163
	v_fmac_f32_e32 v215, v214, v214
	v_fma_f32 v163, -v106, v152, v187
	v_lshlrev_b32_e32 v105, 16, v200
	v_and_b32_e32 v106, 0xffff0000, v200
	v_and_b32_e32 v128, 0xffff0000, v128
	v_fma_f32 v184, -v119, v152, v135
	v_fmac_f32_e32 v215, v186, v186
	v_fma_f32 v135, -v88, v152, v105
	v_fma_f32 v134, -v89, v152, v106
	v_lshlrev_b32_e32 v88, 16, v205
	v_and_b32_e32 v89, 0xffff0000, v205
	v_fma_f32 v182, -v121, v152, v128
	v_fmac_f32_e32 v215, v185, v185
	v_fma_f32 v128, -v66, v152, v88
	v_fma_f32 v126, -v67, v152, v89
	global_load_dwordx4 v[64:67], v[150:151], off offset:3072
	v_fmac_f32_e32 v215, v184, v184
	v_fmac_f32_e32 v215, v183, v183
	v_and_b32_e32 v129, 0xffff0000, v129
	v_fmac_f32_e32 v215, v182, v182
	v_fma_f32 v180, -v123, v152, v129
	v_fmac_f32_e32 v215, v181, v181
	v_fmac_f32_e32 v215, v180, v180
	v_fmac_f32_e32 v215, v175, v175
	v_fmac_f32_e32 v215, v174, v174
	v_fmac_f32_e32 v215, v173, v173
	global_load_dwordx4 v[196:199], v[154:155], off
	v_fmac_f32_e32 v215, v172, v172
	v_fmac_f32_e32 v215, v171, v171
	v_fmac_f32_e32 v215, v170, v170
	v_fmac_f32_e32 v215, v167, v167
	v_fmac_f32_e32 v215, v166, v166
	v_fma_f32 v158, -v108, v152, v188
	v_fma_f32 v145, -v110, v152, v189
	v_lshlrev_b32_e32 v107, 16, v201
	v_and_b32_e32 v108, 0xffff0000, v201
	v_lshlrev_b32_e32 v109, 16, v202
	v_and_b32_e32 v110, 0xffff0000, v202
	v_fmac_f32_e32 v215, v162, v162
	v_fma_f32 v133, -v90, v152, v107
	v_fma_f32 v132, -v91, v152, v108
	v_fma_f32 v129, -v92, v152, v109
	v_fma_f32 v127, -v93, v152, v110
	v_lshlrev_b32_e32 v90, 16, v206
	v_and_b32_e32 v91, 0xffff0000, v206
	v_lshlrev_b32_e32 v92, 16, v207
	v_and_b32_e32 v93, 0xffff0000, v207
	v_fmac_f32_e32 v215, v160, v160
	v_lshlrev_b32_e32 v111, 16, v203
	v_fma_f32 v123, -v68, v152, v90
	v_fma_f32 v122, -v69, v152, v91
	v_fma_f32 v121, -v70, v152, v92
	v_fma_f32 v120, -v71, v152, v93
	s_waitcnt vmcnt(4)
	v_lshlrev_b32_e32 v68, 16, v96
	v_and_b32_e32 v69, 0xffff0000, v96
	v_lshlrev_b32_e32 v70, 16, v97
	v_and_b32_e32 v71, 0xffff0000, v97
	v_fmac_f32_e32 v215, v169, v169
	v_fma_f32 v125, -v94, v152, v111
	v_fma_f32 v115, -v48, v152, v68
	v_fma_f32 v113, -v49, v152, v69
	v_fma_f32 v111, -v50, v152, v70
	v_fma_f32 v109, -v51, v152, v71
	global_load_dwordx4 v[48:51], v[154:155], off offset:1024
	v_fmac_f32_e32 v215, v168, v168
	v_fmac_f32_e32 v215, v165, v165
	v_fmac_f32_e32 v215, v164, v164
	v_fmac_f32_e32 v215, v163, v163
	v_fmac_f32_e32 v215, v161, v161
	v_and_b32_e32 v112, 0xffff0000, v203
	v_lshlrev_b32_e32 v94, 16, v208
	v_fmac_f32_e32 v215, v158, v158
	v_fma_f32 v124, -v95, v152, v112
	v_and_b32_e32 v95, 0xffff0000, v208
	v_lshlrev_b32_e32 v100, 16, v209
	v_and_b32_e32 v101, 0xffff0000, v209
	v_fma_f32 v119, -v72, v152, v94
	v_lshlrev_b32_e32 v72, 16, v98
	v_fmac_f32_e32 v215, v156, v156
	v_lshlrev_b32_e32 v104, 16, v211
	v_and_b32_e32 v105, 0xffff0000, v211
	v_fma_f32 v118, -v73, v152, v95
	v_fma_f32 v117, -v74, v152, v100
	v_fma_f32 v116, -v75, v152, v101
	v_and_b32_e32 v73, 0xffff0000, v98
	v_lshlrev_b32_e32 v74, 16, v99
	v_and_b32_e32 v75, 0xffff0000, v99
	v_fma_f32 v107, -v52, v152, v72
	s_waitcnt vmcnt(4)
	v_lshlrev_b32_e32 v52, 16, v84
	v_fmac_f32_e32 v215, v145, v145
	v_fma_f32 v110, -v78, v152, v104
	v_fma_f32 v108, -v79, v152, v105
	v_fma_f32 v106, -v53, v152, v73
	v_fma_f32 v105, -v54, v152, v74
	v_fma_f32 v104, -v55, v152, v75
	v_fma_f32 v99, -v32, v152, v52
	global_load_dwordx4 v[52:55], v[154:155], off offset:2048
	v_fmac_f32_e32 v215, v144, v144
	v_fmac_f32_e32 v215, v159, v159
	v_fmac_f32_e32 v215, v157, v157
	v_fmac_f32_e32 v215, v147, v147
	v_fmac_f32_e32 v215, v146, v146
	v_fmac_f32_e32 v215, v143, v143
	v_fmac_f32_e32 v215, v142, v142
	v_fmac_f32_e32 v215, v141, v141
	v_fmac_f32_e32 v215, v140, v140
	v_fmac_f32_e32 v215, v135, v135
	v_fmac_f32_e32 v215, v134, v134
	v_fmac_f32_e32 v215, v133, v133
	v_fmac_f32_e32 v215, v132, v132
	v_fmac_f32_e32 v215, v129, v129
	v_fmac_f32_e32 v215, v127, v127
	v_fmac_f32_e32 v215, v125, v125
	v_fmac_f32_e32 v215, v124, v124
	v_fmac_f32_e32 v215, v131, v131
	v_fmac_f32_e32 v215, v130, v130
	v_fmac_f32_e32 v215, v128, v128
	v_fmac_f32_e32 v215, v126, v126
	v_fmac_f32_e32 v215, v123, v123
	v_fmac_f32_e32 v215, v122, v122
	v_fmac_f32_e32 v215, v121, v121
	v_fmac_f32_e32 v215, v120, v120
	v_fmac_f32_e32 v215, v119, v119
	v_fmac_f32_e32 v215, v118, v118
	v_lshlrev_b32_e32 v102, 16, v210
	v_fmac_f32_e32 v215, v117, v117
	v_and_b32_e32 v103, 0xffff0000, v210
	v_fmac_f32_e32 v215, v116, v116
	v_fma_f32 v114, -v76, v152, v102
	v_fmac_f32_e32 v215, v114, v114
	v_fma_f32 v112, -v77, v152, v103
	v_fmac_f32_e32 v215, v112, v112
	v_fmac_f32_e32 v215, v110, v110
	v_fmac_f32_e32 v215, v108, v108
	v_fmac_f32_e32 v215, v115, v115
	v_fmac_f32_e32 v215, v113, v113
	v_fmac_f32_e32 v215, v111, v111
	v_fmac_f32_e32 v215, v109, v109
	v_fmac_f32_e32 v215, v107, v107
	v_fmac_f32_e32 v215, v106, v106
	s_waitcnt vmcnt(4)
	v_lshlrev_b32_e32 v76, 16, v80
	v_fmac_f32_e32 v215, v105, v105
	v_and_b32_e32 v77, 0xffff0000, v80
	v_fmac_f32_e32 v215, v104, v104
	v_fma_f32 v103, -v56, v152, v76
	v_lshlrev_b32_e32 v78, 16, v81
	v_fmac_f32_e32 v215, v103, v103
	v_fma_f32 v102, -v57, v152, v77
	v_and_b32_e32 v79, 0xffff0000, v81
	v_fmac_f32_e32 v215, v102, v102
	v_fma_f32 v101, -v58, v152, v78
	v_lshlrev_b32_e32 v80, 16, v82
	v_fmac_f32_e32 v215, v101, v101
	v_fma_f32 v100, -v59, v152, v79
	v_and_b32_e32 v81, 0xffff0000, v82
	v_fmac_f32_e32 v215, v100, v100
	v_fma_f32 v96, -v60, v152, v80
	v_lshlrev_b32_e32 v82, 16, v83
	v_fmac_f32_e32 v215, v96, v96
	v_fma_f32 v95, -v61, v152, v81
	v_and_b32_e32 v83, 0xffff0000, v83
	v_fmac_f32_e32 v215, v95, v95
	v_fma_f32 v92, -v62, v152, v82
	v_fmac_f32_e32 v215, v92, v92
	v_fma_f32 v91, -v63, v152, v83
	v_fmac_f32_e32 v215, v91, v91
	v_and_b32_e32 v56, 0xffff0000, v84
	v_lshlrev_b32_e32 v57, 16, v85
	v_fmac_f32_e32 v215, v99, v99
	v_fma_f32 v97, -v33, v152, v56
	v_and_b32_e32 v58, 0xffff0000, v85
	v_fmac_f32_e32 v215, v97, v97
	v_fma_f32 v94, -v34, v152, v57
	v_lshlrev_b32_e32 v59, 16, v86
	v_fmac_f32_e32 v215, v94, v94
	v_fma_f32 v93, -v35, v152, v58
	v_and_b32_e32 v60, 0xffff0000, v86
	v_fmac_f32_e32 v215, v93, v93
	v_fma_f32 v89, -v36, v152, v59
	v_lshlrev_b32_e32 v61, 16, v87
	v_fmac_f32_e32 v215, v89, v89
	v_fma_f32 v88, -v37, v152, v60
	v_and_b32_e32 v62, 0xffff0000, v87
	v_fmac_f32_e32 v215, v88, v88
	v_fma_f32 v87, -v38, v152, v61
	s_waitcnt vmcnt(3)
	v_lshlrev_b32_e32 v63, 16, v64
	v_fmac_f32_e32 v215, v87, v87
	v_fma_f32 v86, -v39, v152, v62
	v_and_b32_e32 v64, 0xffff0000, v64
	v_fmac_f32_e32 v215, v86, v86
	v_fma_f32 v85, -v40, v152, v63
	v_lshlrev_b32_e32 v68, 16, v65
	v_fmac_f32_e32 v215, v85, v85
	v_fma_f32 v84, -v41, v152, v64
	v_and_b32_e32 v65, 0xffff0000, v65
	v_fmac_f32_e32 v215, v84, v84
	v_fma_f32 v83, -v42, v152, v68
	v_lshlrev_b32_e32 v69, 16, v66
	v_fmac_f32_e32 v215, v83, v83
	v_fma_f32 v82, -v43, v152, v65
	v_and_b32_e32 v66, 0xffff0000, v66
	v_fmac_f32_e32 v215, v82, v82
	v_fma_f32 v80, -v44, v152, v69
	v_lshlrev_b32_e32 v70, 16, v67
	v_fmac_f32_e32 v215, v80, v80
	v_fma_f32 v78, -v45, v152, v66
	v_and_b32_e32 v67, 0xffff0000, v67
	v_fmac_f32_e32 v215, v78, v78
	v_fma_f32 v76, -v46, v152, v70
	v_fmac_f32_e32 v215, v76, v76
	v_fma_f32 v74, -v47, v152, v67
	s_waitcnt vmcnt(2)
	v_lshlrev_b32_e32 v32, 16, v196
	v_fmac_f32_e32 v215, v74, v74
	v_and_b32_e32 v33, 0xffff0000, v196
	v_fma_f32 v81, -v16, v152, v32
	v_lshlrev_b32_e32 v34, 16, v197
	v_fmac_f32_e32 v215, v81, v81
	v_fma_f32 v79, -v17, v152, v33
	v_and_b32_e32 v35, 0xffff0000, v197
	v_fmac_f32_e32 v215, v79, v79
	v_fma_f32 v77, -v18, v152, v34
	v_lshlrev_b32_e32 v36, 16, v198
	v_fmac_f32_e32 v215, v77, v77
	v_fma_f32 v75, -v19, v152, v35
	v_and_b32_e32 v37, 0xffff0000, v198
	v_fmac_f32_e32 v215, v75, v75
	v_fma_f32 v73, -v20, v152, v36
	v_lshlrev_b32_e32 v38, 16, v199
	v_fmac_f32_e32 v215, v73, v73
	v_fma_f32 v72, -v21, v152, v37
	v_and_b32_e32 v39, 0xffff0000, v199
	v_fmac_f32_e32 v215, v72, v72
	v_fma_f32 v71, -v22, v152, v38
	s_waitcnt vmcnt(1)
	v_lshlrev_b32_e32 v40, 16, v48
	v_fmac_f32_e32 v215, v71, v71
	v_fma_f32 v70, -v23, v152, v39
	v_and_b32_e32 v41, 0xffff0000, v48
	v_fmac_f32_e32 v215, v70, v70
	v_fma_f32 v69, -v24, v152, v40
	v_lshlrev_b32_e32 v42, 16, v49
	v_fmac_f32_e32 v215, v69, v69
	v_fma_f32 v68, -v25, v152, v41
	v_and_b32_e32 v43, 0xffff0000, v49
	v_fmac_f32_e32 v215, v68, v68
	v_fma_f32 v67, -v26, v152, v42
	v_lshlrev_b32_e32 v44, 16, v50
	v_fmac_f32_e32 v215, v67, v67
	v_fma_f32 v66, -v27, v152, v43
	v_and_b32_e32 v45, 0xffff0000, v50
	v_fmac_f32_e32 v215, v66, v66
	v_fma_f32 v65, -v28, v152, v44
	v_lshlrev_b32_e32 v46, 16, v51
	v_fmac_f32_e32 v215, v65, v65
	v_fma_f32 v64, -v29, v152, v45
	v_and_b32_e32 v47, 0xffff0000, v51
	v_fmac_f32_e32 v215, v64, v64
	v_fma_f32 v63, -v30, v152, v46
	v_fmac_f32_e32 v215, v63, v63
	v_fma_f32 v62, -v31, v152, v47
	s_waitcnt vmcnt(0)
	v_lshlrev_b32_e32 v16, 16, v52
	v_fmac_f32_e32 v215, v62, v62
	v_and_b32_e32 v17, 0xffff0000, v52
	v_fma_f32 v61, -v0, v152, v16
	v_lshlrev_b32_e32 v18, 16, v53
	v_lshlrev_b32_e32 v20, 16, v54
	v_and_b32_e32 v21, 0xffff0000, v54
	v_fmac_f32_e32 v215, v61, v61
	v_fma_f32 v60, -v1, v152, v17
	v_and_b32_e32 v1, 0xffff0000, v55
	v_lshlrev_b32_e32 v0, 16, v55
	v_and_b32_e32 v19, 0xffff0000, v53
	v_fmac_f32_e32 v215, v60, v60
	v_fma_f32 v59, -v2, v152, v18
	v_fma_f32 v57, -v4, v152, v20
	v_fma_f32 v56, -v5, v152, v21
	v_pk_fma_f32 v[0:1], v[6:7], v[152:153], v[0:1] op_sel_hi:[1,0,1] neg_lo:[1,0,0] neg_hi:[1,0,0]
	v_lshlrev_b64 v[4:5], 14, v[148:149]
	v_lshrrev_b32_e32 v6, 3, v153
	v_fmac_f32_e32 v215, v59, v59
	v_fma_f32 v58, -v3, v152, v19
	v_lshl_add_u64 v[4:5], s[2:3], 0, v[4:5]
	v_and_b32_e32 v90, 4, v6
	v_fmac_f32_e32 v215, v58, v58
	v_lshl_add_u64 v[4:5], v[4:5], 0, s[4:5]
	v_lshlrev_b32_e32 v178, 1, v90
	v_fmac_f32_e32 v215, v57, v57
	v_lshl_add_u64 v[4:5], v[4:5], 0, v[178:179]
	v_fmac_f32_e32 v215, v56, v56
	v_pk_mul_f32 v[2:3], v[0:1], v[0:1]
	v_add_co_u32_e32 v148, vcc, s63, v4
	v_add_f32_e32 v2, v2, v215
	s_waitcnt vmcnt(0)
	s_nop 0
	v_addc_co_u32_e32 v149, vcc, 0, v5, vcc
	global_load_dwordx2 v[150:151], v[148:149], off
	v_add_f32_e32 v6, v3, v2
	v_and_b32_e32 v3, 0xffff0000, v136
	v_lshlrev_b32_e32 v2, 16, v136
	v_pk_fma_f32 v[16:17], v[8:9], v[152:153], v[2:3] op_sel_hi:[1,0,1] neg_lo:[1,0,0] neg_hi:[1,0,0]
	s_nop 0
	v_pk_mul_f32 v[2:3], v[16:17], v[16:17]
	s_nop 0
	v_add_f32_e32 v2, v2, v6
	v_add_f32_e32 v6, v3, v2
	v_and_b32_e32 v3, 0xffff0000, v137
	v_lshlrev_b32_e32 v2, 16, v137
	v_pk_fma_f32 v[8:9], v[10:11], v[152:153], v[2:3] op_sel_hi:[1,0,1] neg_lo:[1,0,0] neg_hi:[1,0,0]
	v_and_b32_e32 v11, 0xffff0000, v139
	v_pk_mul_f32 v[2:3], v[8:9], v[8:9]
	s_nop 0
	v_add_f32_e32 v2, v2, v6
	v_add_f32_e32 v10, v3, v2
	v_and_b32_e32 v3, 0xffff0000, v138
	v_lshlrev_b32_e32 v2, 16, v138
	v_pk_fma_f32 v[6:7], v[12:13], v[152:153], v[2:3] op_sel_hi:[1,0,1] neg_lo:[1,0,0] neg_hi:[1,0,0]
	s_nop 0
	v_pk_mul_f32 v[2:3], v[6:7], v[6:7]
	s_nop 0
	v_add_f32_e32 v2, v2, v10
	v_add_f32_e32 v12, v3, v2
	v_lshl_add_u64 v[2:3], v[4:5], 0, s[6:7]
	global_load_dwordx2 v[154:155], v[2:3], off offset:16
	v_lshlrev_b32_e32 v10, 16, v139
	v_pk_fma_f32 v[4:5], v[14:15], v[152:153], v[10:11] op_sel_hi:[1,0,1] neg_lo:[1,0,0] neg_hi:[1,0,0]
	global_load_dwordx2 v[152:153], v[2:3], off offset:32
	global_load_dwordx2 v[188:189], v[2:3], off offset:48
	global_load_dwordx2 v[196:197], v[2:3], off offset:64
	global_load_dwordx2 v[198:199], v[2:3], off offset:80
	global_load_dwordx2 v[200:201], v[2:3], off offset:96
	global_load_dwordx2 v[202:203], v[2:3], off offset:112
	global_load_dwordx2 v[204:205], v[2:3], off offset:128
	global_load_dwordx2 v[206:207], v[2:3], off offset:144
	global_load_dwordx2 v[54:55], v[2:3], off offset:160
	global_load_dwordx2 v[52:53], v[2:3], off offset:176
	global_load_dwordx2 v[50:51], v[2:3], off offset:192
	global_load_dwordx2 v[48:49], v[2:3], off offset:208
	global_load_dwordx2 v[46:47], v[2:3], off offset:224
	global_load_dwordx2 v[44:45], v[2:3], off offset:240
	global_load_dwordx2 v[42:43], v[2:3], off offset:256
	global_load_dwordx2 v[40:41], v[2:3], off offset:272
	global_load_dwordx2 v[38:39], v[2:3], off offset:288
	global_load_dwordx2 v[36:37], v[2:3], off offset:304
	global_load_dwordx2 v[34:35], v[2:3], off offset:320
	global_load_dwordx2 v[32:33], v[2:3], off offset:336
	global_load_dwordx2 v[30:31], v[2:3], off offset:352
	global_load_dwordx2 v[28:29], v[2:3], off offset:368
	global_load_dwordx2 v[26:27], v[2:3], off offset:384
	global_load_dwordx2 v[24:25], v[2:3], off offset:400
	global_load_dwordx2 v[22:23], v[2:3], off offset:416
	global_load_dwordx2 v[20:21], v[2:3], off offset:432
	global_load_dwordx2 v[18:19], v[2:3], off offset:448
	v_pk_mul_f32 v[10:11], v[4:5], v[4:5]
	s_nop 0
	v_add_f32_e32 v10, v10, v12
	v_add_f32_e32 v10, v11, v10
	ds_bpermute_b32 v11, v194, v10
	s_waitcnt lgkmcnt(0)
	v_add_f32_e32 v10, v10, v11
	v_fmamk_f32 v10, v10, 0x3b800000, v191
	v_mul_f32_e32 v11, 0x4b800000, v10
	v_cmp_gt_f32_e32 vcc, s64, v10
	s_nop 1
	v_cndmask_b32_e32 v10, v10, v11, vcc
	v_rsq_f32_e32 v10, v10
	s_nop 0
	v_mul_f32_e32 v11, 0x45800000, v10
	v_cndmask_b32_e32 v178, v10, v11, vcc
	v_lshl_add_u32 v10, v90, 2, 0
	v_add_u32_e32 v98, 0x24000, v10
	ds_read_b128 v[136:139], v98
	v_mul_f32_e32 v90, 0x3ee34c56, v178
	v_mul_f32_e32 v178, v190, v90
	global_load_dwordx2 v[14:15], v[2:3], off offset:464
	global_load_dwordx2 v[12:13], v[2:3], off offset:480
	global_load_dwordx2 v[10:11], v[2:3], off offset:496
	v_mul_f32_e32 v143, v143, v90
	s_waitcnt lgkmcnt(0)
	v_mul_f32_e32 v136, v136, v178
	v_mul_f32_e32 v142, v142, v90
	v_mul_f32_e32 v135, v135, v90
	v_mul_f32_e32 v134, v134, v90
	v_mul_f32_e32 v133, v133, v90
	v_mul_f32_e32 v132, v132, v90
	v_mul_f32_e32 v0, v0, v90
	v_mul_f32_e32 v1, v1, v90
	s_waitcnt vmcnt(31)
	v_lshlrev_b32_e32 v178, 16, v150
	v_mul_f32_e32 v136, v136, v178
	v_mul_f32_e32 v178, v195, v90
	v_mul_f32_e32 v137, v137, v178
	v_and_b32_e32 v150, 0xffff0000, v150
	v_mul_f32_e32 v137, v137, v150
	v_cvt_pk_bf16_f32 v150, v136, v137
	v_mul_f32_e32 v136, v212, v90
	v_mul_f32_e32 v136, v138, v136
	v_lshlrev_b32_e32 v137, 16, v151
	v_mul_f32_e32 v136, v136, v137
	v_mul_f32_e32 v137, v213, v90
	v_mul_f32_e32 v137, v139, v137
	v_and_b32_e32 v138, 0xffff0000, v151
	v_mul_f32_e32 v137, v137, v138
	v_cvt_pk_bf16_f32 v151, v136, v137
	ds_read_b128 v[136:139], v98 offset:32
	global_store_dwordx2 v[148:149], v[150:151], off
	v_mul_f32_e32 v148, v214, v90
	s_waitcnt lgkmcnt(0)
	v_mul_f32_e32 v136, v136, v148
	s_waitcnt vmcnt(31)
	v_lshlrev_b32_e32 v148, 16, v154
	v_mul_f32_e32 v136, v136, v148
	v_mul_f32_e32 v148, v186, v90
	v_mul_f32_e32 v137, v137, v148
	v_and_b32_e32 v148, 0xffff0000, v154
	v_mul_f32_e32 v137, v137, v148
	v_cvt_pk_bf16_f32 v148, v136, v137
	v_mul_f32_e32 v136, v185, v90
	v_mul_f32_e32 v136, v138, v136
	v_lshlrev_b32_e32 v137, 16, v155
	v_mul_f32_e32 v136, v136, v137
	v_mul_f32_e32 v137, v184, v90
	v_mul_f32_e32 v137, v139, v137
	v_and_b32_e32 v138, 0xffff0000, v155
	v_mul_f32_e32 v137, v137, v138
	v_cvt_pk_bf16_f32 v149, v136, v137
	ds_read_b128 v[136:139], v98 offset:64
	global_store_dwordx2 v[2:3], v[148:149], off offset:16
	v_mul_f32_e32 v148, v183, v90
	s_waitcnt lgkmcnt(0)
	v_mul_f32_e32 v136, v136, v148
	s_waitcnt vmcnt(31)
	v_lshlrev_b32_e32 v148, 16, v152
	v_mul_f32_e32 v136, v136, v148
	v_mul_f32_e32 v148, v182, v90
	v_mul_f32_e32 v137, v137, v148
	v_and_b32_e32 v148, 0xffff0000, v152
	v_mul_f32_e32 v137, v137, v148
	v_cvt_pk_bf16_f32 v148, v136, v137
	v_mul_f32_e32 v136, v181, v90
	v_mul_f32_e32 v136, v138, v136
	v_lshlrev_b32_e32 v137, 16, v153
	v_mul_f32_e32 v136, v136, v137
	v_mul_f32_e32 v137, v180, v90
	v_mul_f32_e32 v137, v139, v137
	v_and_b32_e32 v138, 0xffff0000, v153
	v_mul_f32_e32 v137, v137, v138
	v_cvt_pk_bf16_f32 v149, v136, v137
	ds_read_b128 v[136:139], v98 offset:96
	global_store_dwordx2 v[2:3], v[148:149], off offset:32
	v_mul_f32_e32 v148, v175, v90
	s_waitcnt lgkmcnt(0)
	v_mul_f32_e32 v136, v136, v148
	s_waitcnt vmcnt(31)
	v_lshlrev_b32_e32 v148, 16, v188
	v_mul_f32_e32 v136, v136, v148
	v_mul_f32_e32 v148, v174, v90
	v_mul_f32_e32 v137, v137, v148
	v_and_b32_e32 v148, 0xffff0000, v188
	v_mul_f32_e32 v137, v137, v148
	v_cvt_pk_bf16_f32 v148, v136, v137
	v_mul_f32_e32 v136, v173, v90
	v_mul_f32_e32 v136, v138, v136
	v_lshlrev_b32_e32 v137, 16, v189
	v_mul_f32_e32 v136, v136, v137
	v_mul_f32_e32 v137, v172, v90
	v_mul_f32_e32 v137, v139, v137
	v_and_b32_e32 v138, 0xffff0000, v189
	v_mul_f32_e32 v137, v137, v138
	v_cvt_pk_bf16_f32 v149, v136, v137
	ds_read_b128 v[136:139], v98 offset:128
	global_store_dwordx2 v[2:3], v[148:149], off offset:48
	v_mul_f32_e32 v148, v171, v90
	s_waitcnt lgkmcnt(0)
	v_mul_f32_e32 v136, v136, v148
	s_waitcnt vmcnt(31)
	v_lshlrev_b32_e32 v148, 16, v196
	v_mul_f32_e32 v136, v136, v148
	v_mul_f32_e32 v148, v170, v90
	v_mul_f32_e32 v137, v137, v148
	v_and_b32_e32 v148, 0xffff0000, v196
	v_mul_f32_e32 v137, v137, v148
	v_cvt_pk_bf16_f32 v148, v136, v137
	v_mul_f32_e32 v136, v167, v90
	v_mul_f32_e32 v136, v138, v136
	v_lshlrev_b32_e32 v137, 16, v197
	v_mul_f32_e32 v136, v136, v137
	v_mul_f32_e32 v137, v166, v90
	v_mul_f32_e32 v137, v139, v137
	v_and_b32_e32 v138, 0xffff0000, v197
	v_mul_f32_e32 v137, v137, v138
	v_cvt_pk_bf16_f32 v149, v136, v137
	ds_read_b128 v[136:139], v98 offset:160
	global_store_dwordx2 v[2:3], v[148:149], off offset:64
	v_mul_f32_e32 v148, v162, v90
	s_waitcnt lgkmcnt(0)
	v_mul_f32_e32 v136, v136, v148
	s_waitcnt vmcnt(31)
	v_lshlrev_b32_e32 v148, 16, v198
	v_mul_f32_e32 v136, v136, v148
	v_mul_f32_e32 v148, v160, v90
	v_mul_f32_e32 v137, v137, v148
	v_and_b32_e32 v148, 0xffff0000, v198
	v_mul_f32_e32 v137, v137, v148
	v_cvt_pk_bf16_f32 v148, v136, v137
	v_mul_f32_e32 v136, v169, v90
	v_mul_f32_e32 v136, v138, v136
	v_lshlrev_b32_e32 v137, 16, v199
	v_mul_f32_e32 v136, v136, v137
	v_mul_f32_e32 v137, v168, v90
	v_mul_f32_e32 v137, v139, v137
	v_and_b32_e32 v138, 0xffff0000, v199
	v_mul_f32_e32 v137, v137, v138
	v_cvt_pk_bf16_f32 v149, v136, v137
	ds_read_b128 v[136:139], v98 offset:192
	global_store_dwordx2 v[2:3], v[148:149], off offset:80
	v_mul_f32_e32 v148, v165, v90
	s_waitcnt lgkmcnt(0)
	v_mul_f32_e32 v136, v136, v148
	s_waitcnt vmcnt(31)
	v_lshlrev_b32_e32 v148, 16, v200
	v_mul_f32_e32 v136, v136, v148
	v_mul_f32_e32 v148, v164, v90
	v_mul_f32_e32 v137, v137, v148
	v_and_b32_e32 v148, 0xffff0000, v200
	v_mul_f32_e32 v137, v137, v148
	v_cvt_pk_bf16_f32 v148, v136, v137
	v_mul_f32_e32 v136, v163, v90
	v_mul_f32_e32 v136, v138, v136
	v_lshlrev_b32_e32 v137, 16, v201
	v_mul_f32_e32 v136, v136, v137
	v_mul_f32_e32 v137, v161, v90
	v_mul_f32_e32 v137, v139, v137
	v_and_b32_e32 v138, 0xffff0000, v201
	v_mul_f32_e32 v137, v137, v138
	v_cvt_pk_bf16_f32 v149, v136, v137
	ds_read_b128 v[136:139], v98 offset:224
	global_store_dwordx2 v[2:3], v[148:149], off offset:96
	v_mul_f32_e32 v148, v158, v90
	s_waitcnt lgkmcnt(0)
	v_mul_f32_e32 v136, v136, v148
	s_waitcnt vmcnt(31)
	v_lshlrev_b32_e32 v148, 16, v202
	v_mul_f32_e32 v136, v136, v148
	v_mul_f32_e32 v148, v156, v90
	v_mul_f32_e32 v137, v137, v148
	v_and_b32_e32 v148, 0xffff0000, v202
	v_mul_f32_e32 v137, v137, v148
	v_cvt_pk_bf16_f32 v148, v136, v137
	v_mul_f32_e32 v136, v145, v90
	v_mul_f32_e32 v136, v138, v136
	v_lshlrev_b32_e32 v137, 16, v203
	v_mul_f32_e32 v136, v136, v137
	v_mul_f32_e32 v137, v144, v90
	v_mul_f32_e32 v137, v139, v137
	v_and_b32_e32 v138, 0xffff0000, v203
	v_mul_f32_e32 v137, v137, v138
	v_cvt_pk_bf16_f32 v149, v136, v137
	ds_read_b128 v[136:139], v98 offset:256
	v_mul_f32_e32 v144, v159, v90
	global_store_dwordx2 v[2:3], v[148:149], off offset:112
	s_waitcnt lgkmcnt(0)
	v_mul_f32_e32 v136, v136, v144
	s_waitcnt vmcnt(31)
	v_lshlrev_b32_e32 v144, 16, v204
	v_mul_f32_e32 v136, v136, v144
	v_mul_f32_e32 v144, v157, v90
	v_mul_f32_e32 v137, v137, v144
	v_and_b32_e32 v144, 0xffff0000, v204
	v_mul_f32_e32 v137, v137, v144
	v_cvt_pk_bf16_f32 v144, v136, v137
	v_mul_f32_e32 v136, v147, v90
	v_mul_f32_e32 v136, v138, v136
	v_lshlrev_b32_e32 v137, 16, v205
	v_mul_f32_e32 v136, v136, v137
	v_mul_f32_e32 v137, v146, v90
	v_mul_f32_e32 v137, v139, v137
	v_and_b32_e32 v138, 0xffff0000, v205
	v_mul_f32_e32 v137, v137, v138
	v_cvt_pk_bf16_f32 v145, v136, v137
	ds_read_b128 v[136:139], v98 offset:288
	global_store_dwordx2 v[2:3], v[144:145], off offset:128
	s_waitcnt lgkmcnt(0)
	v_mul_f32_e32 v136, v136, v143
	s_waitcnt vmcnt(31)
	v_lshlrev_b32_e32 v143, 16, v206
	v_mul_f32_e32 v136, v136, v143
	v_mul_f32_e32 v137, v137, v142
	v_and_b32_e32 v142, 0xffff0000, v206
	v_mul_f32_e32 v137, v137, v142
	v_cvt_pk_bf16_f32 v142, v136, v137
	v_mul_f32_e32 v136, v141, v90
	v_mul_f32_e32 v136, v138, v136
	v_lshlrev_b32_e32 v137, 16, v207
	v_mul_f32_e32 v136, v136, v137
	v_mul_f32_e32 v137, v140, v90
	v_mul_f32_e32 v137, v139, v137
	v_and_b32_e32 v138, 0xffff0000, v207
	v_mul_f32_e32 v137, v137, v138
	v_cvt_pk_bf16_f32 v143, v136, v137
	ds_read_b128 v[136:139], v98 offset:320
	global_store_dwordx2 v[2:3], v[142:143], off offset:144
	s_waitcnt lgkmcnt(0)
	v_mul_f32_e32 v135, v136, v135
	s_waitcnt vmcnt(31)
	v_lshlrev_b32_e32 v136, 16, v54
	v_mul_f32_e32 v134, v137, v134
	v_and_b32_e32 v54, 0xffff0000, v54
	v_mul_f32_e32 v54, v134, v54
	v_mul_f32_e32 v133, v138, v133
	v_lshlrev_b32_e32 v134, 16, v55
	v_mul_f32_e32 v132, v139, v132
	v_and_b32_e32 v55, 0xffff0000, v55
	v_mul_f32_e32 v135, v135, v136
	v_mul_f32_e32 v133, v133, v134
	v_mul_f32_e32 v55, v132, v55
	v_cvt_pk_bf16_f32 v54, v135, v54
	v_cvt_pk_bf16_f32 v55, v133, v55
	ds_read_b128 v[132:135], v98 offset:352
	global_store_dwordx2 v[2:3], v[54:55], off offset:160
	v_mul_f32_e32 v54, v129, v90
	s_waitcnt vmcnt(31)
	v_lshlrev_b32_e32 v55, 16, v52
	v_and_b32_e32 v52, 0xffff0000, v52
	s_waitcnt lgkmcnt(0)
	v_mul_f32_e32 v54, v132, v54
	v_mul_f32_e32 v54, v54, v55
	v_mul_f32_e32 v55, v127, v90
	v_mul_f32_e32 v55, v133, v55
	v_mul_f32_e32 v52, v55, v52
	v_cvt_pk_bf16_f32 v132, v54, v52
	v_mul_f32_e32 v52, v125, v90
	v_mul_f32_e32 v52, v134, v52
	v_lshlrev_b32_e32 v54, 16, v53
	v_mul_f32_e32 v52, v52, v54
	v_mul_f32_e32 v54, v124, v90
	v_mul_f32_e32 v54, v135, v54
	v_and_b32_e32 v53, 0xffff0000, v53
	v_mul_f32_e32 v53, v54, v53
	v_cvt_pk_bf16_f32 v133, v52, v53
	ds_read_b128 v[52:55], v98 offset:384
	v_mul_f32_e32 v124, v131, v90
	global_store_dwordx2 v[2:3], v[132:133], off offset:176
	s_waitcnt lgkmcnt(0)
	v_mul_f32_e32 v52, v52, v124
	s_waitcnt vmcnt(31)
	v_lshlrev_b32_e32 v124, 16, v50
	v_mul_f32_e32 v52, v52, v124
	v_mul_f32_e32 v124, v130, v90
	v_mul_f32_e32 v53, v53, v124
	v_and_b32_e32 v50, 0xffff0000, v50
	v_mul_f32_e32 v50, v53, v50
	v_cvt_pk_bf16_f32 v124, v52, v50
	v_mul_f32_e32 v50, v128, v90
	v_mul_f32_e32 v50, v54, v50
	v_lshlrev_b32_e32 v52, 16, v51
	v_mul_f32_e32 v50, v50, v52
	v_mul_f32_e32 v52, v126, v90
	v_mul_f32_e32 v52, v55, v52
	v_and_b32_e32 v51, 0xffff0000, v51
	v_mul_f32_e32 v51, v52, v51
	v_cvt_pk_bf16_f32 v125, v50, v51
	ds_read_b128 v[50:53], v98 offset:416
	v_mul_f32_e32 v54, v123, v90
	global_store_dwordx2 v[2:3], v[124:125], off offset:192
	s_waitcnt lgkmcnt(0)
	v_mul_f32_e32 v50, v50, v54
	s_waitcnt vmcnt(31)
	v_lshlrev_b32_e32 v54, 16, v48
	v_mul_f32_e32 v50, v50, v54
	v_mul_f32_e32 v54, v122, v90
	v_mul_f32_e32 v51, v51, v54
	v_and_b32_e32 v48, 0xffff0000, v48
	v_mul_f32_e32 v48, v51, v48
	v_cvt_pk_bf16_f32 v54, v50, v48
	v_mul_f32_e32 v48, v121, v90
	v_mul_f32_e32 v48, v52, v48
	v_lshlrev_b32_e32 v50, 16, v49
	v_mul_f32_e32 v48, v48, v50
	v_mul_f32_e32 v50, v120, v90
	v_mul_f32_e32 v50, v53, v50
	v_and_b32_e32 v49, 0xffff0000, v49
	v_mul_f32_e32 v49, v50, v49
	v_cvt_pk_bf16_f32 v55, v48, v49
	ds_read_b128 v[48:51], v98 offset:448
	v_mul_f32_e32 v52, v119, v90
	global_store_dwordx2 v[2:3], v[54:55], off offset:208
	s_waitcnt lgkmcnt(0)
	v_mul_f32_e32 v48, v48, v52
	s_waitcnt vmcnt(31)
	v_lshlrev_b32_e32 v52, 16, v46
	v_mul_f32_e32 v48, v48, v52
	v_mul_f32_e32 v52, v118, v90
	v_mul_f32_e32 v49, v49, v52
	v_and_b32_e32 v46, 0xffff0000, v46
	v_mul_f32_e32 v46, v49, v46
	v_cvt_pk_bf16_f32 v52, v48, v46
	v_mul_f32_e32 v46, v117, v90
	v_mul_f32_e32 v46, v50, v46
	v_lshlrev_b32_e32 v48, 16, v47
	v_mul_f32_e32 v46, v46, v48
	v_mul_f32_e32 v48, v116, v90
	v_mul_f32_e32 v48, v51, v48
	v_and_b32_e32 v47, 0xffff0000, v47
	v_mul_f32_e32 v47, v48, v47
	v_cvt_pk_bf16_f32 v53, v46, v47
	ds_read_b128 v[46:49], v98 offset:480
	v_mul_f32_e32 v50, v114, v90
	global_store_dwordx2 v[2:3], v[52:53], off offset:224
	s_waitcnt lgkmcnt(0)
	v_mul_f32_e32 v46, v46, v50
	s_waitcnt vmcnt(31)
	v_lshlrev_b32_e32 v50, 16, v44
	v_mul_f32_e32 v46, v46, v50
	v_mul_f32_e32 v50, v112, v90
	v_mul_f32_e32 v47, v47, v50
	v_and_b32_e32 v44, 0xffff0000, v44
	v_mul_f32_e32 v44, v47, v44
	v_cvt_pk_bf16_f32 v50, v46, v44
	v_mul_f32_e32 v44, v110, v90
	v_mul_f32_e32 v44, v48, v44
	v_lshlrev_b32_e32 v46, 16, v45
	v_mul_f32_e32 v44, v44, v46
	v_mul_f32_e32 v46, v108, v90
	v_mul_f32_e32 v46, v49, v46
	v_and_b32_e32 v45, 0xffff0000, v45
	v_mul_f32_e32 v45, v46, v45
	v_cvt_pk_bf16_f32 v51, v44, v45
	ds_read_b128 v[44:47], v98 offset:512
	v_mul_f32_e32 v48, v115, v90
	global_store_dwordx2 v[2:3], v[50:51], off offset:240
	s_waitcnt lgkmcnt(0)
	v_mul_f32_e32 v44, v44, v48
	s_waitcnt vmcnt(31)
	v_lshlrev_b32_e32 v48, 16, v42
	v_mul_f32_e32 v44, v44, v48
	v_mul_f32_e32 v48, v113, v90
	v_mul_f32_e32 v45, v45, v48
	v_and_b32_e32 v42, 0xffff0000, v42
	v_mul_f32_e32 v42, v45, v42
	v_cvt_pk_bf16_f32 v48, v44, v42
	v_mul_f32_e32 v42, v111, v90
	v_mul_f32_e32 v42, v46, v42
	v_lshlrev_b32_e32 v44, 16, v43
	v_mul_f32_e32 v42, v42, v44
	v_mul_f32_e32 v44, v109, v90
	v_mul_f32_e32 v44, v47, v44
	v_and_b32_e32 v43, 0xffff0000, v43
	v_mul_f32_e32 v43, v44, v43
	v_cvt_pk_bf16_f32 v49, v42, v43
	ds_read_b128 v[42:45], v98 offset:544
	v_mul_f32_e32 v46, v107, v90
	global_store_dwordx2 v[2:3], v[48:49], off offset:256
	s_waitcnt lgkmcnt(0)
	v_mul_f32_e32 v42, v42, v46
	s_waitcnt vmcnt(31)
	v_lshlrev_b32_e32 v46, 16, v40
	v_mul_f32_e32 v42, v42, v46
	v_mul_f32_e32 v46, v106, v90
	v_mul_f32_e32 v43, v43, v46
	v_and_b32_e32 v40, 0xffff0000, v40
	v_mul_f32_e32 v40, v43, v40
	v_cvt_pk_bf16_f32 v46, v42, v40
	v_mul_f32_e32 v40, v105, v90
	v_mul_f32_e32 v40, v44, v40
	v_lshlrev_b32_e32 v42, 16, v41
	v_mul_f32_e32 v40, v40, v42
	v_mul_f32_e32 v42, v104, v90
	v_mul_f32_e32 v42, v45, v42
	v_and_b32_e32 v41, 0xffff0000, v41
	v_mul_f32_e32 v41, v42, v41
	v_cvt_pk_bf16_f32 v47, v40, v41
	ds_read_b128 v[40:43], v98 offset:576
	v_mul_f32_e32 v44, v103, v90
	global_store_dwordx2 v[2:3], v[46:47], off offset:272
	s_waitcnt lgkmcnt(0)
	v_mul_f32_e32 v40, v40, v44
	s_waitcnt vmcnt(31)
	v_lshlrev_b32_e32 v44, 16, v38
	v_mul_f32_e32 v40, v40, v44
	v_mul_f32_e32 v44, v102, v90
	v_mul_f32_e32 v41, v41, v44
	v_and_b32_e32 v38, 0xffff0000, v38
	v_mul_f32_e32 v38, v41, v38
	v_cvt_pk_bf16_f32 v44, v40, v38
	v_mul_f32_e32 v38, v101, v90
	v_mul_f32_e32 v38, v42, v38
	v_lshlrev_b32_e32 v40, 16, v39
	v_mul_f32_e32 v38, v38, v40
	v_mul_f32_e32 v40, v100, v90
	v_mul_f32_e32 v40, v43, v40
	v_and_b32_e32 v39, 0xffff0000, v39
	v_mul_f32_e32 v39, v40, v39
	v_cvt_pk_bf16_f32 v45, v38, v39
	ds_read_b128 v[38:41], v98 offset:608
	v_mul_f32_e32 v42, v96, v90
	global_store_dwordx2 v[2:3], v[44:45], off offset:288
	s_waitcnt lgkmcnt(0)
	v_mul_f32_e32 v38, v38, v42
	s_waitcnt vmcnt(31)
	v_lshlrev_b32_e32 v42, 16, v36
	v_mul_f32_e32 v38, v38, v42
	v_mul_f32_e32 v42, v95, v90
	v_mul_f32_e32 v39, v39, v42
	v_and_b32_e32 v36, 0xffff0000, v36
	v_mul_f32_e32 v36, v39, v36
	v_cvt_pk_bf16_f32 v42, v38, v36
	v_mul_f32_e32 v36, v92, v90
	v_mul_f32_e32 v36, v40, v36
	v_lshlrev_b32_e32 v38, 16, v37
	v_mul_f32_e32 v36, v36, v38
	v_mul_f32_e32 v38, v91, v90
	v_mul_f32_e32 v38, v41, v38
	v_and_b32_e32 v37, 0xffff0000, v37
	v_mul_f32_e32 v37, v38, v37
	v_cvt_pk_bf16_f32 v43, v36, v37
	ds_read_b128 v[36:39], v98 offset:640
	v_mul_f32_e32 v40, v99, v90
	global_store_dwordx2 v[2:3], v[42:43], off offset:304
	s_waitcnt lgkmcnt(0)
	v_mul_f32_e32 v36, v36, v40
	s_waitcnt vmcnt(31)
	v_lshlrev_b32_e32 v40, 16, v34
	v_mul_f32_e32 v36, v36, v40
	v_mul_f32_e32 v40, v97, v90
	v_mul_f32_e32 v37, v37, v40
	v_and_b32_e32 v34, 0xffff0000, v34
	v_mul_f32_e32 v34, v37, v34
	v_cvt_pk_bf16_f32 v40, v36, v34
	v_mul_f32_e32 v34, v94, v90
	v_mul_f32_e32 v34, v38, v34
	v_lshlrev_b32_e32 v36, 16, v35
	v_mul_f32_e32 v34, v34, v36
	v_mul_f32_e32 v36, v93, v90
	v_mul_f32_e32 v36, v39, v36
	v_and_b32_e32 v35, 0xffff0000, v35
	v_mul_f32_e32 v35, v36, v35
	v_cvt_pk_bf16_f32 v41, v34, v35
	ds_read_b128 v[34:37], v98 offset:672
	v_mul_f32_e32 v38, v89, v90
	global_store_dwordx2 v[2:3], v[40:41], off offset:320
	s_waitcnt lgkmcnt(0)
	v_mul_f32_e32 v34, v34, v38
	s_waitcnt vmcnt(31)
	v_lshlrev_b32_e32 v38, 16, v32
	v_mul_f32_e32 v34, v34, v38
	v_mul_f32_e32 v38, v88, v90
	v_mul_f32_e32 v35, v35, v38
	v_and_b32_e32 v32, 0xffff0000, v32
	v_mul_f32_e32 v32, v35, v32
	v_cvt_pk_bf16_f32 v38, v34, v32
	v_mul_f32_e32 v32, v87, v90
	v_mul_f32_e32 v32, v36, v32
	v_lshlrev_b32_e32 v34, 16, v33
	v_mul_f32_e32 v32, v32, v34
	v_mul_f32_e32 v34, v86, v90
	v_mul_f32_e32 v34, v37, v34
	v_and_b32_e32 v33, 0xffff0000, v33
	v_mul_f32_e32 v33, v34, v33
	v_cvt_pk_bf16_f32 v39, v32, v33
	ds_read_b128 v[32:35], v98 offset:704
	v_mul_f32_e32 v36, v85, v90
	global_store_dwordx2 v[2:3], v[38:39], off offset:336
	s_waitcnt lgkmcnt(0)
	v_mul_f32_e32 v32, v32, v36
	s_waitcnt vmcnt(31)
	v_lshlrev_b32_e32 v36, 16, v30
	v_mul_f32_e32 v32, v32, v36
	v_mul_f32_e32 v36, v84, v90
	v_mul_f32_e32 v33, v33, v36
	v_and_b32_e32 v30, 0xffff0000, v30
	v_mul_f32_e32 v30, v33, v30
	v_cvt_pk_bf16_f32 v36, v32, v30
	v_mul_f32_e32 v30, v83, v90
	v_mul_f32_e32 v30, v34, v30
	v_lshlrev_b32_e32 v32, 16, v31
	v_mul_f32_e32 v30, v30, v32
	v_mul_f32_e32 v32, v82, v90
	v_mul_f32_e32 v32, v35, v32
	v_and_b32_e32 v31, 0xffff0000, v31
	v_mul_f32_e32 v31, v32, v31
	v_cvt_pk_bf16_f32 v37, v30, v31
	ds_read_b128 v[30:33], v98 offset:736
	v_mul_f32_e32 v34, v80, v90
	global_store_dwordx2 v[2:3], v[36:37], off offset:352
	s_waitcnt lgkmcnt(0)
	v_mul_f32_e32 v30, v30, v34
	s_waitcnt vmcnt(31)
	v_lshlrev_b32_e32 v34, 16, v28
	v_mul_f32_e32 v30, v30, v34
	v_mul_f32_e32 v34, v78, v90
	v_mul_f32_e32 v31, v31, v34
	v_and_b32_e32 v28, 0xffff0000, v28
	v_mul_f32_e32 v28, v31, v28
	v_cvt_pk_bf16_f32 v34, v30, v28
	v_mul_f32_e32 v28, v76, v90
	v_mul_f32_e32 v28, v32, v28
	v_lshlrev_b32_e32 v30, 16, v29
	v_mul_f32_e32 v28, v28, v30
	v_mul_f32_e32 v30, v74, v90
	v_mul_f32_e32 v30, v33, v30
	v_and_b32_e32 v29, 0xffff0000, v29
	v_mul_f32_e32 v29, v30, v29
	v_cvt_pk_bf16_f32 v35, v28, v29
	ds_read_b128 v[28:31], v98 offset:768
	v_mul_f32_e32 v32, v81, v90
	global_store_dwordx2 v[2:3], v[34:35], off offset:368
	s_waitcnt lgkmcnt(0)
	v_mul_f32_e32 v28, v32, v28
	s_waitcnt vmcnt(31)
	v_lshlrev_b32_e32 v32, 16, v26
	v_mul_f32_e32 v28, v28, v32
	v_mul_f32_e32 v32, v79, v90
	v_mul_f32_e32 v29, v32, v29
	v_and_b32_e32 v26, 0xffff0000, v26
	v_mul_f32_e32 v26, v29, v26
	v_cvt_pk_bf16_f32 v32, v28, v26
	v_mul_f32_e32 v26, v77, v90
	v_mul_f32_e32 v26, v26, v30
	v_lshlrev_b32_e32 v28, 16, v27
	v_mul_f32_e32 v26, v26, v28
	v_mul_f32_e32 v28, v75, v90
	v_mul_f32_e32 v28, v28, v31
	v_and_b32_e32 v27, 0xffff0000, v27
	v_mul_f32_e32 v27, v28, v27
	v_cvt_pk_bf16_f32 v33, v26, v27
	ds_read_b128 v[26:29], v98 offset:800
	v_mul_f32_e32 v30, v73, v90
	global_store_dwordx2 v[2:3], v[32:33], off offset:384
	s_waitcnt lgkmcnt(0)
	v_mul_f32_e32 v26, v30, v26
	s_waitcnt vmcnt(31)
	v_lshlrev_b32_e32 v30, 16, v24
	v_mul_f32_e32 v26, v26, v30
	v_mul_f32_e32 v30, v72, v90
	v_mul_f32_e32 v27, v30, v27
	v_and_b32_e32 v24, 0xffff0000, v24
	v_mul_f32_e32 v24, v27, v24
	v_cvt_pk_bf16_f32 v30, v26, v24
	v_mul_f32_e32 v24, v71, v90
	v_mul_f32_e32 v24, v24, v28
	v_lshlrev_b32_e32 v26, 16, v25
	v_mul_f32_e32 v24, v24, v26
	v_mul_f32_e32 v26, v70, v90
	v_mul_f32_e32 v26, v26, v29
	v_and_b32_e32 v25, 0xffff0000, v25
	v_mul_f32_e32 v25, v26, v25
	v_cvt_pk_bf16_f32 v31, v24, v25
	ds_read_b128 v[24:27], v98 offset:832
	v_mul_f32_e32 v28, v69, v90
	global_store_dwordx2 v[2:3], v[30:31], off offset:400
	s_waitcnt lgkmcnt(0)
	v_mul_f32_e32 v24, v28, v24
	s_waitcnt vmcnt(31)
	v_lshlrev_b32_e32 v28, 16, v22
	v_mul_f32_e32 v24, v24, v28
	v_mul_f32_e32 v28, v68, v90
	v_mul_f32_e32 v25, v28, v25
	v_and_b32_e32 v22, 0xffff0000, v22
	v_mul_f32_e32 v22, v25, v22
	v_cvt_pk_bf16_f32 v28, v24, v22
	v_mul_f32_e32 v22, v67, v90
	v_mul_f32_e32 v22, v22, v26
	v_lshlrev_b32_e32 v24, 16, v23
	v_mul_f32_e32 v22, v22, v24
	v_mul_f32_e32 v24, v66, v90
	v_mul_f32_e32 v24, v24, v27
	v_and_b32_e32 v23, 0xffff0000, v23
	v_mul_f32_e32 v23, v24, v23
	v_cvt_pk_bf16_f32 v29, v22, v23
	ds_read_b128 v[22:25], v98 offset:864
	v_mul_f32_e32 v26, v65, v90
	global_store_dwordx2 v[2:3], v[28:29], off offset:416
	s_waitcnt lgkmcnt(0)
	v_mul_f32_e32 v22, v26, v22
	s_waitcnt vmcnt(31)
	v_lshlrev_b32_e32 v26, 16, v20
	v_mul_f32_e32 v22, v22, v26
	v_mul_f32_e32 v26, v64, v90
	v_mul_f32_e32 v23, v26, v23
	v_and_b32_e32 v20, 0xffff0000, v20
	v_mul_f32_e32 v20, v23, v20
	v_cvt_pk_bf16_f32 v26, v22, v20
	v_mul_f32_e32 v20, v63, v90
	v_mul_f32_e32 v20, v20, v24
	v_lshlrev_b32_e32 v22, 16, v21
	v_mul_f32_e32 v20, v20, v22
	v_mul_f32_e32 v22, v62, v90
	v_mul_f32_e32 v22, v22, v25
	v_and_b32_e32 v21, 0xffff0000, v21
	v_mul_f32_e32 v21, v22, v21
	v_cvt_pk_bf16_f32 v27, v20, v21
	ds_read_b128 v[20:23], v98 offset:896
	v_mul_f32_e32 v24, v61, v90
	global_store_dwordx2 v[2:3], v[26:27], off offset:432
	s_waitcnt lgkmcnt(0)
	v_mul_f32_e32 v20, v24, v20
	s_waitcnt vmcnt(31)
	v_lshlrev_b32_e32 v24, 16, v18
	v_mul_f32_e32 v20, v20, v24
	v_mul_f32_e32 v24, v60, v90
	v_mul_f32_e32 v21, v24, v21
	v_and_b32_e32 v18, 0xffff0000, v18
	v_mul_f32_e32 v18, v21, v18
	v_cvt_pk_bf16_f32 v24, v20, v18
	v_mul_f32_e32 v18, v59, v90
	v_mul_f32_e32 v18, v18, v22
	v_lshlrev_b32_e32 v20, 16, v19
	v_mul_f32_e32 v18, v18, v20
	v_mul_f32_e32 v20, v58, v90
	v_mul_f32_e32 v20, v20, v23
	v_and_b32_e32 v19, 0xffff0000, v19
	v_mul_f32_e32 v19, v20, v19
	v_cvt_pk_bf16_f32 v25, v18, v19
	ds_read_b128 v[18:21], v98 offset:928
	v_mul_f32_e32 v22, v57, v90
	global_store_dwordx2 v[2:3], v[24:25], off offset:448
	s_waitcnt lgkmcnt(0)
	v_mul_f32_e32 v18, v22, v18
	s_waitcnt vmcnt(31)
	v_lshlrev_b32_e32 v22, 16, v14
	v_mul_f32_e32 v18, v18, v22
	v_mul_f32_e32 v22, v56, v90
	v_mul_f32_e32 v19, v22, v19
	v_and_b32_e32 v14, 0xffff0000, v14
	v_mul_f32_e32 v14, v19, v14
	v_cvt_pk_bf16_f32 v14, v18, v14
	v_mul_f32_e32 v0, v0, v20
	v_lshlrev_b32_e32 v18, 16, v15
	v_mul_f32_e32 v1, v1, v21
	v_and_b32_e32 v15, 0xffff0000, v15
	v_mul_f32_e32 v0, v0, v18
	v_mul_f32_e32 v1, v1, v15
	v_cvt_pk_bf16_f32 v15, v0, v1
	ds_read_b128 v[18:21], v98 offset:960
	v_mul_f32_e32 v0, v16, v90
	s_waitcnt vmcnt(30)
	v_lshlrev_b32_e32 v1, 16, v12
	v_and_b32_e32 v12, 0xffff0000, v12
	global_store_dwordx2 v[2:3], v[14:15], off offset:464
	s_waitcnt lgkmcnt(0)
	v_mul_f32_e32 v0, v0, v18
	v_mul_f32_e32 v0, v0, v1
	v_mul_f32_e32 v1, v17, v90
	v_mul_f32_e32 v1, v1, v19
	v_mul_f32_e32 v1, v1, v12
	v_cvt_pk_bf16_f32 v0, v0, v1
	v_mul_f32_e32 v1, v8, v90
	v_mul_f32_e32 v1, v1, v20
	v_lshlrev_b32_e32 v8, 16, v13
	v_mul_f32_e32 v1, v1, v8
	v_mul_f32_e32 v8, v9, v90
	v_mul_f32_e32 v8, v8, v21
	v_and_b32_e32 v9, 0xffff0000, v13
	v_mul_f32_e32 v8, v8, v9
	v_cvt_pk_bf16_f32 v1, v1, v8
	ds_read_b128 v[12:15], v98 offset:992
	global_store_dwordx2 v[2:3], v[0:1], off offset:480
	v_mul_f32_e32 v0, v6, v90
	s_waitcnt vmcnt(31)
	v_lshlrev_b32_e32 v1, 16, v10
	v_and_b32_e32 v6, 0xffff0000, v10
	s_waitcnt lgkmcnt(0)
	v_mul_f32_e32 v0, v0, v12
	v_mul_f32_e32 v0, v0, v1
	v_mul_f32_e32 v1, v7, v90
	v_mul_f32_e32 v1, v1, v13
	v_mul_f32_e32 v1, v1, v6
	v_cvt_pk_bf16_f32 v0, v0, v1
	v_mul_f32_e32 v1, v4, v90
	v_mul_f32_e32 v1, v1, v14
	v_lshlrev_b32_e32 v4, 16, v11
	v_mul_f32_e32 v1, v1, v4
	v_mul_f32_e32 v4, v5, v90
	v_mul_f32_e32 v4, v4, v15
	v_and_b32_e32 v5, 0xffff0000, v11
	v_mul_f32_e32 v4, v4, v5
	v_cvt_pk_bf16_f32 v1, v1, v4
	global_store_dwordx2 v[2:3], v[0:1], off offset:496
	v_mov_b32_e32 v4, v176
	v_mov_b32_e32 v181, v179
	v_bfe_u32 v0, v4, 4, 2
	v_or_b32_e32 v1, s71, v0
	v_bitop3_b32 v0, v0, v4, s71 bitop3:0x36
	v_lshlrev_b32_e32 v2, 14, v1
	v_lshlrev_b32_e32 v0, 4, v0
	v_and_or_b32 v178, v0, s55, v2
	v_or_b32_e32 v0, 4, v1
	v_bitop3_b32 v1, v1, v4, 4 bitop3:0x36
	v_lshlrev_b32_e32 v0, 14, v0
	v_lshlrev_b32_e32 v1, 4, v1
	v_and_or_b32 v180, v1, s55, v0
	v_bfe_u32 v0, v4, 5, 1
	v_or_b32_e32 v1, s71, v0
	v_and_b32_e32 v2, 31, v4
	v_lshlrev_b32_e32 v3, 14, v1
	v_lshlrev_b32_e32 v0, 6, v0
	v_lshlrev_b32_e32 v5, 4, v2
	v_bitop3_b32 v182, v0, v3, v5 bitop3:0xde
	v_or_b32_e32 v0, 2, v1
	v_lshlrev_b32_e32 v3, 2, v0
	v_bitop3_b32 v3, v3, v2, 12 bitop3:0x6c
	v_lshlrev_b32_e32 v0, 14, v0
	v_lshl_or_b32 v184, v3, 4, v0
	v_or_b32_e32 v0, 6, v1
	v_lshlrev_b32_e32 v1, 2, v0
	v_bitop3_b32 v1, v1, v2, 12 bitop3:0x6c
	v_lshlrev_b32_e32 v0, 14, v0
	v_lshl_or_b32 v188, v1, 4, v0
	v_lshl_add_u64 v[0:1], s[34:35], 0, v[178:179]
	s_mov_b32 s13, m0
	s_mov_b32 m0, s36
	s_nop 0
	global_load_lds_dwordx4 v[0:1], off
	s_mov_b32 m0, s13
	v_lshl_add_u64 v[0:1], s[34:35], 0, v[180:181]
	v_mov_b32_e32 v183, v179
	s_add_i32 s13, s36, 0x400
	s_mov_b32 s14, m0
	s_mov_b32 m0, s13
	s_nop 0
	global_load_lds_dwordx4 v[0:1], off
	s_mov_b32 m0, s14
	v_lshl_add_u64 v[0:1], s[16:17], 0, v[182:183]
	v_mov_b32_e32 v185, v179
	v_or_b32_e32 v186, 0x10000, v182
	s_mov_b32 s13, m0
	s_mov_b32 m0, s37
	s_nop 0
	global_load_lds_dwordx4 v[0:1], off
	s_mov_b32 m0, s13
	v_lshl_add_u64 v[0:1], s[16:17], 0, v[184:185]
	s_add_i32 s12, s12, s33
	v_mov_b32_e32 v187, v179
	s_add_i32 s13, s12, 0xc400
	s_mov_b32 s14, m0
	s_mov_b32 m0, s13
	s_nop 0
	global_load_lds_dwordx4 v[0:1], off
	s_mov_b32 m0, s14
	v_lshl_add_u64 v[0:1], s[16:17], 0, v[186:187]
	v_mov_b32_e32 v189, v179
	s_add_i32 s13, s12, 0xc800
	s_mov_b32 s14, m0
	s_mov_b32 m0, s13
	s_nop 0
	global_load_lds_dwordx4 v[0:1], off
	s_mov_b32 m0, s14
	v_lshl_add_u64 v[0:1], s[16:17], 0, v[188:189]
	s_add_i32 s13, s12, 0xcc00
	s_mov_b32 s14, m0
	s_mov_b32 m0, s13
	s_nop 0
	global_load_lds_dwordx4 v[0:1], off
	s_mov_b32 m0, s14
	v_lshl_add_u64 v[0:1], s[40:41], 0, v[178:179]
	s_add_i32 s13, s36, 0x4000
	s_mov_b32 s14, m0
	s_mov_b32 m0, s13
	s_nop 0
	global_load_lds_dwordx4 v[0:1], off
	s_mov_b32 m0, s14
	v_lshl_add_u64 v[0:1], s[40:41], 0, v[180:181]
	s_add_i32 s13, s36, 0x4400
	s_mov_b32 s14, m0
	s_mov_b32 m0, s13
	s_nop 0
	global_load_lds_dwordx4 v[0:1], off
	s_mov_b32 m0, s14
	v_lshl_add_u64 v[0:1], s[10:11], 0, v[182:183]
	s_add_i32 s13, s12, 0x14000
	s_mov_b32 s14, m0
	s_mov_b32 m0, s13
	s_nop 0
	global_load_lds_dwordx4 v[0:1], off
	s_mov_b32 m0, s14
	v_lshl_add_u64 v[0:1], s[10:11], 0, v[184:185]
	s_add_i32 s13, s12, 0x14400
	s_mov_b32 s14, m0
	s_mov_b32 m0, s13
	s_nop 0
	global_load_lds_dwordx4 v[0:1], off
	s_mov_b32 m0, s14
	v_lshl_add_u64 v[0:1], s[10:11], 0, v[186:187]
	s_add_i32 s13, s12, 0x14800
	s_mov_b32 s14, m0
	s_mov_b32 m0, s13
	s_nop 0
	global_load_lds_dwordx4 v[0:1], off
	s_mov_b32 m0, s14
	v_lshl_add_u64 v[0:1], s[10:11], 0, v[188:189]
	s_add_i32 s12, s12, 0x14c00
	s_mov_b32 s13, m0
	s_mov_b32 m0, s12
	s_nop 0
	global_load_lds_dwordx4 v[0:1], off
	s_mov_b32 m0, s13
	v_or_b32_e32 v0, s18, v2
	v_mov_b32_e32 v1, s19
	v_lshlrev_b64 v[0:1], 14, v[0:1]
	v_lshrrev_b32_e32 v2, 1, v4
	v_lshl_add_u64 v[0:1], s[8:9], 0, v[0:1]
	v_and_b32_e32 v2, 16, v2
	v_mov_b32_e32 v3, v179
	v_lshl_add_u64 v[0:1], v[0:1], 0, v[2:3]
	global_load_dwordx4 v[144:147], v[0:1], off
	global_load_dwordx4 v[148:151], v[0:1], off offset:32
	global_load_dwordx4 v[152:155], v[0:1], off offset:64
	global_load_dwordx4 v[156:159], v[0:1], off offset:96
	global_load_dwordx4 v[160:163], v[0:1], off offset:128
	global_load_dwordx4 v[164:167], v[0:1], off offset:160
	global_load_dwordx4 v[168:171], v[0:1], off offset:192
	global_load_dwordx4 v[172:175], v[0:1], off offset:224
	v_lshrrev_b32_e32 v0, 5, v4
	v_and_b32_e32 v1, 15, v4
	v_bitop3_b32 v0, v0, v1, 1 bitop3:0x6c
	v_lshlrev_b32_e32 v1, 8, v4
	v_lshlrev_b32_e32 v0, 4, v0
	v_and_b32_e32 v1, 0x1f00, v1
	v_mov_b32_e32 v14, v179
	v_mov_b32_e32 v15, v179
	v_or_b32_e32 v195, v0, v1
	v_bitop3_b32 v196, v0, 32, v1 bitop3:0x36
	v_bitop3_b32 v197, v0, 64, v1 bitop3:0x36
	v_bitop3_b32 v198, v0, s56, v1 bitop3:0x36
	v_bitop3_b32 v199, v0, s57, v1 bitop3:0x36
	v_bitop3_b32 v200, v0, s58, v1 bitop3:0x36
	v_bitop3_b32 v201, v0, s59, v1 bitop3:0x36
	v_bitop3_b32 v202, v0, s60, v1 bitop3:0x36
	v_mov_b32_e32 v0, v179
	v_mov_b32_e32 v1, v179
	v_mov_b32_e32 v2, v179
	v_mov_b32_e32 v4, v179
	v_mov_b32_e32 v5, v179
	v_mov_b32_e32 v6, v179
	v_mov_b32_e32 v7, v179
	v_mov_b32_e32 v8, v179
	s_waitcnt vmcnt(7)
	s_waitcnt vmcnt(6)
	s_waitcnt vmcnt(5)
	s_waitcnt vmcnt(4)
	s_waitcnt vmcnt(3)
	s_waitcnt vmcnt(2)
	s_waitcnt vmcnt(1)
	s_waitcnt vmcnt(0)
	s_waitcnt vmcnt(0)
	v_mov_b32_e32 v9, v179
	v_mov_b32_e32 v10, v179
	v_mov_b32_e32 v11, v179
	v_mov_b32_e32 v12, v179
	v_mov_b32_e32 v13, v179
	v_mov_b64_e32 v[30:31], v[14:15]
	v_mov_b64_e32 v[46:47], v[14:15]
	v_mov_b64_e32 v[62:63], v[14:15]
	v_mov_b64_e32 v[78:79], v[14:15]
	v_mov_b64_e32 v[94:95], v[14:15]
	v_mov_b64_e32 v[110:111], v[14:15]
	v_mov_b64_e32 v[126:127], v[14:15]
	v_mov_b32_e32 v190, 0xf149f2ca
	v_mov_b32_e32 v203, 0
	v_mov_b64_e32 v[28:29], v[12:13]
	v_mov_b64_e32 v[26:27], v[10:11]
	v_mov_b64_e32 v[24:25], v[8:9]
	v_mov_b64_e32 v[22:23], v[6:7]
	v_mov_b64_e32 v[20:21], v[4:5]
	v_mov_b64_e32 v[18:19], v[2:3]
	v_mov_b64_e32 v[16:17], v[0:1]
	v_mov_b64_e32 v[44:45], v[12:13]
	v_mov_b64_e32 v[42:43], v[10:11]
	v_mov_b64_e32 v[40:41], v[8:9]
	v_mov_b64_e32 v[38:39], v[6:7]
	v_mov_b64_e32 v[36:37], v[4:5]
	v_mov_b64_e32 v[34:35], v[2:3]
	v_mov_b64_e32 v[32:33], v[0:1]
	v_mov_b64_e32 v[60:61], v[12:13]
	v_mov_b64_e32 v[58:59], v[10:11]
	v_mov_b64_e32 v[56:57], v[8:9]
	v_mov_b64_e32 v[54:55], v[6:7]
	v_mov_b64_e32 v[52:53], v[4:5]
	v_mov_b64_e32 v[50:51], v[2:3]
	v_mov_b64_e32 v[48:49], v[0:1]
	v_mov_b64_e32 v[76:77], v[12:13]
	v_mov_b64_e32 v[74:75], v[10:11]
	v_mov_b64_e32 v[72:73], v[8:9]
	v_mov_b64_e32 v[70:71], v[6:7]
	v_mov_b64_e32 v[68:69], v[4:5]
	v_mov_b64_e32 v[66:67], v[2:3]
	v_mov_b64_e32 v[64:65], v[0:1]
	v_mov_b64_e32 v[92:93], v[12:13]
	v_mov_b64_e32 v[90:91], v[10:11]
	v_mov_b64_e32 v[88:89], v[8:9]
	v_mov_b64_e32 v[86:87], v[6:7]
	v_mov_b64_e32 v[84:85], v[4:5]
	v_mov_b64_e32 v[82:83], v[2:3]
	v_mov_b64_e32 v[80:81], v[0:1]
	v_mov_b64_e32 v[108:109], v[12:13]
	v_mov_b64_e32 v[106:107], v[10:11]
	v_mov_b64_e32 v[104:105], v[8:9]
	v_mov_b64_e32 v[102:103], v[6:7]
	v_mov_b64_e32 v[100:101], v[4:5]
	v_mov_b64_e32 v[98:99], v[2:3]
	v_mov_b64_e32 v[96:97], v[0:1]
	v_mov_b64_e32 v[124:125], v[12:13]
	v_mov_b64_e32 v[122:123], v[10:11]
	v_mov_b64_e32 v[120:121], v[8:9]
	v_mov_b64_e32 v[118:119], v[6:7]
	v_mov_b64_e32 v[116:117], v[4:5]
	v_mov_b64_e32 v[114:115], v[2:3]
	v_mov_b64_e32 v[112:113], v[0:1]
	s_mov_b32 s34, 0
	v_lshrrev_b32_e32 v246, 8, v220
	s_nop 0
	v_readfirstlane_b32 s100, v246
	s_nop 3
	s_cmp_lg_u32 s100, 0
	s_cbranch_scc0 .Latt_prio_6
	s_setprio 1

.LBB0_1854:
	ds_bpermute_b32 v128, v194, v203
	s_add_i32 s12, s74, s46
	s_mov_b32 s13, s5
	s_lshl_b64 s[12:13], s[12:13], 14
	s_add_u32 s12, s44, s12
	s_waitcnt lgkmcnt(0)
	v_add_f32_e32 v128, v203, v128
	v_rcp_f32_e32 v130, v128
	v_mov_b32_e32 v128, v176
	s_addc_u32 s13, s45, s13
	v_lshlrev_b32_e32 v128, 4, v128
	v_mul_f32_e32 v112, v112, v130
	v_mul_f32_e32 v113, v113, v130
	v_mul_f32_e32 v114, v114, v130
	v_mul_f32_e32 v115, v115, v130
	v_and_b32_e32 v178, 0x3f0, v128
	v_mul_f32_e32 v116, v116, v130
	v_mul_f32_e32 v117, v117, v130
	v_mul_f32_e32 v118, v118, v130
	v_mul_f32_e32 v119, v119, v130
	v_cvt_pk_bf16_f32 v112, v112, v113
	v_cvt_pk_bf16_f32 v113, v114, v115
	v_cvt_pk_bf16_f32 v114, v116, v117
	v_cvt_pk_bf16_f32 v115, v118, v119
	v_mul_f32_e32 v96, v96, v130
	v_mul_f32_e32 v97, v97, v130
	v_mul_f32_e32 v98, v98, v130
	v_mul_f32_e32 v99, v99, v130
	v_lshl_add_u64 v[128:129], s[12:13], 0, v[178:179]
	v_mul_f32_e32 v120, v120, v130
	v_mul_f32_e32 v121, v121, v130
	v_mul_f32_e32 v122, v122, v130
	v_mul_f32_e32 v123, v123, v130
	v_mul_f32_e32 v124, v124, v130
	v_mul_f32_e32 v125, v125, v130
	v_mul_f32_e32 v126, v126, v130
	v_mul_f32_e32 v127, v127, v130
	v_cvt_pk_bf16_f32 v116, v120, v121
	v_cvt_pk_bf16_f32 v117, v122, v123
	v_cvt_pk_bf16_f32 v118, v124, v125
	v_cvt_pk_bf16_f32 v119, v126, v127
	global_store_dwordx4 v178, v[112:115], s[12:13]
	global_store_dwordx4 v178, v[116:119], s[12:13] offset:1024
	v_mul_f32_e32 v100, v100, v130
	v_mul_f32_e32 v101, v101, v130
	v_mul_f32_e32 v102, v102, v130
	v_mul_f32_e32 v103, v103, v130
	v_cvt_pk_bf16_f32 v96, v96, v97
	v_cvt_pk_bf16_f32 v97, v98, v99
	v_cvt_pk_bf16_f32 v98, v100, v101
	v_cvt_pk_bf16_f32 v99, v102, v103
	v_mul_f32_e32 v80, v80, v130
	v_mul_f32_e32 v81, v81, v130
	v_mul_f32_e32 v82, v82, v130
	v_mul_f32_e32 v83, v83, v130
	v_mul_f32_e32 v84, v84, v130
	v_mul_f32_e32 v88, v88, v130
	v_mul_f32_e32 v104, v104, v130
	v_mul_f32_e32 v105, v105, v130
	v_mul_f32_e32 v106, v106, v130
	v_mul_f32_e32 v107, v107, v130
	v_mul_f32_e32 v108, v108, v130
	v_mul_f32_e32 v109, v109, v130
	v_mul_f32_e32 v110, v110, v130
	v_mul_f32_e32 v111, v111, v130
	v_cvt_pk_bf16_f32 v100, v104, v105
	v_cvt_pk_bf16_f32 v101, v106, v107
	v_cvt_pk_bf16_f32 v102, v108, v109
	v_cvt_pk_bf16_f32 v103, v110, v111
	global_store_dwordx4 v178, v[96:99], s[12:13] offset:2048
	global_store_dwordx4 v178, v[100:103], s[12:13] offset:3072
	v_mul_f32_e32 v85, v85, v130
	v_mul_f32_e32 v86, v86, v130
	v_mul_f32_e32 v87, v87, v130
	v_mul_f32_e32 v89, v89, v130
	v_cvt_pk_bf16_f32 v80, v80, v81
	v_cvt_pk_bf16_f32 v81, v82, v83
	v_cvt_pk_bf16_f32 v82, v84, v85
	v_cvt_pk_bf16_f32 v83, v86, v87
	v_cvt_pk_bf16_f32 v84, v88, v89
	v_add_co_u32_e32 v88, vcc, s61, v128
	v_mul_f32_e32 v90, v90, v130
	s_nop 0
	v_addc_co_u32_e32 v89, vcc, 0, v129, vcc
	v_mul_f32_e32 v91, v91, v130
	v_cvt_pk_bf16_f32 v85, v90, v91
	v_add_co_u32_e32 v90, vcc, s62, v128
	v_mul_f32_e32 v64, v64, v130
	s_nop 0
	v_addc_co_u32_e32 v91, vcc, 0, v129, vcc
	v_mul_f32_e32 v65, v65, v130
	v_mul_f32_e32 v66, v66, v130
	v_mul_f32_e32 v67, v67, v130
	v_mul_f32_e32 v92, v92, v130
	v_mul_f32_e32 v93, v93, v130
	v_mul_f32_e32 v94, v94, v130
	v_mul_f32_e32 v95, v95, v130
	v_cvt_pk_bf16_f32 v86, v92, v93
	v_cvt_pk_bf16_f32 v87, v94, v95
	global_store_dwordx4 v[90:91], v[80:83], off offset:-4096
	global_store_dwordx4 v[88:89], v[84:87], off offset:1024
	v_mul_f32_e32 v68, v68, v130
	v_mul_f32_e32 v69, v69, v130
	v_mul_f32_e32 v70, v70, v130
	v_mul_f32_e32 v71, v71, v130
	v_cvt_pk_bf16_f32 v64, v64, v65
	v_cvt_pk_bf16_f32 v65, v66, v67
	v_cvt_pk_bf16_f32 v66, v68, v69
	v_cvt_pk_bf16_f32 v67, v70, v71
	v_mul_f32_e32 v48, v48, v130
	v_mul_f32_e32 v49, v49, v130
	v_mul_f32_e32 v50, v50, v130
	v_mul_f32_e32 v51, v51, v130
	v_mul_f32_e32 v72, v72, v130
	v_mul_f32_e32 v73, v73, v130
	v_mul_f32_e32 v74, v74, v130
	v_mul_f32_e32 v75, v75, v130
	v_mul_f32_e32 v76, v76, v130
	v_mul_f32_e32 v77, v77, v130
	v_mul_f32_e32 v78, v78, v130
	v_mul_f32_e32 v79, v79, v130
	v_cvt_pk_bf16_f32 v68, v72, v73
	v_cvt_pk_bf16_f32 v69, v74, v75
	v_cvt_pk_bf16_f32 v70, v76, v77
	v_cvt_pk_bf16_f32 v71, v78, v79
	global_store_dwordx4 v[88:89], v[64:67], off offset:2048
	global_store_dwordx4 v[88:89], v[68:71], off offset:3072
	v_mul_f32_e32 v52, v52, v130
	v_mul_f32_e32 v53, v53, v130
	v_mul_f32_e32 v54, v54, v130
	v_mul_f32_e32 v55, v55, v130
	v_cvt_pk_bf16_f32 v48, v48, v49
	v_cvt_pk_bf16_f32 v49, v50, v51
	v_cvt_pk_bf16_f32 v50, v52, v53
	v_cvt_pk_bf16_f32 v51, v54, v55
	v_mul_f32_e32 v32, v32, v130
	v_mul_f32_e32 v33, v33, v130
	v_mul_f32_e32 v34, v34, v130
	v_mul_f32_e32 v35, v35, v130
	v_mul_f32_e32 v56, v56, v130
	v_mul_f32_e32 v57, v57, v130
	v_mul_f32_e32 v58, v58, v130
	v_mul_f32_e32 v59, v59, v130
	v_mul_f32_e32 v60, v60, v130
	v_mul_f32_e32 v61, v61, v130
	v_mul_f32_e32 v62, v62, v130
	v_mul_f32_e32 v63, v63, v130
	v_cvt_pk_bf16_f32 v52, v56, v57
	v_cvt_pk_bf16_f32 v53, v58, v59
	v_cvt_pk_bf16_f32 v54, v60, v61
	v_cvt_pk_bf16_f32 v55, v62, v63
	global_store_dwordx4 v[90:91], v[48:51], off
	global_store_dwordx4 v[90:91], v[52:55], off offset:1024
	v_mul_f32_e32 v36, v36, v130
	v_mul_f32_e32 v37, v37, v130
	v_mul_f32_e32 v38, v38, v130
	v_mul_f32_e32 v39, v39, v130
	v_cvt_pk_bf16_f32 v32, v32, v33
	v_cvt_pk_bf16_f32 v33, v34, v35
	v_cvt_pk_bf16_f32 v34, v36, v37
	v_cvt_pk_bf16_f32 v35, v38, v39
	v_mul_f32_e32 v16, v16, v130
	v_mul_f32_e32 v17, v17, v130
	v_mul_f32_e32 v18, v18, v130
	v_mul_f32_e32 v19, v19, v130
	v_mul_f32_e32 v20, v20, v130
	v_mul_f32_e32 v24, v24, v130
	v_mul_f32_e32 v40, v40, v130
	v_mul_f32_e32 v41, v41, v130
	v_mul_f32_e32 v42, v42, v130
	v_mul_f32_e32 v43, v43, v130
	v_mul_f32_e32 v44, v44, v130
	v_mul_f32_e32 v45, v45, v130
	v_mul_f32_e32 v46, v46, v130
	v_mul_f32_e32 v47, v47, v130
	v_cvt_pk_bf16_f32 v36, v40, v41
	v_cvt_pk_bf16_f32 v37, v42, v43
	v_cvt_pk_bf16_f32 v38, v44, v45
	v_cvt_pk_bf16_f32 v39, v46, v47
	global_store_dwordx4 v[90:91], v[32:35], off offset:2048
	global_store_dwordx4 v[90:91], v[36:39], off offset:3072
	v_mul_f32_e32 v21, v21, v130
	v_mul_f32_e32 v22, v22, v130
	v_mul_f32_e32 v23, v23, v130
	v_mul_f32_e32 v25, v25, v130
	v_cvt_pk_bf16_f32 v16, v16, v17
	v_cvt_pk_bf16_f32 v17, v18, v19
	v_cvt_pk_bf16_f32 v18, v20, v21
	v_cvt_pk_bf16_f32 v19, v22, v23
	v_cvt_pk_bf16_f32 v20, v24, v25
	v_add_co_u32_e32 v24, vcc, s63, v128
	v_mul_f32_e32 v0, v0, v130
	s_nop 0
	v_addc_co_u32_e32 v25, vcc, 0, v129, vcc
	v_mul_f32_e32 v1, v1, v130
	v_mul_f32_e32 v2, v2, v130
	v_mul_f32_e32 v3, v3, v130
	s_mov_b32 s14, 0
	v_mul_f32_e32 v26, v26, v130
	v_mul_f32_e32 v27, v27, v130
	v_mul_f32_e32 v28, v28, v130
	v_mul_f32_e32 v29, v29, v130
	v_mul_f32_e32 v30, v30, v130
	v_mul_f32_e32 v31, v31, v130
	v_cvt_pk_bf16_f32 v21, v26, v27
	v_cvt_pk_bf16_f32 v22, v28, v29
	v_cvt_pk_bf16_f32 v23, v30, v31
	global_store_dwordx4 v[24:25], v[16:19], off
	global_store_dwordx4 v[24:25], v[20:23], off offset:1024
	v_mul_f32_e32 v4, v4, v130
	v_mul_f32_e32 v5, v5, v130
	v_mul_f32_e32 v6, v6, v130
	v_mul_f32_e32 v7, v7, v130
	v_mul_f32_e32 v8, v8, v130
	v_mul_f32_e32 v9, v9, v130
	v_mul_f32_e32 v10, v10, v130
	v_mul_f32_e32 v11, v11, v130
	v_mul_f32_e32 v12, v12, v130
	v_mul_f32_e32 v13, v13, v130
	v_mul_f32_e32 v14, v14, v130
	v_mul_f32_e32 v15, v15, v130
	v_cvt_pk_bf16_f32 v0, v0, v1
	v_cvt_pk_bf16_f32 v1, v2, v3
	v_cvt_pk_bf16_f32 v2, v4, v5
	v_cvt_pk_bf16_f32 v3, v6, v7
	v_cvt_pk_bf16_f32 v4, v8, v9
	v_cvt_pk_bf16_f32 v5, v10, v11
	v_cvt_pk_bf16_f32 v6, v12, v13
	v_cvt_pk_bf16_f32 v7, v14, v15
	global_store_dwordx4 v[24:25], v[0:3], off offset:2048
	global_store_dwordx4 v[24:25], v[4:7], off offset:3072
	s_nop 1
	v_mov_b32_e32 v4, v176
	s_cmp_lg_u32 0, -1
	v_bfe_u32 v0, v4, 4, 2
	v_or_b32_e32 v1, s71, v0
	v_bitop3_b32 v0, v0, v4, s71 bitop3:0x36
	v_lshlrev_b32_e32 v2, 14, v1
	v_lshlrev_b32_e32 v0, 4, v0
	v_and_or_b32 v178, v0, s55, v2
	v_or_b32_e32 v0, 4, v1
	v_bitop3_b32 v1, v1, v4, 4 bitop3:0x36
	v_lshlrev_b32_e32 v0, 14, v0
	v_lshlrev_b32_e32 v1, 4, v1
	v_and_or_b32 v180, v1, s55, v0
	v_bfe_u32 v0, v4, 5, 1
	v_or_b32_e32 v1, s71, v0
	v_and_b32_e32 v2, 31, v4
	v_lshlrev_b32_e32 v3, 14, v1
	v_lshlrev_b32_e32 v0, 6, v0
	v_lshlrev_b32_e32 v5, 4, v2
	v_bitop3_b32 v182, v0, v3, v5 bitop3:0xde
	v_or_b32_e32 v0, 2, v1
	v_lshlrev_b32_e32 v3, 2, v0
	v_bitop3_b32 v3, v3, v2, 12 bitop3:0x6c
	v_lshlrev_b32_e32 v0, 14, v0
	v_lshl_or_b32 v184, v3, 4, v0
	v_or_b32_e32 v0, 6, v1
	v_lshlrev_b32_e32 v1, 2, v0
	v_bitop3_b32 v1, v1, v2, 12 bitop3:0x6c
	v_lshlrev_b32_e32 v0, 14, v0
	v_lshl_or_b32 v188, v1, 4, v0
	v_lshl_add_u64 v[0:1], s[38:39], 0, v[178:179]
	s_cselect_b32 s15, 0, 0
	v_mov_b32_e32 v181, v179
	s_add_i32 s20, s70, s15
	s_mov_b32 s21, m0
	s_mov_b32 m0, s20
	s_nop 0
	global_load_lds_dwordx4 v[0:1], off
	s_mov_b32 m0, s21
	v_lshl_add_u64 v[0:1], s[38:39], 0, v[180:181]
	v_mov_b32_e32 v183, v179
	s_add_i32 s21, s20, 0x400
	s_mov_b32 s34, m0
	s_mov_b32 m0, s21
	s_nop 0
	global_load_lds_dwordx4 v[0:1], off
	s_mov_b32 m0, s34
	v_lshl_add_u64 v[0:1], s[16:17], 0, v[182:183]
	s_add_i32 s15, s15, s33
	v_mov_b32_e32 v185, v179
	v_or_b32_e32 v186, 0x10000, v182
	s_add_i32 s21, s15, 0xc000
	s_mov_b32 s33, m0
	s_mov_b32 m0, s21
	s_nop 0
	global_load_lds_dwordx4 v[0:1], off
	s_mov_b32 m0, s33
	v_lshl_add_u64 v[0:1], s[16:17], 0, v[184:185]
	v_mov_b32_e32 v187, v179
	s_add_i32 s21, s15, 0xc400
	s_mov_b32 s33, m0
	s_mov_b32 m0, s21
	s_nop 0
	global_load_lds_dwordx4 v[0:1], off
	s_mov_b32 m0, s33
	v_lshl_add_u64 v[0:1], s[16:17], 0, v[186:187]
	v_mov_b32_e32 v189, v179
	s_add_i32 s21, s15, 0xc800
	s_mov_b32 s33, m0
	s_mov_b32 m0, s21
	s_nop 0
	global_load_lds_dwordx4 v[0:1], off
	s_mov_b32 m0, s33
	v_lshl_add_u64 v[0:1], s[16:17], 0, v[188:189]
	s_add_i32 s16, s15, 0xcc00
	s_mov_b32 s17, m0
	s_mov_b32 m0, s16
	s_nop 0
	global_load_lds_dwordx4 v[0:1], off
	s_mov_b32 m0, s17
	v_lshl_add_u64 v[0:1], s[42:43], 0, v[178:179]
	s_add_i32 s16, s20, 0x4000
	s_mov_b32 s17, m0
	s_mov_b32 m0, s16
	s_nop 0
	global_load_lds_dwordx4 v[0:1], off
	s_mov_b32 m0, s17
	v_lshl_add_u64 v[0:1], s[42:43], 0, v[180:181]
	s_addk_i32 s20, 0x4400
	s_mov_b32 s16, m0
	s_mov_b32 m0, s20
	s_nop 0
	global_load_lds_dwordx4 v[0:1], off
	s_mov_b32 m0, s16
	v_lshl_add_u64 v[0:1], s[10:11], 0, v[182:183]
	s_add_i32 s16, s15, 0x14000
	s_mov_b32 s17, m0
	s_mov_b32 m0, s16
	s_nop 0
	global_load_lds_dwordx4 v[0:1], off
	s_mov_b32 m0, s17
	v_lshl_add_u64 v[0:1], s[10:11], 0, v[184:185]
	s_add_i32 s16, s15, 0x14400
	s_mov_b32 s17, m0
	s_mov_b32 m0, s16
	s_nop 0
	global_load_lds_dwordx4 v[0:1], off
	s_mov_b32 m0, s17
	v_lshl_add_u64 v[0:1], s[10:11], 0, v[186:187]
	s_add_i32 s16, s15, 0x14800
	s_mov_b32 s17, m0
	s_mov_b32 m0, s16
	s_nop 0
	global_load_lds_dwordx4 v[0:1], off
	s_mov_b32 m0, s17
	v_lshl_add_u64 v[0:1], s[10:11], 0, v[188:189]
	s_add_i32 s15, s15, 0x14c00
	s_mov_b32 s10, m0
	s_mov_b32 m0, s15
	s_nop 0
	global_load_lds_dwordx4 v[0:1], off
	s_mov_b32 m0, s10
	v_or_b32_e32 v0, s18, v2
	v_mov_b32_e32 v1, s19
	v_lshlrev_b64 v[0:1], 14, v[0:1]
	v_lshrrev_b32_e32 v2, 1, v4
	v_lshl_add_u64 v[0:1], s[8:9], 0, v[0:1]
	v_and_b32_e32 v2, 16, v2
	v_mov_b32_e32 v3, v179
	v_lshl_add_u64 v[0:1], v[0:1], 0, v[2:3]
	global_load_dwordx4 v[144:147], v[0:1], off offset:256
	global_load_dwordx4 v[148:151], v[0:1], off offset:288
	global_load_dwordx4 v[152:155], v[0:1], off offset:320
	global_load_dwordx4 v[156:159], v[0:1], off offset:352
	global_load_dwordx4 v[160:163], v[0:1], off offset:384
	global_load_dwordx4 v[164:167], v[0:1], off offset:416
	global_load_dwordx4 v[168:171], v[0:1], off offset:448
	global_load_dwordx4 v[172:175], v[0:1], off offset:480
	v_lshrrev_b32_e32 v0, 5, v4
	v_and_b32_e32 v1, 15, v4
	v_bitop3_b32 v0, v0, v1, 1 bitop3:0x6c
	v_lshlrev_b32_e32 v1, 8, v4
	v_lshlrev_b32_e32 v0, 4, v0
	v_and_b32_e32 v1, 0x1f00, v1
	v_mov_b32_e32 v14, v179
	v_mov_b32_e32 v15, v179
	v_or_b32_e32 v196, v0, v1
	v_bitop3_b32 v197, v0, 32, v1 bitop3:0x36
	v_bitop3_b32 v198, v0, 64, v1 bitop3:0x36
	v_bitop3_b32 v199, v0, s56, v1 bitop3:0x36
	v_bitop3_b32 v200, v0, s57, v1 bitop3:0x36
	v_bitop3_b32 v201, v0, s58, v1 bitop3:0x36
	v_bitop3_b32 v202, v0, s59, v1 bitop3:0x36
	v_bitop3_b32 v203, v0, s60, v1 bitop3:0x36
	v_mov_b32_e32 v0, v179
	v_mov_b32_e32 v1, v179
	v_mov_b32_e32 v2, v179
	v_mov_b32_e32 v4, v179
	s_waitcnt vmcnt(7)
	s_waitcnt vmcnt(6)
	s_waitcnt vmcnt(5)
	s_waitcnt vmcnt(4)
	s_waitcnt vmcnt(3)
	s_waitcnt vmcnt(2)
	s_waitcnt vmcnt(1)
	s_waitcnt vmcnt(0)
	s_waitcnt vmcnt(0)
	v_mov_b32_e32 v5, v179
	v_mov_b32_e32 v6, v179
	v_mov_b32_e32 v7, v179
	v_mov_b32_e32 v8, v179
	v_mov_b32_e32 v9, v179
	v_mov_b32_e32 v10, v179
	v_mov_b32_e32 v11, v179
	v_mov_b32_e32 v12, v179
	v_mov_b32_e32 v13, v179
	v_mov_b64_e32 v[30:31], v[14:15]
	v_mov_b64_e32 v[46:47], v[14:15]
	v_mov_b64_e32 v[62:63], v[14:15]
	v_mov_b64_e32 v[78:79], v[14:15]
	v_mov_b64_e32 v[94:95], v[14:15]
	v_mov_b64_e32 v[110:111], v[14:15]
	v_mov_b64_e32 v[126:127], v[14:15]
	s_mov_b32 s10, 2
	v_mov_b32_e32 v190, 0xf149f2ca
	v_mov_b32_e32 v195, 0
	v_mov_b64_e32 v[28:29], v[12:13]
	v_mov_b64_e32 v[26:27], v[10:11]
	v_mov_b64_e32 v[24:25], v[8:9]
	v_mov_b64_e32 v[22:23], v[6:7]
	v_mov_b64_e32 v[20:21], v[4:5]
	v_mov_b64_e32 v[18:19], v[2:3]
	v_mov_b64_e32 v[16:17], v[0:1]
	v_mov_b64_e32 v[44:45], v[12:13]
	v_mov_b64_e32 v[42:43], v[10:11]
	v_mov_b64_e32 v[40:41], v[8:9]
	v_mov_b64_e32 v[38:39], v[6:7]
	v_mov_b64_e32 v[36:37], v[4:5]
	v_mov_b64_e32 v[34:35], v[2:3]
	v_mov_b64_e32 v[32:33], v[0:1]
	v_mov_b64_e32 v[60:61], v[12:13]
	v_mov_b64_e32 v[58:59], v[10:11]
	v_mov_b64_e32 v[56:57], v[8:9]
	v_mov_b64_e32 v[54:55], v[6:7]
	v_mov_b64_e32 v[52:53], v[4:5]
	v_mov_b64_e32 v[50:51], v[2:3]
	v_mov_b64_e32 v[48:49], v[0:1]
	v_mov_b64_e32 v[76:77], v[12:13]
	v_mov_b64_e32 v[74:75], v[10:11]
	v_mov_b64_e32 v[72:73], v[8:9]
	v_mov_b64_e32 v[70:71], v[6:7]
	v_mov_b64_e32 v[68:69], v[4:5]
	v_mov_b64_e32 v[66:67], v[2:3]
	v_mov_b64_e32 v[64:65], v[0:1]
	v_mov_b64_e32 v[92:93], v[12:13]
	v_mov_b64_e32 v[90:91], v[10:11]
	v_mov_b64_e32 v[88:89], v[8:9]
	v_mov_b64_e32 v[86:87], v[6:7]
	v_mov_b64_e32 v[84:85], v[4:5]
	v_mov_b64_e32 v[82:83], v[2:3]
	v_mov_b64_e32 v[80:81], v[0:1]
	v_mov_b64_e32 v[108:109], v[12:13]
	v_mov_b64_e32 v[106:107], v[10:11]
	v_mov_b64_e32 v[104:105], v[8:9]
	v_mov_b64_e32 v[102:103], v[6:7]
	v_mov_b64_e32 v[100:101], v[4:5]
	v_mov_b64_e32 v[98:99], v[2:3]
	v_mov_b64_e32 v[96:97], v[0:1]
	v_mov_b64_e32 v[124:125], v[12:13]
	v_mov_b64_e32 v[122:123], v[10:11]
	v_mov_b64_e32 v[120:121], v[8:9]
	v_mov_b64_e32 v[118:119], v[6:7]
	v_mov_b64_e32 v[116:117], v[4:5]
	v_mov_b64_e32 v[114:115], v[2:3]
	v_mov_b64_e32 v[112:113], v[0:1]
	s_mov_b32 s11, 0
	v_lshrrev_b32_e32 v246, 8, v220
	s_nop 0
	v_readfirstlane_b32 s100, v246
	s_nop 3
	s_cmp_lg_u32 s100, 0
	s_cbranch_scc0 .Latt_prio_7
	s_setprio 1
